# v80 + code placement: one s_nop in front of each K-loop MMA segment whose MFMA run started at 4 mod 8 bytes, so all 8-byte MFMAs are 8-byte aligned
# speedup vs baseline: 1.0115x; 1.0062x over previous
; #define PG8_WAIT_V(n) asm volatile("s_waitcnt vmcnt(" #n ")" ::: "memory")
; template <class Epi, bool ALIGN_EPI, bool SP2, class Hook>
; __device__ __forceinline__ void gemm_phase(LAS unsigned char* lds, const Gemm g, const StaticOrder& S, const Epi& E, Acc& acc, const bool fresh, const Hook& H, const int wave_id) {
;     ...
;         if constexpr (SP2 && Epi::NSTORE > 0) {
;             const Src a1 = cA + kstep, a2 = cA + 2 * kstep, b2 = cB + 2 * kstep, a3 = a2 + kstep, b3 = b2 + kstep;
;             if constexpr (Epi::NSTORE == 16) PG8_TRIP_SP2(PG8_WAIT_V(24)); else PG8_TRIP_SP2(PG8_WAIT_V(16));
;             t0 = 2;
.LBB0_382:
	ds_read_b128 v[2:5], v150
	ds_read_b128 v[6:9], v150 offset:1024
	ds_read_b128 v[10:13], v150 offset:2048
	ds_read_b128 v[14:17], v150 offset:3072
	ds_read_b128 v[18:21], v151
	ds_read_b128 v[22:25], v151 offset:1024
	ds_read_b128 v[26:29], v151 offset:2048
	ds_read_b128 v[30:33], v151 offset:3072
	s_or_b32 s9, s68, 0x100
	s_or_b32 s8, s68, 0x180
	s_or_b32 s10, s69, 0x100
	s_or_b32 s11, s68, 0x40080
	s_mov_b32 m0, s45
	ds_read_b128 v[34:37], v149
	ds_read_b128 v[38:41], v149 offset:1024
	ds_read_b128 v[42:45], v149 offset:2048
	ds_read_b128 v[46:49], v149 offset:3072
	ds_read_b128 v[50:53], v149 offset:4096
	ds_read_b128 v[54:57], v149 offset:5120
	ds_read_b128 v[58:61], v149 offset:6144
	ds_read_b128 v[62:65], v149 offset:7168
	buffer_load_dwordx4 v144, s[0:3], s11 offen lds
	s_mov_b32 m0, s46
	s_nop 0
	buffer_load_dwordx4 v146, s[0:3], s11 offen lds
	s_waitcnt vmcnt(24)
	s_waitcnt lgkmcnt(0)
	s_setprio 1
	s_barrier
	v_mfma_f32_16x16x32_bf16 v[86:89], v[10:13], v[50:53], 0
	v_mfma_f32_16x16x32_bf16 v[92:95], v[14:17], v[54:57], v[86:89]
	v_mfma_f32_16x16x32_bf16 v[86:89], v[2:5], v[58:61], 0
	v_mfma_f32_16x16x32_bf16 v[66:69], v[2:5], v[34:37], 0
	v_mfma_f32_16x16x32_bf16 v[70:73], v[10:13], v[34:37], 0
	v_mfma_f32_16x16x32_bf16 v[74:77], v[2:5], v[42:45], 0
	v_mfma_f32_16x16x32_bf16 v[78:81], v[10:13], v[42:45], 0
	v_mfma_f32_16x16x32_bf16 v[82:85], v[2:5], v[50:53], 0
	v_mfma_f32_16x16x32_bf16 v[96:99], v[6:9], v[62:65], v[86:89]
	v_mfma_f32_16x16x32_bf16 v[86:89], v[10:13], v[58:61], 0
	v_mfma_f32_16x16x32_bf16 v[66:69], v[6:9], v[38:41], v[66:69]
	v_mfma_f32_16x16x32_bf16 v[70:73], v[14:17], v[38:41], v[70:73]
	v_mfma_f32_16x16x32_bf16 v[74:77], v[6:9], v[46:49], v[74:77]
	v_mfma_f32_16x16x32_bf16 v[78:81], v[14:17], v[46:49], v[78:81]
	v_mfma_f32_16x16x32_bf16 v[82:85], v[6:9], v[54:57], v[82:85]
	v_mfma_f32_16x16x32_bf16 v[104:107], v[14:17], v[62:65], v[86:89]
	v_mfma_f32_16x16x32_bf16 v[86:89], v[18:21], v[34:37], 0
	v_mfma_f32_16x16x32_bf16 v[34:37], v[26:29], v[34:37], 0
	v_mfma_f32_16x16x32_bf16 v[116:119], v[30:33], v[38:41], v[34:37]
	v_mfma_f32_16x16x32_bf16 v[34:37], v[18:21], v[42:45], 0
	v_mfma_f32_16x16x32_bf16 v[132:135], v[22:25], v[46:49], v[34:37]
	v_mfma_f32_16x16x32_bf16 v[34:37], v[26:29], v[42:45], 0
	v_mfma_f32_16x16x32_bf16 v[108:111], v[22:25], v[38:41], v[86:89]
	v_mfma_f32_16x16x32_bf16 v[40:43], v[30:33], v[46:49], v[34:37]
	v_mfma_f32_16x16x32_bf16 v[34:37], v[18:21], v[50:53], 0
	v_mfma_f32_16x16x32_bf16 v[44:47], v[22:25], v[54:57], v[34:37]
	v_mfma_f32_16x16x32_bf16 v[34:37], v[26:29], v[50:53], 0
	v_mfma_f32_16x16x32_bf16 v[48:51], v[30:33], v[54:57], v[34:37]
	v_mfma_f32_16x16x32_bf16 v[34:37], v[18:21], v[58:61], 0
	v_mfma_f32_16x16x32_bf16 v[52:55], v[22:25], v[62:65], v[34:37]
	v_mfma_f32_16x16x32_bf16 v[34:37], v[26:29], v[58:61], 0
	v_mfma_f32_16x16x32_bf16 v[60:63], v[30:33], v[62:65], v[34:37]
	s_barrier
	s_setprio 0
	s_mov_b32 m0, s92
	s_nop 3
	ds_read_b128 v[34:37], v149 offset:16384
	ds_read_b128 v[56:59], v149 offset:17408
	ds_read_b128 v[86:89], v149 offset:18432
	ds_read_b128 v[100:103], v149 offset:19456
	ds_read_b128 v[112:115], v149 offset:20480
	ds_read_b128 v[120:123], v149 offset:21504
	ds_read_b128 v[124:127], v149 offset:22528
	ds_read_b128 v[128:131], v149 offset:23552
	buffer_load_dwordx4 v145, s[4:7], s10 offen lds
	s_mov_b32 m0, s93
	s_nop 0
	buffer_load_dwordx4 v147, s[4:7], s10 offen lds
	s_or_b32 s10, s69, 0x40100
	s_mov_b32 m0, s94
	s_nop 0
	buffer_load_dwordx4 v145, s[4:7], s10 offen lds
	s_mov_b32 m0, s95
	s_nop 0
	buffer_load_dwordx4 v147, s[4:7], s10 offen lds
	s_waitcnt vmcnt(22)
	s_waitcnt lgkmcnt(0)
	s_setprio 1
	s_barrier
	v_mfma_f32_16x16x32_bf16 v[136:139], v[2:5], v[34:37], 0
	v_mfma_f32_16x16x32_bf16 v[154:157], v[2:5], v[86:89], 0
	v_mfma_f32_16x16x32_bf16 v[162:165], v[2:5], v[112:115], 0
	v_mfma_f32_16x16x32_bf16 v[2:5], v[2:5], v[124:127], 0
	v_mfma_f32_16x16x32_bf16 v[136:139], v[6:9], v[56:59], v[136:139]
	v_mfma_f32_16x16x32_bf16 v[140:143], v[10:13], v[34:37], 0
	v_mfma_f32_16x16x32_bf16 v[154:157], v[6:9], v[100:103], v[154:157]
	v_mfma_f32_16x16x32_bf16 v[158:161], v[10:13], v[86:89], 0
	v_mfma_f32_16x16x32_bf16 v[162:165], v[6:9], v[120:123], v[162:165]
	v_mfma_f32_16x16x32_bf16 v[166:169], v[10:13], v[112:115], 0
	v_mfma_f32_16x16x32_bf16 v[2:5], v[6:9], v[128:131], v[2:5]
	v_mfma_f32_16x16x32_bf16 v[6:9], v[10:13], v[124:127], 0
	v_mfma_f32_16x16x32_bf16 v[140:143], v[14:17], v[56:59], v[140:143]
	v_mfma_f32_16x16x32_bf16 v[158:161], v[14:17], v[100:103], v[158:161]
	v_mfma_f32_16x16x32_bf16 v[166:169], v[14:17], v[120:123], v[166:169]
	v_mfma_f32_16x16x32_bf16 v[170:173], v[14:17], v[128:131], v[6:9]
	v_mfma_f32_16x16x32_bf16 v[6:9], v[18:21], v[34:37], 0
	v_mfma_f32_16x16x32_bf16 v[174:177], v[22:25], v[56:59], v[6:9]
	v_mfma_f32_16x16x32_bf16 v[6:9], v[26:29], v[34:37], 0
	v_mfma_f32_16x16x32_bf16 v[178:181], v[30:33], v[56:59], v[6:9]
	v_mfma_f32_16x16x32_bf16 v[6:9], v[18:21], v[86:89], 0
	v_mfma_f32_16x16x32_bf16 v[182:185], v[22:25], v[100:103], v[6:9]
	v_mfma_f32_16x16x32_bf16 v[6:9], v[26:29], v[86:89], 0
	v_mfma_f32_16x16x32_bf16 v[186:189], v[30:33], v[100:103], v[6:9]
	v_mfma_f32_16x16x32_bf16 v[6:9], v[18:21], v[112:115], 0
	v_mfma_f32_16x16x32_bf16 v[190:193], v[22:25], v[120:123], v[6:9]
	v_mfma_f32_16x16x32_bf16 v[6:9], v[26:29], v[112:115], 0
	v_mfma_f32_16x16x32_bf16 v[212:215], v[30:33], v[120:123], v[6:9]
	v_mfma_f32_16x16x32_bf16 v[6:9], v[18:21], v[124:127], 0
	v_mfma_f32_16x16x32_bf16 v[20:23], v[22:25], v[128:131], v[6:9]
	v_mfma_f32_16x16x32_bf16 v[6:9], v[26:29], v[124:127], 0
	v_mfma_f32_16x16x32_bf16 v[216:219], v[30:33], v[128:131], v[6:9]
	s_barrier
; #define PG8_WAIT_V(n) asm volatile("s_waitcnt vmcnt(" #n ")" ::: "memory")
; template <class Epi, bool ALIGN_EPI, bool SP2, class Hook>
; __device__ __forceinline__ void gemm_phase(LAS unsigned char* lds, const Gemm g, const StaticOrder& S, const Epi& E, Acc& acc, const bool fresh, const Hook& H, const int wave_id) {
;     ...
;         if constexpr (SP2 && Epi::NSTORE > 0) {
;             const Src a1 = cA + kstep, a2 = cA + 2 * kstep, b2 = cB + 2 * kstep, a3 = a2 + kstep, b3 = b2 + kstep;
;             if constexpr (Epi::NSTORE == 16) PG8_TRIP_SP2(PG8_WAIT_V(24)); else PG8_TRIP_SP2(PG8_WAIT_V(16));
;             t0 = 2;
	s_setprio 0
	s_mov_b32 m0, s44
	s_nop 0
	buffer_load_dwordx4 v144, s[0:3], s9 offen lds
	s_mov_b32 m0, s36
	s_nop 0
	buffer_load_dwordx4 v146, s[0:3], s9 offen lds
	s_nop 4
	ds_read_b128 v[6:9], v152
	ds_read_b128 v[24:27], v152 offset:1024
	ds_read_b128 v[228:231], v152 offset:2048
	ds_read_b128 v[232:235], v152 offset:3072
	ds_read_b128 v[236:239], v153
	ds_read_b128 v[240:243], v153 offset:1024
	ds_read_b128 v[244:247], v153 offset:2048
	ds_read_b128 v[150:153], v153 offset:3072
	s_or_b32 s9, s68, 0x40100
	s_mov_b32 m0, s37
	ds_read_b128 v[10:13], v149 offset:32768
	ds_read_b128 v[14:17], v149 offset:33792
	ds_read_b128 v[32:35], v149 offset:34816
	ds_read_b128 v[194:197], v149 offset:35840
	ds_read_b128 v[208:211], v149 offset:36864
	ds_read_b128 v[200:203], v149 offset:37888
	ds_read_b128 v[204:207], v149 offset:38912
	ds_read_b128 v[220:223], v149 offset:39936
	buffer_load_dwordx4 v144, s[0:3], s9 offen lds
	s_mov_b32 m0, s38
	s_nop 0
	buffer_load_dwordx4 v146, s[0:3], s9 offen lds
	s_waitcnt vmcnt(8)
	s_waitcnt lgkmcnt(0)
	s_setprio 1
	s_barrier
	v_mfma_f32_16x16x32_bf16 v[28:31], v[6:9], v[10:13], v[66:69]
	v_mfma_f32_16x16x32_bf16 v[120:123], v[24:27], v[14:17], v[28:31]
	v_mfma_f32_16x16x32_bf16 v[28:31], v[228:231], v[10:13], v[70:73]
	v_mfma_f32_16x16x32_bf16 v[112:115], v[232:235], v[14:17], v[28:31]
	v_mfma_f32_16x16x32_bf16 v[28:31], v[6:9], v[32:35], v[74:77]
	v_mfma_f32_16x16x32_bf16 v[100:103], v[24:27], v[194:197], v[28:31]
	v_mfma_f32_16x16x32_bf16 v[28:31], v[228:231], v[32:35], v[78:81]
	v_mfma_f32_16x16x32_bf16 v[88:91], v[232:235], v[194:197], v[28:31]
	v_mfma_f32_16x16x32_bf16 v[28:31], v[6:9], v[208:211], v[82:85]
	v_mfma_f32_16x16x32_bf16 v[68:71], v[24:27], v[200:203], v[28:31]
	v_mfma_f32_16x16x32_bf16 v[28:31], v[228:231], v[208:211], v[92:95]
	v_mfma_f32_16x16x32_bf16 v[56:59], v[232:235], v[200:203], v[28:31]
	v_mfma_f32_16x16x32_bf16 v[28:31], v[6:9], v[204:207], v[96:99]
	v_mfma_f32_16x16x32_bf16 v[36:39], v[24:27], v[220:223], v[28:31]
	v_mfma_f32_16x16x32_bf16 v[28:31], v[228:231], v[204:207], v[104:107]
	v_mfma_f32_16x16x32_bf16 v[28:31], v[232:235], v[220:223], v[28:31]
	v_mfma_f32_16x16x32_bf16 v[64:67], v[236:239], v[10:13], v[108:111]
	v_mfma_f32_16x16x32_bf16 v[10:13], v[244:247], v[10:13], v[116:119]
	v_mfma_f32_16x16x32_bf16 v[124:127], v[150:153], v[14:17], v[10:13]
	v_mfma_f32_16x16x32_bf16 v[10:13], v[236:239], v[32:35], v[132:135]
	v_mfma_f32_16x16x32_bf16 v[116:119], v[240:243], v[194:197], v[10:13]
	v_mfma_f32_16x16x32_bf16 v[10:13], v[244:247], v[32:35], v[40:43]
	v_mfma_f32_16x16x32_bf16 v[108:111], v[150:153], v[194:197], v[10:13]
	v_mfma_f32_16x16x32_bf16 v[10:13], v[236:239], v[208:211], v[44:47]
	v_mfma_f32_16x16x32_bf16 v[92:95], v[240:243], v[200:203], v[10:13]
	v_mfma_f32_16x16x32_bf16 v[10:13], v[244:247], v[208:211], v[48:51]
	v_mfma_f32_16x16x32_bf16 v[80:83], v[150:153], v[200:203], v[10:13]
	v_mfma_f32_16x16x32_bf16 v[10:13], v[236:239], v[204:207], v[52:55]
	v_mfma_f32_16x16x32_bf16 v[128:131], v[240:243], v[14:17], v[64:67]
	v_mfma_f32_16x16x32_bf16 v[64:67], v[240:243], v[220:223], v[10:13]
	v_mfma_f32_16x16x32_bf16 v[10:13], v[244:247], v[204:207], v[60:63]
	v_mfma_f32_16x16x32_bf16 v[48:51], v[150:153], v[220:223], v[10:13]
	s_barrier
	s_setprio 0
	s_mov_b32 m0, s39
	s_or_b32 s9, s69, 0x180
	ds_read_b128 v[44:47], v149 offset:49152
	ds_read_b128 v[52:55], v149 offset:50176
	ds_read_b128 v[76:79], v149 offset:51200
	ds_read_b128 v[132:135], v149 offset:52224
	ds_read_b128 v[194:197], v149 offset:53248
	ds_read_b128 v[200:203], v149 offset:54272
	ds_read_b128 v[204:207], v149 offset:55296
	ds_read_b128 v[208:211], v149 offset:56320
	buffer_load_dwordx4 v145, s[4:7], s9 offen lds
	s_mov_b32 m0, s40
	s_nop 0
	buffer_load_dwordx4 v147, s[4:7], s9 offen lds
	s_or_b32 s9, s69, 0x40180
	s_mov_b32 m0, s43
	s_nop 0
	buffer_load_dwordx4 v145, s[4:7], s9 offen lds
	s_mov_b32 m0, s42
	s_nop 0
	buffer_load_dwordx4 v147, s[4:7], s9 offen lds
	s_waitcnt vmcnt(6)
	s_waitcnt lgkmcnt(0)
	s_nop 0
	s_setprio 1
	s_barrier
	v_mfma_f32_16x16x32_bf16 v[10:13], v[6:9], v[44:47], v[136:139]
	v_mfma_f32_16x16x32_bf16 v[72:75], v[24:27], v[52:55], v[10:13]
	v_mfma_f32_16x16x32_bf16 v[10:13], v[228:231], v[44:47], v[140:143]
	v_mfma_f32_16x16x32_bf16 v[60:63], v[232:235], v[52:55], v[10:13]
	v_mfma_f32_16x16x32_bf16 v[10:13], v[6:9], v[76:79], v[154:157]
	v_mfma_f32_16x16x32_bf16 v[40:43], v[24:27], v[132:135], v[10:13]
	v_mfma_f32_16x16x32_bf16 v[10:13], v[228:231], v[76:79], v[158:161]
	v_mfma_f32_16x16x32_bf16 v[32:35], v[232:235], v[132:135], v[10:13]
	v_mfma_f32_16x16x32_bf16 v[10:13], v[6:9], v[194:197], v[162:165]
	v_mfma_f32_16x16x32_bf16 v[16:19], v[24:27], v[200:203], v[10:13]
	v_mfma_f32_16x16x32_bf16 v[10:13], v[228:231], v[194:197], v[166:169]
	v_mfma_f32_16x16x32_bf16 v[2:5], v[6:9], v[204:207], v[2:5]
	v_mfma_f32_16x16x32_bf16 v[12:15], v[232:235], v[200:203], v[10:13]
	v_mfma_f32_16x16x32_bf16 v[8:11], v[24:27], v[208:211], v[2:5]
	v_mfma_f32_16x16x32_bf16 v[2:5], v[228:231], v[204:207], v[170:173]
	v_mfma_f32_16x16x32_bf16 v[4:7], v[232:235], v[208:211], v[2:5]
	v_mfma_f32_16x16x32_bf16 v[24:27], v[236:239], v[44:47], v[174:177]
	v_mfma_f32_16x16x32_bf16 v[96:99], v[240:243], v[52:55], v[24:27]
	v_mfma_f32_16x16x32_bf16 v[24:27], v[244:247], v[44:47], v[178:181]
	v_mfma_f32_16x16x32_bf16 v[104:107], v[150:153], v[52:55], v[24:27]
	v_mfma_f32_16x16x32_bf16 v[24:27], v[236:239], v[76:79], v[182:185]
	v_mfma_f32_16x16x32_bf16 v[84:87], v[240:243], v[132:135], v[24:27]
	v_mfma_f32_16x16x32_bf16 v[24:27], v[244:247], v[76:79], v[186:189]
	v_mfma_f32_16x16x32_bf16 v[76:79], v[150:153], v[132:135], v[24:27]
	v_mfma_f32_16x16x32_bf16 v[24:27], v[236:239], v[194:197], v[190:193]
	v_mfma_f32_16x16x32_bf16 v[52:55], v[240:243], v[200:203], v[24:27]
	v_mfma_f32_16x16x32_bf16 v[24:27], v[244:247], v[194:197], v[212:215]
	v_mfma_f32_16x16x32_bf16 v[20:23], v[236:239], v[204:207], v[20:23]
	v_mfma_f32_16x16x32_bf16 v[44:47], v[150:153], v[200:203], v[24:27]
	v_mfma_f32_16x16x32_bf16 v[24:27], v[240:243], v[208:211], v[20:23]
	v_mfma_f32_16x16x32_bf16 v[20:23], v[244:247], v[204:207], v[216:219]
	v_mfma_f32_16x16x32_bf16 v[20:23], v[150:153], v[208:211], v[20:23]
	s_barrier
	s_setprio 0
	s_mov_b64 s[8:9], 0
	v_mov_b64_e32 v[234:235], v[198:199]
	v_mov_b64_e32 v[236:237], v[226:227]
	v_mov_b32_e32 v198, v0
	v_mov_b32_e32 v226, v225
	v_mov_b64_e32 v[244:245], 0x100
	v_mov_b64_e32 v[246:247], 0xff

; #define PG8_WAIT_V(n) asm volatile("s_waitcnt vmcnt(" #n ")" ::: "memory")
; template <class Epi, bool ALIGN_EPI, bool SP2, class Hook>
; __device__ __forceinline__ void gemm_phase(LAS unsigned char* lds, const Gemm g, const StaticOrder& S, const Epi& E, Acc& acc, const bool fresh, const Hook& H, const int wave_id) {
;     ...
;         for (int t = t0; t < nt; t += 2) {
;             const bool last = (t == nt - 2);
;             const Src a1 = cA + (size_t)(t + 1) * kstep;
;             const Src a2 = last ? nA : cA + (size_t)(t + 2) * kstep, b2 = last ? nB : cB + (size_t)(t + 2) * kstep;
;             const Src a3 = a2 + kstep, b3 = b2 + kstep;
;             if (last && has_next) H(nxt);
;             if constexpr (SP2) {
;             PG8_TRIP_SP2(PG8_WAIT_V(8));
.LBB0_391:
	s_add_i32 s100, s56, 0xfffc0000
	v_add_u32_e32 v150, 0x10000, v148
	v_add_u32_e32 v151, 0x14000, v148
	ds_read_b128 v[132:135], v150
	ds_read_b128 v[136:139], v150 offset:1024
	ds_read_b128 v[140:143], v150 offset:2048
	ds_read_b128 v[152:155], v150 offset:3072
	ds_read_b128 v[156:159], v151
	ds_read_b128 v[160:163], v151 offset:1024
	ds_read_b128 v[164:167], v151 offset:2048
	ds_read_b128 v[168:171], v151 offset:3072
	s_mov_b32 m0, s41
	s_nop 0
	buffer_load_dwordx4 v144, s[8:11], s100 offen lds
	s_mov_b32 m0, s33
	s_nop 0
	buffer_load_dwordx4 v146, s[8:11], s100 offen lds
	s_mov_b32 m0, s45
	ds_read_b128 v[172:175], v149
	ds_read_b128 v[176:179], v149 offset:1024
	ds_read_b128 v[180:183], v149 offset:2048
	ds_read_b128 v[184:187], v149 offset:3072
	ds_read_b128 v[188:191], v149 offset:4096
	ds_read_b128 v[212:215], v149 offset:5120
	ds_read_b128 v[216:219], v149 offset:6144
	ds_read_b128 v[228:231], v149 offset:7168
	buffer_load_dwordx4 v144, s[8:11], s56 offen lds
	s_mov_b32 m0, s46
	s_nop 0
	buffer_load_dwordx4 v146, s[8:11], s56 offen lds
	s_waitcnt vmcnt(8)
	s_waitcnt lgkmcnt(0)
	s_nop 0
	s_setprio 1
	s_barrier
	v_mfma_f32_16x16x32_bf16 v[120:123], v[132:135], v[172:175], v[120:123]
	v_mfma_f32_16x16x32_bf16 v[112:115], v[140:143], v[172:175], v[112:115]
	v_mfma_f32_16x16x32_bf16 v[100:103], v[132:135], v[180:183], v[100:103]
	v_mfma_f32_16x16x32_bf16 v[88:91], v[140:143], v[180:183], v[88:91]
	v_mfma_f32_16x16x32_bf16 v[68:71], v[132:135], v[188:191], v[68:71]
	v_mfma_f32_16x16x32_bf16 v[56:59], v[140:143], v[188:191], v[56:59]
	v_mfma_f32_16x16x32_bf16 v[36:39], v[132:135], v[216:219], v[36:39]
	v_mfma_f32_16x16x32_bf16 v[28:31], v[140:143], v[216:219], v[28:31]
	v_mfma_f32_16x16x32_bf16 v[120:123], v[136:139], v[176:179], v[120:123]
	v_mfma_f32_16x16x32_bf16 v[112:115], v[152:155], v[176:179], v[112:115]
	v_mfma_f32_16x16x32_bf16 v[100:103], v[136:139], v[184:187], v[100:103]
	v_mfma_f32_16x16x32_bf16 v[88:91], v[152:155], v[184:187], v[88:91]
	v_mfma_f32_16x16x32_bf16 v[68:71], v[136:139], v[212:215], v[68:71]
	v_mfma_f32_16x16x32_bf16 v[56:59], v[152:155], v[212:215], v[56:59]
	v_mfma_f32_16x16x32_bf16 v[36:39], v[136:139], v[228:231], v[36:39]
	v_mfma_f32_16x16x32_bf16 v[28:31], v[152:155], v[228:231], v[28:31]
	v_mfma_f32_16x16x32_bf16 v[128:131], v[156:159], v[172:175], v[128:131]
	v_mfma_f32_16x16x32_bf16 v[124:127], v[164:167], v[172:175], v[124:127]
	v_mfma_f32_16x16x32_bf16 v[116:119], v[156:159], v[180:183], v[116:119]
	v_mfma_f32_16x16x32_bf16 v[108:111], v[164:167], v[180:183], v[108:111]
	v_mfma_f32_16x16x32_bf16 v[92:95], v[156:159], v[188:191], v[92:95]
	v_mfma_f32_16x16x32_bf16 v[80:83], v[164:167], v[188:191], v[80:83]
	v_mfma_f32_16x16x32_bf16 v[64:67], v[156:159], v[216:219], v[64:67]
	v_mfma_f32_16x16x32_bf16 v[48:51], v[164:167], v[216:219], v[48:51]
	v_mfma_f32_16x16x32_bf16 v[128:131], v[160:163], v[176:179], v[128:131]
	v_mfma_f32_16x16x32_bf16 v[124:127], v[168:171], v[176:179], v[124:127]
	v_mfma_f32_16x16x32_bf16 v[116:119], v[160:163], v[184:187], v[116:119]
	v_mfma_f32_16x16x32_bf16 v[108:111], v[168:171], v[184:187], v[108:111]
	v_mfma_f32_16x16x32_bf16 v[92:95], v[160:163], v[212:215], v[92:95]
	v_mfma_f32_16x16x32_bf16 v[80:83], v[168:171], v[212:215], v[80:83]
	v_mfma_f32_16x16x32_bf16 v[64:67], v[160:163], v[228:231], v[64:67]
	v_mfma_f32_16x16x32_bf16 v[48:51], v[168:171], v[228:231], v[48:51]
	s_barrier
	s_setprio 0
	s_add_i32 s12, s56, 0xfffc0080
	s_cmp_eq_u32 s29, 12
	s_cselect_b32 s60, s68, s12
	s_cselect_b32 s13, s5, s77
	s_cselect_b32 s12, s4, s76
	s_cselect_b32 s15, s7, s55
	s_cselect_b32 s14, s6, s54
	s_cselect_b32 s58, s69, s57
	s_cselect_b32 s16, s0, s8
	s_cselect_b32 s17, s1, s9
	s_cselect_b32 s18, s2, s10
	s_cselect_b32 s19, s3, s11
	s_or_b32 s59, s60, 0x80
	s_mov_b32 m0, s92
	ds_read_b128 v[172:175], v149 offset:16384
	ds_read_b128 v[176:179], v149 offset:17408
	ds_read_b128 v[180:183], v149 offset:18432
	ds_read_b128 v[184:187], v149 offset:19456
	ds_read_b128 v[188:191], v149 offset:20480
	ds_read_b128 v[212:215], v149 offset:21504
	ds_read_b128 v[216:219], v149 offset:22528
	ds_read_b128 v[228:231], v149 offset:23552
	buffer_load_dwordx4 v145, s[12:15], s58 offen lds
	s_mov_b32 m0, s93
	s_add_i32 s61, s58, 0x40000
	buffer_load_dwordx4 v147, s[12:15], s58 offen lds
	s_mov_b32 m0, s94
	s_nop 0
	buffer_load_dwordx4 v145, s[12:15], s61 offen lds
	s_mov_b32 m0, s95
	s_nop 0
	buffer_load_dwordx4 v147, s[12:15], s61 offen lds
	s_waitcnt vmcnt(6)
	s_waitcnt lgkmcnt(0)
	s_nop 0
	s_setprio 1
	s_barrier
; #define PG8_WAIT_V(n) asm volatile("s_waitcnt vmcnt(" #n ")" ::: "memory")
; template <class Epi, bool ALIGN_EPI, bool SP2, class Hook>
; __device__ __forceinline__ void gemm_phase(LAS unsigned char* lds, const Gemm g, const StaticOrder& S, const Epi& E, Acc& acc, const bool fresh, const Hook& H, const int wave_id) {
;     ...
;         for (int t = t0; t < nt; t += 2) {
;             const bool last = (t == nt - 2);
;             const Src a1 = cA + (size_t)(t + 1) * kstep;
;             const Src a2 = last ? nA : cA + (size_t)(t + 2) * kstep, b2 = last ? nB : cB + (size_t)(t + 2) * kstep;
;             const Src a3 = a2 + kstep, b3 = b2 + kstep;
;             if (last && has_next) H(nxt);
;             if constexpr (SP2) {
;             PG8_TRIP_SP2(PG8_WAIT_V(8));
	v_mfma_f32_16x16x32_bf16 v[72:75], v[132:135], v[172:175], v[72:75]
	v_mfma_f32_16x16x32_bf16 v[60:63], v[140:143], v[172:175], v[60:63]
	v_mfma_f32_16x16x32_bf16 v[40:43], v[132:135], v[180:183], v[40:43]
	v_mfma_f32_16x16x32_bf16 v[32:35], v[140:143], v[180:183], v[32:35]
	v_mfma_f32_16x16x32_bf16 v[16:19], v[132:135], v[188:191], v[16:19]
	v_mfma_f32_16x16x32_bf16 v[12:15], v[140:143], v[188:191], v[12:15]
	v_mfma_f32_16x16x32_bf16 v[8:11], v[132:135], v[216:219], v[8:11]
	v_mfma_f32_16x16x32_bf16 v[2:5], v[140:143], v[216:219], v[4:7]
	v_mfma_f32_16x16x32_bf16 v[72:75], v[136:139], v[176:179], v[72:75]
	v_mfma_f32_16x16x32_bf16 v[60:63], v[152:155], v[176:179], v[60:63]
	v_mfma_f32_16x16x32_bf16 v[40:43], v[136:139], v[184:187], v[40:43]
	v_mfma_f32_16x16x32_bf16 v[32:35], v[152:155], v[184:187], v[32:35]
	v_mfma_f32_16x16x32_bf16 v[16:19], v[136:139], v[212:215], v[16:19]
	v_mfma_f32_16x16x32_bf16 v[12:15], v[152:155], v[212:215], v[12:15]
	v_mfma_f32_16x16x32_bf16 v[8:11], v[136:139], v[228:231], v[8:11]
	v_mfma_f32_16x16x32_bf16 v[2:5], v[152:155], v[228:231], v[2:5]
	v_mfma_f32_16x16x32_bf16 v[96:99], v[156:159], v[172:175], v[96:99]
	v_mfma_f32_16x16x32_bf16 v[104:107], v[164:167], v[172:175], v[104:107]
	v_mfma_f32_16x16x32_bf16 v[84:87], v[156:159], v[180:183], v[84:87]
	v_mfma_f32_16x16x32_bf16 v[76:79], v[164:167], v[180:183], v[76:79]
	v_mfma_f32_16x16x32_bf16 v[52:55], v[156:159], v[188:191], v[52:55]
	v_mfma_f32_16x16x32_bf16 v[44:47], v[164:167], v[188:191], v[44:47]
	v_mfma_f32_16x16x32_bf16 v[24:27], v[156:159], v[216:219], v[24:27]
	v_mfma_f32_16x16x32_bf16 v[20:23], v[164:167], v[216:219], v[20:23]
	v_mfma_f32_16x16x32_bf16 v[96:99], v[160:163], v[176:179], v[96:99]
	v_mfma_f32_16x16x32_bf16 v[104:107], v[168:171], v[176:179], v[104:107]
	v_mfma_f32_16x16x32_bf16 v[84:87], v[160:163], v[184:187], v[84:87]
	v_mfma_f32_16x16x32_bf16 v[76:79], v[168:171], v[184:187], v[76:79]
	v_mfma_f32_16x16x32_bf16 v[52:55], v[160:163], v[212:215], v[52:55]
	v_mfma_f32_16x16x32_bf16 v[44:47], v[168:171], v[212:215], v[44:47]
	v_mfma_f32_16x16x32_bf16 v[24:27], v[160:163], v[228:231], v[24:27]
	v_mfma_f32_16x16x32_bf16 v[20:23], v[168:171], v[228:231], v[20:23]
	s_barrier
	s_setprio 0
	s_mov_b32 m0, s44
	s_nop 0
	buffer_load_dwordx4 v144, s[16:19], s60 offen lds
	s_mov_b32 m0, s36
	s_nop 0
	buffer_load_dwordx4 v146, s[16:19], s60 offen lds
	v_add_u32_e32 v152, 0x18000, v148
	v_add_u32_e32 v153, 0x1c000, v148
	ds_read_b128 v[132:135], v152
	ds_read_b128 v[136:139], v152 offset:1024
	ds_read_b128 v[140:143], v152 offset:2048
	ds_read_b128 v[154:157], v152 offset:3072
	ds_read_b128 v[158:161], v153
	ds_read_b128 v[162:165], v153 offset:1024
	ds_read_b128 v[166:169], v153 offset:2048
	ds_read_b128 v[170:173], v153 offset:3072
	s_add_i32 s60, s60, 0x40000
	s_mov_b32 m0, s37
	ds_read_b128 v[174:177], v149 offset:32768
	ds_read_b128 v[178:181], v149 offset:33792
	ds_read_b128 v[182:185], v149 offset:34816
	ds_read_b128 v[186:189], v149 offset:35840
	ds_read_b128 v[190:193], v149 offset:36864
	ds_read_b128 v[212:215], v149 offset:37888
	ds_read_b128 v[216:219], v149 offset:38912
	ds_read_b128 v[228:231], v149 offset:39936
	buffer_load_dwordx4 v144, s[16:19], s60 offen lds
	s_mov_b32 m0, s38
	s_nop 0
	buffer_load_dwordx4 v146, s[16:19], s60 offen lds
	s_waitcnt vmcnt(8)
	s_waitcnt lgkmcnt(0)
	s_nop 0
	s_setprio 1
	s_barrier
	v_mfma_f32_16x16x32_bf16 v[120:123], v[132:135], v[174:177], v[120:123]
	v_mfma_f32_16x16x32_bf16 v[112:115], v[140:143], v[174:177], v[112:115]
	v_mfma_f32_16x16x32_bf16 v[100:103], v[132:135], v[182:185], v[100:103]
	v_mfma_f32_16x16x32_bf16 v[88:91], v[140:143], v[182:185], v[88:91]
	v_mfma_f32_16x16x32_bf16 v[68:71], v[132:135], v[190:193], v[68:71]
	v_mfma_f32_16x16x32_bf16 v[56:59], v[140:143], v[190:193], v[56:59]
	v_mfma_f32_16x16x32_bf16 v[36:39], v[132:135], v[216:219], v[36:39]
	v_mfma_f32_16x16x32_bf16 v[28:31], v[140:143], v[216:219], v[28:31]
	v_mfma_f32_16x16x32_bf16 v[120:123], v[136:139], v[178:181], v[120:123]
	v_mfma_f32_16x16x32_bf16 v[112:115], v[154:157], v[178:181], v[112:115]
	v_mfma_f32_16x16x32_bf16 v[100:103], v[136:139], v[186:189], v[100:103]
	v_mfma_f32_16x16x32_bf16 v[88:91], v[154:157], v[186:189], v[88:91]
	v_mfma_f32_16x16x32_bf16 v[68:71], v[136:139], v[212:215], v[68:71]
	v_mfma_f32_16x16x32_bf16 v[56:59], v[154:157], v[212:215], v[56:59]
	v_mfma_f32_16x16x32_bf16 v[36:39], v[136:139], v[228:231], v[36:39]
	v_mfma_f32_16x16x32_bf16 v[28:31], v[154:157], v[228:231], v[28:31]
	v_mfma_f32_16x16x32_bf16 v[128:131], v[158:161], v[174:177], v[128:131]
	v_mfma_f32_16x16x32_bf16 v[124:127], v[166:169], v[174:177], v[124:127]
	v_mfma_f32_16x16x32_bf16 v[116:119], v[158:161], v[182:185], v[116:119]
	v_mfma_f32_16x16x32_bf16 v[108:111], v[166:169], v[182:185], v[108:111]
	v_mfma_f32_16x16x32_bf16 v[92:95], v[158:161], v[190:193], v[92:95]
	v_mfma_f32_16x16x32_bf16 v[80:83], v[166:169], v[190:193], v[80:83]
	v_mfma_f32_16x16x32_bf16 v[64:67], v[158:161], v[216:219], v[64:67]
	v_mfma_f32_16x16x32_bf16 v[48:51], v[166:169], v[216:219], v[48:51]
	v_mfma_f32_16x16x32_bf16 v[128:131], v[162:165], v[178:181], v[128:131]
	v_mfma_f32_16x16x32_bf16 v[124:127], v[170:173], v[178:181], v[124:127]
	v_mfma_f32_16x16x32_bf16 v[116:119], v[162:165], v[186:189], v[116:119]
	v_mfma_f32_16x16x32_bf16 v[108:111], v[170:173], v[186:189], v[108:111]
	v_mfma_f32_16x16x32_bf16 v[92:95], v[162:165], v[212:215], v[92:95]
	v_mfma_f32_16x16x32_bf16 v[80:83], v[170:173], v[212:215], v[80:83]
	v_mfma_f32_16x16x32_bf16 v[64:67], v[162:165], v[228:231], v[64:67]
	v_mfma_f32_16x16x32_bf16 v[48:51], v[170:173], v[228:231], v[48:51]
	s_barrier
; template <class Epi, bool ALIGN_EPI, bool SP2, class Hook>
; __device__ __forceinline__ void gemm_phase(LAS unsigned char* lds, const Gemm g, const StaticOrder& S, const Epi& E, Acc& acc, const bool fresh, const Hook& H, const int wave_id) {
;     ...
;         for (int t = t0; t < nt; t += 2) {
;             const bool last = (t == nt - 2);
;             const Src a1 = cA + (size_t)(t + 1) * kstep;
;             const Src a2 = last ? nA : cA + (size_t)(t + 2) * kstep, b2 = last ? nB : cB + (size_t)(t + 2) * kstep;
;             const Src a3 = a2 + kstep, b3 = b2 + kstep;
;             if (last && has_next) H(nxt);
	s_setprio 0
	s_mov_b32 m0, s39
	s_or_b32 s60, s58, 0x80
	ds_read_b128 v[174:177], v149 offset:49152
	ds_read_b128 v[178:181], v149 offset:50176
	ds_read_b128 v[182:185], v149 offset:51200
	ds_read_b128 v[186:189], v149 offset:52224
	ds_read_b128 v[190:193], v149 offset:53248
	ds_read_b128 v[212:215], v149 offset:54272
	ds_read_b128 v[216:219], v149 offset:55296
	ds_read_b128 v[228:231], v149 offset:56320
	buffer_load_dwordx4 v145, s[12:15], s60 offen lds
	s_mov_b32 m0, s40
	s_add_i32 s58, s58, 0x40080
	buffer_load_dwordx4 v147, s[12:15], s60 offen lds
	s_mov_b32 m0, s43
	s_nop 0
	buffer_load_dwordx4 v145, s[12:15], s58 offen lds
	s_mov_b32 m0, s42
	s_nop 0
	buffer_load_dwordx4 v147, s[12:15], s58 offen lds
	s_add_i32 s29, s29, 2
	s_addk_i32 s56, 0x100
	s_addk_i32 s57, 0x100
	s_cmp_gt_u32 s29, 13
	s_waitcnt vmcnt(6)
	s_waitcnt lgkmcnt(0)
	s_setprio 1
	s_barrier
	v_mfma_f32_16x16x32_bf16 v[72:75], v[132:135], v[174:177], v[72:75]
	v_mfma_f32_16x16x32_bf16 v[60:63], v[140:143], v[174:177], v[60:63]
	v_mfma_f32_16x16x32_bf16 v[40:43], v[132:135], v[182:185], v[40:43]
	v_mfma_f32_16x16x32_bf16 v[32:35], v[140:143], v[182:185], v[32:35]
	v_mfma_f32_16x16x32_bf16 v[16:19], v[132:135], v[190:193], v[16:19]
	v_mfma_f32_16x16x32_bf16 v[12:15], v[140:143], v[190:193], v[12:15]
	v_mfma_f32_16x16x32_bf16 v[6:9], v[132:135], v[216:219], v[8:11]
	v_mfma_f32_16x16x32_bf16 v[2:5], v[140:143], v[216:219], v[2:5]
	v_mfma_f32_16x16x32_bf16 v[72:75], v[136:139], v[178:181], v[72:75]
	v_mfma_f32_16x16x32_bf16 v[60:63], v[154:157], v[178:181], v[60:63]
	v_mfma_f32_16x16x32_bf16 v[40:43], v[136:139], v[186:189], v[40:43]
	v_mfma_f32_16x16x32_bf16 v[32:35], v[154:157], v[186:189], v[32:35]
	v_mfma_f32_16x16x32_bf16 v[16:19], v[136:139], v[212:215], v[16:19]
	v_mfma_f32_16x16x32_bf16 v[12:15], v[154:157], v[212:215], v[12:15]
	v_mfma_f32_16x16x32_bf16 v[8:11], v[136:139], v[228:231], v[6:9]
	v_mfma_f32_16x16x32_bf16 v[4:7], v[154:157], v[228:231], v[2:5]
	v_mfma_f32_16x16x32_bf16 v[96:99], v[158:161], v[174:177], v[96:99]
	v_mfma_f32_16x16x32_bf16 v[104:107], v[166:169], v[174:177], v[104:107]
	v_mfma_f32_16x16x32_bf16 v[84:87], v[158:161], v[182:185], v[84:87]
	v_mfma_f32_16x16x32_bf16 v[76:79], v[166:169], v[182:185], v[76:79]
	v_mfma_f32_16x16x32_bf16 v[52:55], v[158:161], v[190:193], v[52:55]
	v_mfma_f32_16x16x32_bf16 v[44:47], v[166:169], v[190:193], v[44:47]
	v_mfma_f32_16x16x32_bf16 v[24:27], v[158:161], v[216:219], v[24:27]
	v_mfma_f32_16x16x32_bf16 v[20:23], v[166:169], v[216:219], v[20:23]
	v_mfma_f32_16x16x32_bf16 v[96:99], v[162:165], v[178:181], v[96:99]
	v_mfma_f32_16x16x32_bf16 v[104:107], v[170:173], v[178:181], v[104:107]
	v_mfma_f32_16x16x32_bf16 v[84:87], v[162:165], v[186:189], v[84:87]
	v_mfma_f32_16x16x32_bf16 v[76:79], v[170:173], v[186:189], v[76:79]
	v_mfma_f32_16x16x32_bf16 v[52:55], v[162:165], v[212:215], v[52:55]
	v_mfma_f32_16x16x32_bf16 v[44:47], v[170:173], v[212:215], v[44:47]
	v_mfma_f32_16x16x32_bf16 v[24:27], v[162:165], v[228:231], v[24:27]
	v_mfma_f32_16x16x32_bf16 v[20:23], v[170:173], v[228:231], v[20:23]
	s_barrier
	s_setprio 0
	s_cbranch_scc0 .LBB0_391
	s_mov_b32 m0, s41
	s_nop 0
	buffer_load_dwordx4 v144, s[16:19], s59 offen lds
	s_mov_b32 m0, s33
	s_nop 0
	buffer_load_dwordx4 v146, s[16:19], s59 offen lds
	v_readlane_b32 s8, v251, 45
	v_readlane_b32 s9, v251, 46
	s_and_b64 vcc, exec, s[8:9]
	s_cbranch_vccz .LBB0_394
	s_barrier

; #define PG8_WAIT_V(n) asm volatile("s_waitcnt vmcnt(" #n ")" ::: "memory")
; template <class Epi, bool ALIGN_EPI, bool SP2, class Hook>
; __device__ __forceinline__ void gemm_phase(LAS unsigned char* lds, const Gemm g, const StaticOrder& S, const Epi& E, Acc& acc, const bool fresh, const Hook& H, const int wave_id) {
;     ...
;         for (int t = t0; t < nt; t += 2) {
;             const bool last = (t == nt - 2);
;             const Src a1 = cA + (size_t)(t + 1) * kstep;
;             const Src a2 = last ? nA : cA + (size_t)(t + 2) * kstep, b2 = last ? nB : cB + (size_t)(t + 2) * kstep;
;             const Src a3 = a2 + kstep, b3 = b2 + kstep;
;             if (last && has_next) H(nxt);
;             if constexpr (SP2) {
;             PG8_TRIP_SP2(PG8_WAIT_V(8));
.LBB0_702:
	v_add_u32_e32 v70, 0x10000, v216
	v_add_u32_e32 v118, 0x14000, v216
	ds_read_b128 v[34:37], v70
	ds_read_b128 v[46:49], v70 offset:1024
	ds_read_b128 v[58:61], v70 offset:2048
	ds_read_b128 v[70:73], v70 offset:3072
	ds_read_b128 v[82:85], v118
	ds_read_b128 v[94:97], v118 offset:1024
	ds_read_b128 v[106:109], v118 offset:2048
	ds_read_b128 v[118:121], v118 offset:3072
	s_add_i32 s12, s55, 0xfffe0080
	s_cmp_eq_u32 s57, 4
	s_cselect_b32 s60, s53, s12
	s_cselect_b32 s13, s29, s77
	s_cselect_b32 s12, s28, s76
	s_cselect_b32 s15, s31, s35
	s_cselect_b32 s14, s30, s34
	s_cselect_b32 s58, s54, s56
	s_cselect_b32 s16, s2, s8
	s_cselect_b32 s17, s3, s9
	s_cselect_b32 s18, s26, s10
	s_cselect_b32 s19, s27, s11
	s_or_b32 s59, s60, 0x80
	s_mov_b32 m0, s45
	s_waitcnt vmcnt(14)
	ds_read_b128 v[130:133], v217
	ds_read_b128 v[142:145], v217 offset:1024
	ds_read_b128 v[154:157], v217 offset:2048
	ds_read_b128 v[166:169], v217 offset:3072
	ds_read_b128 v[174:177], v217 offset:4096
	ds_read_b128 v[182:185], v217 offset:5120
	ds_read_b128 v[186:189], v217 offset:6144
	ds_read_b128 v[190:193], v217 offset:7168
	buffer_load_dwordx4 v0, s[8:11], s55 offen lds
	s_mov_b32 m0, s46
	s_nop 0
	buffer_load_dwordx4 v214, s[8:11], s55 offen lds
	s_waitcnt vmcnt(8)
	s_waitcnt lgkmcnt(0)
	s_nop 0
	s_setprio 1
	s_barrier
	v_mfma_f32_16x16x32_bf16 v[178:181], v[34:37], v[130:133], v[178:181]
	v_mfma_f32_16x16x32_bf16 v[170:173], v[58:61], v[130:133], v[170:173]
	v_mfma_f32_16x16x32_bf16 v[150:153], v[34:37], v[154:157], v[150:153]
	v_mfma_f32_16x16x32_bf16 v[146:149], v[58:61], v[154:157], v[146:149]
	v_mfma_f32_16x16x32_bf16 v[126:129], v[34:37], v[174:177], v[126:129]
	v_mfma_f32_16x16x32_bf16 v[122:125], v[58:61], v[174:177], v[122:125]
	v_mfma_f32_16x16x32_bf16 v[102:105], v[34:37], v[186:189], v[102:105]
	v_mfma_f32_16x16x32_bf16 v[98:101], v[58:61], v[186:189], v[98:101]
	v_mfma_f32_16x16x32_bf16 v[178:181], v[46:49], v[142:145], v[178:181]
	v_mfma_f32_16x16x32_bf16 v[170:173], v[70:73], v[142:145], v[170:173]
	v_mfma_f32_16x16x32_bf16 v[150:153], v[46:49], v[166:169], v[150:153]
	v_mfma_f32_16x16x32_bf16 v[146:149], v[70:73], v[166:169], v[146:149]
	v_mfma_f32_16x16x32_bf16 v[126:129], v[46:49], v[182:185], v[126:129]
	v_mfma_f32_16x16x32_bf16 v[122:125], v[70:73], v[182:185], v[122:125]
	v_mfma_f32_16x16x32_bf16 v[102:105], v[46:49], v[190:193], v[102:105]
	v_mfma_f32_16x16x32_bf16 v[98:101], v[70:73], v[190:193], v[98:101]
	v_mfma_f32_16x16x32_bf16 v[162:165], v[82:85], v[130:133], v[162:165]
	v_mfma_f32_16x16x32_bf16 v[138:141], v[82:85], v[154:157], v[138:141]
	v_mfma_f32_16x16x32_bf16 v[134:137], v[106:109], v[154:157], v[134:137]
	v_mfma_f32_16x16x32_bf16 v[114:117], v[82:85], v[174:177], v[114:117]
	v_mfma_f32_16x16x32_bf16 v[110:113], v[106:109], v[174:177], v[110:113]
	v_mfma_f32_16x16x32_bf16 v[90:93], v[82:85], v[186:189], v[90:93]
	v_mfma_f32_16x16x32_bf16 v[86:89], v[106:109], v[186:189], v[86:89]
	v_mfma_f32_16x16x32_bf16 v[162:165], v[94:97], v[142:145], v[162:165]
	v_mfma_f32_16x16x32_bf16 v[130:133], v[106:109], v[130:133], v[158:161]
	v_mfma_f32_16x16x32_bf16 v[138:141], v[94:97], v[166:169], v[138:141]
	v_mfma_f32_16x16x32_bf16 v[134:137], v[118:121], v[166:169], v[134:137]
	v_mfma_f32_16x16x32_bf16 v[114:117], v[94:97], v[182:185], v[114:117]
	v_mfma_f32_16x16x32_bf16 v[110:113], v[118:121], v[182:185], v[110:113]
	v_mfma_f32_16x16x32_bf16 v[90:93], v[94:97], v[190:193], v[90:93]
	v_mfma_f32_16x16x32_bf16 v[86:89], v[118:121], v[190:193], v[86:89]
	v_mfma_f32_16x16x32_bf16 v[130:133], v[118:121], v[142:145], v[130:133]
	s_barrier
	s_setprio 0
	s_mov_b32 m0, s92
	ds_read_b128 v[142:145], v217 offset:16384
	ds_read_b128 v[154:157], v217 offset:17408
	ds_read_b128 v[158:161], v217 offset:18432
	ds_read_b128 v[166:169], v217 offset:19456
	ds_read_b128 v[174:177], v217 offset:20480
	ds_read_b128 v[182:185], v217 offset:21504
	ds_read_b128 v[186:189], v217 offset:22528
	ds_read_b128 v[190:193], v217 offset:23552
	buffer_load_dwordx4 v199, s[12:15], s58 offen lds
	s_mov_b32 m0, s93
	s_add_i32 s61, s58, 0x20000
	buffer_load_dwordx4 v215, s[12:15], s58 offen lds
	s_mov_b32 m0, s94
	s_nop 0
	buffer_load_dwordx4 v199, s[12:15], s61 offen lds
	s_mov_b32 m0, s95
	s_nop 0
	buffer_load_dwordx4 v215, s[12:15], s61 offen lds
	s_mov_b32 m0, s44
	s_nop 0
	buffer_load_dwordx4 v0, s[16:19], s60 offen lds
	s_mov_b32 m0, s36
	s_nop 0
	buffer_load_dwordx4 v214, s[16:19], s60 offen lds
	s_waitcnt vmcnt(8)
	s_waitcnt lgkmcnt(0)
	s_setprio 1
	s_barrier
	v_mfma_f32_16x16x32_bf16 v[78:81], v[34:37], v[142:145], v[78:81]
	v_mfma_f32_16x16x32_bf16 v[74:77], v[58:61], v[142:145], v[74:77]
	v_mfma_f32_16x16x32_bf16 v[54:57], v[34:37], v[158:161], v[54:57]
	v_mfma_f32_16x16x32_bf16 v[50:53], v[58:61], v[158:161], v[50:53]
	v_mfma_f32_16x16x32_bf16 v[30:33], v[34:37], v[174:177], v[30:33]
	v_mfma_f32_16x16x32_bf16 v[26:29], v[58:61], v[174:177], v[26:29]
	v_mfma_f32_16x16x32_bf16 v[14:17], v[34:37], v[186:189], v[14:17]
	v_mfma_f32_16x16x32_bf16 v[10:13], v[58:61], v[186:189], v[10:13]
	v_mfma_f32_16x16x32_bf16 v[78:81], v[46:49], v[154:157], v[78:81]
	v_mfma_f32_16x16x32_bf16 v[74:77], v[70:73], v[154:157], v[74:77]
	v_mfma_f32_16x16x32_bf16 v[54:57], v[46:49], v[166:169], v[54:57]
	v_mfma_f32_16x16x32_bf16 v[50:53], v[70:73], v[166:169], v[50:53]
	v_mfma_f32_16x16x32_bf16 v[30:33], v[46:49], v[182:185], v[30:33]
	v_mfma_f32_16x16x32_bf16 v[26:29], v[70:73], v[182:185], v[26:29]
	v_mfma_f32_16x16x32_bf16 v[14:17], v[46:49], v[190:193], v[14:17]
	v_mfma_f32_16x16x32_bf16 v[10:13], v[70:73], v[190:193], v[10:13]
	v_mfma_f32_16x16x32_bf16 v[42:45], v[82:85], v[158:161], v[42:45]
	v_mfma_f32_16x16x32_bf16 v[38:41], v[106:109], v[158:161], v[38:41]
	v_mfma_f32_16x16x32_bf16 v[22:25], v[82:85], v[174:177], v[22:25]
	v_mfma_f32_16x16x32_bf16 v[18:21], v[106:109], v[174:177], v[18:21]
	v_mfma_f32_16x16x32_bf16 v[6:9], v[82:85], v[186:189], v[6:9]
	v_mfma_f32_16x16x32_bf16 v[2:5], v[106:109], v[186:189], v[2:5]
	v_mfma_f32_16x16x32_bf16 v[34:37], v[82:85], v[142:145], v[66:69]
	v_mfma_f32_16x16x32_bf16 v[46:49], v[106:109], v[142:145], v[62:65]
	v_mfma_f32_16x16x32_bf16 v[42:45], v[94:97], v[166:169], v[42:45]
	v_mfma_f32_16x16x32_bf16 v[38:41], v[118:121], v[166:169], v[38:41]
	v_mfma_f32_16x16x32_bf16 v[22:25], v[94:97], v[182:185], v[22:25]
	v_mfma_f32_16x16x32_bf16 v[18:21], v[118:121], v[182:185], v[18:21]
	v_mfma_f32_16x16x32_bf16 v[6:9], v[94:97], v[190:193], v[6:9]
	v_mfma_f32_16x16x32_bf16 v[2:5], v[118:121], v[190:193], v[2:5]
	v_mfma_f32_16x16x32_bf16 v[34:37], v[94:97], v[154:157], v[34:37]
	v_mfma_f32_16x16x32_bf16 v[46:49], v[118:121], v[154:157], v[46:49]
	s_barrier
; #define PG8_WAIT_V(n) asm volatile("s_waitcnt vmcnt(" #n ")" ::: "memory")
; template <class Epi, bool ALIGN_EPI, bool SP2, class Hook>
; __device__ __forceinline__ void gemm_phase(LAS unsigned char* lds, const Gemm g, const StaticOrder& S, const Epi& E, Acc& acc, const bool fresh, const Hook& H, const int wave_id) {
;     ...
;         for (int t = t0; t < nt; t += 2) {
;             const bool last = (t == nt - 2);
;             const Src a1 = cA + (size_t)(t + 1) * kstep;
;             const Src a2 = last ? nA : cA + (size_t)(t + 2) * kstep, b2 = last ? nB : cB + (size_t)(t + 2) * kstep;
;             const Src a3 = a2 + kstep, b3 = b2 + kstep;
;             if (last && has_next) H(nxt);
;             if constexpr (SP2) {
;             PG8_TRIP_SP2(PG8_WAIT_V(8));
	s_setprio 0
	v_add_u32_e32 v70, 0x18000, v216
	v_add_u32_e32 v118, 0x1c000, v216
	ds_read_b128 v[58:61], v70
	ds_read_b128 v[62:65], v70 offset:1024
	ds_read_b128 v[66:69], v70 offset:2048
	ds_read_b128 v[70:73], v70 offset:3072
	ds_read_b128 v[82:85], v118
	ds_read_b128 v[94:97], v118 offset:1024
	ds_read_b128 v[106:109], v118 offset:2048
	ds_read_b128 v[118:121], v118 offset:3072
	s_add_i32 s60, s60, 0x20000
	s_mov_b32 m0, s37
	ds_read_b128 v[142:145], v217 offset:32768
	ds_read_b128 v[154:157], v217 offset:33792
	ds_read_b128 v[166:169], v217 offset:34816
	ds_read_b128 v[174:177], v217 offset:35840
	ds_read_b128 v[182:185], v217 offset:36864
	ds_read_b128 v[186:189], v217 offset:37888
	ds_read_b128 v[190:193], v217 offset:38912
	ds_read_b128 v[194:197], v217 offset:39936
	buffer_load_dwordx4 v0, s[16:19], s60 offen lds
	s_mov_b32 m0, s38
	s_nop 0
	buffer_load_dwordx4 v214, s[16:19], s60 offen lds
	s_waitcnt vmcnt(8)
	s_waitcnt lgkmcnt(0)
	s_nop 0
	s_setprio 1
	s_barrier
	v_mfma_f32_16x16x32_bf16 v[158:161], v[58:61], v[142:145], v[178:181]
	v_mfma_f32_16x16x32_bf16 v[178:181], v[62:65], v[154:157], v[158:161]
	v_mfma_f32_16x16x32_bf16 v[158:161], v[66:69], v[142:145], v[170:173]
	v_mfma_f32_16x16x32_bf16 v[150:153], v[58:61], v[166:169], v[150:153]
	v_mfma_f32_16x16x32_bf16 v[146:149], v[66:69], v[166:169], v[146:149]
	v_mfma_f32_16x16x32_bf16 v[126:129], v[58:61], v[182:185], v[126:129]
	v_mfma_f32_16x16x32_bf16 v[122:125], v[66:69], v[182:185], v[122:125]
	v_mfma_f32_16x16x32_bf16 v[102:105], v[58:61], v[190:193], v[102:105]
	v_mfma_f32_16x16x32_bf16 v[98:101], v[66:69], v[190:193], v[98:101]
	v_mfma_f32_16x16x32_bf16 v[170:173], v[70:73], v[154:157], v[158:161]
	v_mfma_f32_16x16x32_bf16 v[150:153], v[62:65], v[174:177], v[150:153]
	v_mfma_f32_16x16x32_bf16 v[146:149], v[70:73], v[174:177], v[146:149]
	v_mfma_f32_16x16x32_bf16 v[126:129], v[62:65], v[186:189], v[126:129]
	v_mfma_f32_16x16x32_bf16 v[122:125], v[70:73], v[186:189], v[122:125]
	v_mfma_f32_16x16x32_bf16 v[102:105], v[62:65], v[194:197], v[102:105]
	v_mfma_f32_16x16x32_bf16 v[98:101], v[70:73], v[194:197], v[98:101]
	v_mfma_f32_16x16x32_bf16 v[158:161], v[82:85], v[142:145], v[162:165]
	v_mfma_f32_16x16x32_bf16 v[130:133], v[106:109], v[142:145], v[130:133]
	v_mfma_f32_16x16x32_bf16 v[162:165], v[94:97], v[154:157], v[158:161]
	v_mfma_f32_16x16x32_bf16 v[158:161], v[118:121], v[154:157], v[130:133]
	v_mfma_f32_16x16x32_bf16 v[130:133], v[82:85], v[166:169], v[138:141]
	v_mfma_f32_16x16x32_bf16 v[138:141], v[94:97], v[174:177], v[130:133]
	v_mfma_f32_16x16x32_bf16 v[130:133], v[106:109], v[166:169], v[134:137]
	v_mfma_f32_16x16x32_bf16 v[114:117], v[82:85], v[182:185], v[114:117]
	v_mfma_f32_16x16x32_bf16 v[110:113], v[106:109], v[182:185], v[110:113]
	v_mfma_f32_16x16x32_bf16 v[90:93], v[82:85], v[190:193], v[90:93]
	v_mfma_f32_16x16x32_bf16 v[86:89], v[106:109], v[190:193], v[86:89]
	v_mfma_f32_16x16x32_bf16 v[134:137], v[118:121], v[174:177], v[130:133]
	v_mfma_f32_16x16x32_bf16 v[114:117], v[94:97], v[186:189], v[114:117]
	v_mfma_f32_16x16x32_bf16 v[110:113], v[118:121], v[186:189], v[110:113]
	v_mfma_f32_16x16x32_bf16 v[90:93], v[94:97], v[194:197], v[90:93]
	v_mfma_f32_16x16x32_bf16 v[86:89], v[118:121], v[194:197], v[86:89]
	s_barrier
	s_setprio 0
	s_mov_b32 m0, s39
	s_or_b32 s60, s58, 0x80
	ds_read_b128 v[130:133], v217 offset:49152
	ds_read_b128 v[142:145], v217 offset:50176
	ds_read_b128 v[154:157], v217 offset:51200
	ds_read_b128 v[166:169], v217 offset:52224
	ds_read_b128 v[174:177], v217 offset:53248
	ds_read_b128 v[182:185], v217 offset:54272
	ds_read_b128 v[186:189], v217 offset:55296
	ds_read_b128 v[190:193], v217 offset:56320
	buffer_load_dwordx4 v199, s[12:15], s60 offen lds
	s_mov_b32 m0, s40
	s_add_i32 s58, s58, 0x20080
	buffer_load_dwordx4 v215, s[12:15], s60 offen lds
	s_mov_b32 m0, s43
	s_nop 0
	buffer_load_dwordx4 v199, s[12:15], s58 offen lds
	s_mov_b32 m0, s42
	s_nop 0
	buffer_load_dwordx4 v215, s[12:15], s58 offen lds
	s_mov_b32 m0, s41
	s_nop 0
	buffer_load_dwordx4 v0, s[16:19], s59 offen lds
	s_mov_b32 m0, s33
	s_nop 0
	buffer_load_dwordx4 v214, s[16:19], s59 offen lds
	s_waitcnt vmcnt(8)
	s_waitcnt lgkmcnt(0)
	s_setprio 1
	s_barrier
	v_mfma_f32_16x16x32_bf16 v[78:81], v[58:61], v[130:133], v[78:81]
	v_mfma_f32_16x16x32_bf16 v[74:77], v[66:69], v[130:133], v[74:77]
	v_mfma_f32_16x16x32_bf16 v[54:57], v[58:61], v[154:157], v[54:57]
	v_mfma_f32_16x16x32_bf16 v[50:53], v[66:69], v[154:157], v[50:53]
	v_mfma_f32_16x16x32_bf16 v[30:33], v[58:61], v[174:177], v[30:33]
	v_mfma_f32_16x16x32_bf16 v[26:29], v[66:69], v[174:177], v[26:29]
	v_mfma_f32_16x16x32_bf16 v[14:17], v[58:61], v[186:189], v[14:17]
	v_mfma_f32_16x16x32_bf16 v[10:13], v[66:69], v[186:189], v[10:13]
	v_mfma_f32_16x16x32_bf16 v[78:81], v[62:65], v[142:145], v[78:81]
	v_mfma_f32_16x16x32_bf16 v[74:77], v[70:73], v[142:145], v[74:77]
	v_mfma_f32_16x16x32_bf16 v[54:57], v[62:65], v[166:169], v[54:57]
	v_mfma_f32_16x16x32_bf16 v[50:53], v[70:73], v[166:169], v[50:53]
	v_mfma_f32_16x16x32_bf16 v[30:33], v[62:65], v[182:185], v[30:33]
	v_mfma_f32_16x16x32_bf16 v[26:29], v[70:73], v[182:185], v[26:29]
	v_mfma_f32_16x16x32_bf16 v[14:17], v[62:65], v[190:193], v[14:17]
	v_mfma_f32_16x16x32_bf16 v[10:13], v[70:73], v[190:193], v[10:13]
	v_mfma_f32_16x16x32_bf16 v[34:37], v[82:85], v[130:133], v[34:37]
	v_mfma_f32_16x16x32_bf16 v[66:69], v[94:97], v[142:145], v[34:37]
	v_mfma_f32_16x16x32_bf16 v[34:37], v[106:109], v[130:133], v[46:49]
	v_mfma_f32_16x16x32_bf16 v[62:65], v[118:121], v[142:145], v[34:37]
	v_mfma_f32_16x16x32_bf16 v[34:37], v[82:85], v[154:157], v[42:45]
	v_mfma_f32_16x16x32_bf16 v[42:45], v[94:97], v[166:169], v[34:37]
	v_mfma_f32_16x16x32_bf16 v[34:37], v[106:109], v[154:157], v[38:41]
	v_mfma_f32_16x16x32_bf16 v[22:25], v[82:85], v[174:177], v[22:25]
	v_mfma_f32_16x16x32_bf16 v[18:21], v[106:109], v[174:177], v[18:21]
	v_mfma_f32_16x16x32_bf16 v[6:9], v[82:85], v[186:189], v[6:9]
	v_mfma_f32_16x16x32_bf16 v[2:5], v[106:109], v[186:189], v[2:5]
	v_mfma_f32_16x16x32_bf16 v[38:41], v[118:121], v[166:169], v[34:37]
	v_mfma_f32_16x16x32_bf16 v[22:25], v[94:97], v[182:185], v[22:25]
	v_mfma_f32_16x16x32_bf16 v[18:21], v[118:121], v[182:185], v[18:21]
	v_mfma_f32_16x16x32_bf16 v[6:9], v[94:97], v[190:193], v[6:9]
	v_mfma_f32_16x16x32_bf16 v[2:5], v[118:121], v[190:193], v[2:5]
	s_barrier
	s_setprio 0
	s_add_i32 s57, s57, 2
	s_addk_i32 s55, 0x100
	s_addk_i32 s56, 0x100
	s_cmp_gt_u32 s57, 5
	s_cbranch_scc0 .LBB0_702
	v_readlane_b32 s8, v251, 45
	v_readlane_b32 s9, v251, 46
	s_and_b64 vcc, exec, s[8:9]
	s_cbranch_vccz .LBB0_705
	s_barrier

; #define PG8_WAIT_V(n) asm volatile("s_waitcnt vmcnt(" #n ")" ::: "memory")
; template <class Epi, bool ALIGN_EPI, bool SP2, class Hook>
; __device__ __forceinline__ void gemm_phase(LAS unsigned char* lds, const Gemm g, const StaticOrder& S, const Epi& E, Acc& acc, const bool fresh, const Hook& H, const int wave_id) {
;     ...
;         for (int t = t0; t < nt; t += 2) {
;             const bool last = (t == nt - 2);
;             const Src a1 = cA + (size_t)(t + 1) * kstep;
;             const Src a2 = last ? nA : cA + (size_t)(t + 2) * kstep, b2 = last ? nB : cB + (size_t)(t + 2) * kstep;
;             const Src a3 = a2 + kstep, b3 = b2 + kstep;
;             if (last && has_next) H(nxt);
;             if constexpr (SP2) {
;             PG8_TRIP_SP2(PG8_WAIT_V(8));
.LBB0_779:
	v_add_u32_e32 v0, 0x10000, v230
	s_waitcnt vmcnt(0)
	ds_read_b128 v[130:133], v0
	ds_read_b128 v[134:137], v0 offset:1024
	ds_read_b128 v[138:141], v0 offset:2048
	ds_read_b128 v[142:145], v0 offset:3072
	v_add_u32_e32 v0, 0x14000, v230
	ds_read_b128 v[146:149], v0
	ds_read_b128 v[150:153], v0 offset:1024
	ds_read_b128 v[154:157], v0 offset:2048
	ds_read_b128 v[158:161], v0 offset:3072
	s_add_i32 s12, s2, 0xfffe0080
	s_cmp_eq_u32 s63, 4
	s_cselect_b32 s66, s60, s12
	s_cselect_b32 s13, s53, s77
	s_cselect_b32 s12, s52, s76
	s_cselect_b32 s15, s55, s7
	s_cselect_b32 s14, s54, s6
	s_cselect_b32 s64, s61, s3
	s_cselect_b32 s16, s34, s8
	s_cselect_b32 s17, s35, s9
	s_cselect_b32 s18, s50, s10
	s_cselect_b32 s19, s51, s11
	s_or_b32 s65, s66, 0x80
	s_mov_b32 m0, s45
	ds_read_b128 v[162:165], v231
	ds_read_b128 v[166:169], v231 offset:1024
	ds_read_b128 v[170:173], v231 offset:2048
	ds_read_b128 v[174:177], v231 offset:3072
	ds_read_b128 v[178:181], v231 offset:4096
	ds_read_b128 v[182:185], v231 offset:5120
	ds_read_b128 v[186:189], v231 offset:6144
	ds_read_b128 v[190:193], v231 offset:7168
	buffer_load_dwordx4 v199, s[8:11], s2 offen lds
	s_mov_b32 m0, s46
	s_nop 0
	buffer_load_dwordx4 v228, s[8:11], s2 offen lds
	s_waitcnt vmcnt(8)
	s_waitcnt lgkmcnt(0)
	s_setprio 1
	s_barrier
	v_mfma_f32_16x16x32_bf16 v[126:129], v[130:133], v[162:165], v[126:129]
	v_mfma_f32_16x16x32_bf16 v[122:125], v[138:141], v[162:165], v[122:125]
	v_mfma_f32_16x16x32_bf16 v[118:121], v[130:133], v[170:173], v[118:121]
	v_mfma_f32_16x16x32_bf16 v[114:117], v[138:141], v[170:173], v[114:117]
	v_mfma_f32_16x16x32_bf16 v[110:113], v[130:133], v[178:181], v[110:113]
	v_mfma_f32_16x16x32_bf16 v[106:109], v[138:141], v[178:181], v[106:109]
	v_mfma_f32_16x16x32_bf16 v[102:105], v[130:133], v[186:189], v[102:105]
	v_mfma_f32_16x16x32_bf16 v[98:101], v[138:141], v[186:189], v[98:101]
	v_mfma_f32_16x16x32_bf16 v[126:129], v[134:137], v[166:169], v[126:129]
	v_mfma_f32_16x16x32_bf16 v[122:125], v[142:145], v[166:169], v[122:125]
	v_mfma_f32_16x16x32_bf16 v[118:121], v[134:137], v[174:177], v[118:121]
	v_mfma_f32_16x16x32_bf16 v[114:117], v[142:145], v[174:177], v[114:117]
	v_mfma_f32_16x16x32_bf16 v[110:113], v[134:137], v[182:185], v[110:113]
	v_mfma_f32_16x16x32_bf16 v[106:109], v[142:145], v[182:185], v[106:109]
	v_mfma_f32_16x16x32_bf16 v[102:105], v[134:137], v[190:193], v[102:105]
	v_mfma_f32_16x16x32_bf16 v[98:101], v[142:145], v[190:193], v[98:101]
	v_mfma_f32_16x16x32_bf16 v[94:97], v[146:149], v[162:165], v[94:97]
	v_mfma_f32_16x16x32_bf16 v[90:93], v[154:157], v[162:165], v[90:93]
	v_mfma_f32_16x16x32_bf16 v[86:89], v[146:149], v[170:173], v[86:89]
	v_mfma_f32_16x16x32_bf16 v[82:85], v[154:157], v[170:173], v[82:85]
	v_mfma_f32_16x16x32_bf16 v[78:81], v[146:149], v[178:181], v[78:81]
	v_mfma_f32_16x16x32_bf16 v[74:77], v[154:157], v[178:181], v[74:77]
	v_mfma_f32_16x16x32_bf16 v[70:73], v[146:149], v[186:189], v[70:73]
	v_mfma_f32_16x16x32_bf16 v[66:69], v[154:157], v[186:189], v[66:69]
	v_mfma_f32_16x16x32_bf16 v[94:97], v[150:153], v[166:169], v[94:97]
	v_mfma_f32_16x16x32_bf16 v[90:93], v[158:161], v[166:169], v[90:93]
	v_mfma_f32_16x16x32_bf16 v[86:89], v[150:153], v[174:177], v[86:89]
	v_mfma_f32_16x16x32_bf16 v[82:85], v[158:161], v[174:177], v[82:85]
	v_mfma_f32_16x16x32_bf16 v[78:81], v[150:153], v[182:185], v[78:81]
	v_mfma_f32_16x16x32_bf16 v[74:77], v[158:161], v[182:185], v[74:77]
	v_mfma_f32_16x16x32_bf16 v[70:73], v[150:153], v[190:193], v[70:73]
	v_mfma_f32_16x16x32_bf16 v[66:69], v[158:161], v[190:193], v[66:69]
	s_barrier
	s_setprio 0
	s_mov_b32 m0, s92
	ds_read_b128 v[162:165], v231 offset:16384
	ds_read_b128 v[166:169], v231 offset:17408
	ds_read_b128 v[170:173], v231 offset:18432
	ds_read_b128 v[174:177], v231 offset:19456
	ds_read_b128 v[178:181], v231 offset:20480
	ds_read_b128 v[182:185], v231 offset:21504
	ds_read_b128 v[186:189], v231 offset:22528
	ds_read_b128 v[190:193], v231 offset:23552
	buffer_load_dwordx4 v227, s[12:15], s64 offen lds
	s_mov_b32 m0, s93
	s_add_i32 s67, s64, 0x20000
	buffer_load_dwordx4 v229, s[12:15], s64 offen lds
	s_mov_b32 m0, s94
	s_nop 0
	buffer_load_dwordx4 v227, s[12:15], s67 offen lds
	s_mov_b32 m0, s95
	s_nop 0
	buffer_load_dwordx4 v229, s[12:15], s67 offen lds
	s_mov_b32 m0, s44
	s_nop 0
	buffer_load_dwordx4 v199, s[16:19], s66 offen lds
	s_mov_b32 m0, s36
	s_nop 0
	buffer_load_dwordx4 v228, s[16:19], s66 offen lds
	s_waitcnt vmcnt(8)
	s_waitcnt lgkmcnt(0)
	s_setprio 1
	s_barrier
	v_mfma_f32_16x16x32_bf16 v[62:65], v[130:133], v[162:165], v[62:65]
	v_mfma_f32_16x16x32_bf16 v[58:61], v[138:141], v[162:165], v[58:61]
	v_mfma_f32_16x16x32_bf16 v[54:57], v[130:133], v[170:173], v[54:57]
	v_mfma_f32_16x16x32_bf16 v[50:53], v[138:141], v[170:173], v[50:53]
	v_mfma_f32_16x16x32_bf16 v[46:49], v[130:133], v[178:181], v[46:49]
	v_mfma_f32_16x16x32_bf16 v[42:45], v[138:141], v[178:181], v[42:45]
	v_mfma_f32_16x16x32_bf16 v[38:41], v[130:133], v[186:189], v[38:41]
	v_mfma_f32_16x16x32_bf16 v[34:37], v[138:141], v[186:189], v[34:37]
	v_mfma_f32_16x16x32_bf16 v[62:65], v[134:137], v[166:169], v[62:65]
	v_mfma_f32_16x16x32_bf16 v[58:61], v[142:145], v[166:169], v[58:61]
	v_mfma_f32_16x16x32_bf16 v[54:57], v[134:137], v[174:177], v[54:57]
	v_mfma_f32_16x16x32_bf16 v[50:53], v[142:145], v[174:177], v[50:53]
	v_mfma_f32_16x16x32_bf16 v[46:49], v[134:137], v[182:185], v[46:49]
	v_mfma_f32_16x16x32_bf16 v[42:45], v[142:145], v[182:185], v[42:45]
	v_mfma_f32_16x16x32_bf16 v[38:41], v[134:137], v[190:193], v[38:41]
	v_mfma_f32_16x16x32_bf16 v[34:37], v[142:145], v[190:193], v[34:37]
	v_mfma_f32_16x16x32_bf16 v[30:33], v[146:149], v[162:165], v[30:33]
	v_mfma_f32_16x16x32_bf16 v[26:29], v[154:157], v[162:165], v[26:29]
	v_mfma_f32_16x16x32_bf16 v[22:25], v[146:149], v[170:173], v[22:25]
	v_mfma_f32_16x16x32_bf16 v[18:21], v[154:157], v[170:173], v[18:21]
	v_mfma_f32_16x16x32_bf16 v[14:17], v[146:149], v[178:181], v[14:17]
	v_mfma_f32_16x16x32_bf16 v[10:13], v[154:157], v[178:181], v[10:13]
	v_mfma_f32_16x16x32_bf16 v[6:9], v[146:149], v[186:189], v[6:9]
	v_mfma_f32_16x16x32_bf16 v[2:5], v[154:157], v[186:189], v[2:5]
	v_mfma_f32_16x16x32_bf16 v[30:33], v[150:153], v[166:169], v[30:33]
	v_mfma_f32_16x16x32_bf16 v[26:29], v[158:161], v[166:169], v[26:29]
	v_mfma_f32_16x16x32_bf16 v[22:25], v[150:153], v[174:177], v[22:25]
	v_mfma_f32_16x16x32_bf16 v[18:21], v[158:161], v[174:177], v[18:21]
	v_mfma_f32_16x16x32_bf16 v[14:17], v[150:153], v[182:185], v[14:17]
	v_mfma_f32_16x16x32_bf16 v[10:13], v[158:161], v[182:185], v[10:13]
	v_mfma_f32_16x16x32_bf16 v[6:9], v[150:153], v[190:193], v[6:9]
	v_mfma_f32_16x16x32_bf16 v[2:5], v[158:161], v[190:193], v[2:5]
	s_barrier
; #define PG8_WAIT_V(n) asm volatile("s_waitcnt vmcnt(" #n ")" ::: "memory")
; template <class Epi, bool ALIGN_EPI, bool SP2, class Hook>
; __device__ __forceinline__ void gemm_phase(LAS unsigned char* lds, const Gemm g, const StaticOrder& S, const Epi& E, Acc& acc, const bool fresh, const Hook& H, const int wave_id) {
;     ...
;         for (int t = t0; t < nt; t += 2) {
;             const bool last = (t == nt - 2);
;             const Src a1 = cA + (size_t)(t + 1) * kstep;
;             const Src a2 = last ? nA : cA + (size_t)(t + 2) * kstep, b2 = last ? nB : cB + (size_t)(t + 2) * kstep;
;             const Src a3 = a2 + kstep, b3 = b2 + kstep;
;             if (last && has_next) H(nxt);
;             if constexpr (SP2) {
;             PG8_TRIP_SP2(PG8_WAIT_V(8));
	s_setprio 0
	v_add_u32_e32 v0, 0x18000, v230
	ds_read_b128 v[130:133], v0
	ds_read_b128 v[134:137], v0 offset:1024
	ds_read_b128 v[138:141], v0 offset:2048
	ds_read_b128 v[142:145], v0 offset:3072
	v_add_u32_e32 v0, 0x1c000, v230
	ds_read_b128 v[146:149], v0
	ds_read_b128 v[150:153], v0 offset:1024
	ds_read_b128 v[154:157], v0 offset:2048
	ds_read_b128 v[158:161], v0 offset:3072
	s_add_i32 s66, s66, 0x20000
	s_mov_b32 m0, s37
	ds_read_b128 v[162:165], v231 offset:32768
	ds_read_b128 v[166:169], v231 offset:33792
	ds_read_b128 v[170:173], v231 offset:34816
	ds_read_b128 v[174:177], v231 offset:35840
	ds_read_b128 v[178:181], v231 offset:36864
	ds_read_b128 v[182:185], v231 offset:37888
	ds_read_b128 v[186:189], v231 offset:38912
	ds_read_b128 v[190:193], v231 offset:39936
	buffer_load_dwordx4 v199, s[16:19], s66 offen lds
	s_mov_b32 m0, s38
	s_nop 0
	buffer_load_dwordx4 v228, s[16:19], s66 offen lds
	s_waitcnt vmcnt(8)
	s_waitcnt lgkmcnt(0)
	s_nop 0
	s_setprio 1
	s_barrier
	v_mfma_f32_16x16x32_bf16 v[126:129], v[130:133], v[162:165], v[126:129]
	v_mfma_f32_16x16x32_bf16 v[122:125], v[138:141], v[162:165], v[122:125]
	v_mfma_f32_16x16x32_bf16 v[118:121], v[130:133], v[170:173], v[118:121]
	v_mfma_f32_16x16x32_bf16 v[114:117], v[138:141], v[170:173], v[114:117]
	v_mfma_f32_16x16x32_bf16 v[110:113], v[130:133], v[178:181], v[110:113]
	v_mfma_f32_16x16x32_bf16 v[106:109], v[138:141], v[178:181], v[106:109]
	v_mfma_f32_16x16x32_bf16 v[102:105], v[130:133], v[186:189], v[102:105]
	v_mfma_f32_16x16x32_bf16 v[98:101], v[138:141], v[186:189], v[98:101]
	v_mfma_f32_16x16x32_bf16 v[126:129], v[134:137], v[166:169], v[126:129]
	v_mfma_f32_16x16x32_bf16 v[122:125], v[142:145], v[166:169], v[122:125]
	v_mfma_f32_16x16x32_bf16 v[118:121], v[134:137], v[174:177], v[118:121]
	v_mfma_f32_16x16x32_bf16 v[114:117], v[142:145], v[174:177], v[114:117]
	v_mfma_f32_16x16x32_bf16 v[110:113], v[134:137], v[182:185], v[110:113]
	v_mfma_f32_16x16x32_bf16 v[106:109], v[142:145], v[182:185], v[106:109]
	v_mfma_f32_16x16x32_bf16 v[102:105], v[134:137], v[190:193], v[102:105]
	v_mfma_f32_16x16x32_bf16 v[98:101], v[142:145], v[190:193], v[98:101]
	v_mfma_f32_16x16x32_bf16 v[94:97], v[146:149], v[162:165], v[94:97]
	v_mfma_f32_16x16x32_bf16 v[90:93], v[154:157], v[162:165], v[90:93]
	v_mfma_f32_16x16x32_bf16 v[86:89], v[146:149], v[170:173], v[86:89]
	v_mfma_f32_16x16x32_bf16 v[82:85], v[154:157], v[170:173], v[82:85]
	v_mfma_f32_16x16x32_bf16 v[78:81], v[146:149], v[178:181], v[78:81]
	v_mfma_f32_16x16x32_bf16 v[74:77], v[154:157], v[178:181], v[74:77]
	v_mfma_f32_16x16x32_bf16 v[70:73], v[146:149], v[186:189], v[70:73]
	v_mfma_f32_16x16x32_bf16 v[66:69], v[154:157], v[186:189], v[66:69]
	v_mfma_f32_16x16x32_bf16 v[94:97], v[150:153], v[166:169], v[94:97]
	v_mfma_f32_16x16x32_bf16 v[90:93], v[158:161], v[166:169], v[90:93]
	v_mfma_f32_16x16x32_bf16 v[86:89], v[150:153], v[174:177], v[86:89]
	v_mfma_f32_16x16x32_bf16 v[82:85], v[158:161], v[174:177], v[82:85]
	v_mfma_f32_16x16x32_bf16 v[78:81], v[150:153], v[182:185], v[78:81]
	v_mfma_f32_16x16x32_bf16 v[74:77], v[158:161], v[182:185], v[74:77]
	v_mfma_f32_16x16x32_bf16 v[70:73], v[150:153], v[190:193], v[70:73]
	v_mfma_f32_16x16x32_bf16 v[66:69], v[158:161], v[190:193], v[66:69]
	s_barrier
	s_setprio 0
	s_mov_b32 m0, s39
	s_or_b32 s66, s64, 0x80
	ds_read_b128 v[162:165], v231 offset:49152
	ds_read_b128 v[166:169], v231 offset:50176
	ds_read_b128 v[170:173], v231 offset:51200
	ds_read_b128 v[174:177], v231 offset:52224
	ds_read_b128 v[178:181], v231 offset:53248
	ds_read_b128 v[182:185], v231 offset:54272
	ds_read_b128 v[186:189], v231 offset:55296
	ds_read_b128 v[190:193], v231 offset:56320
	buffer_load_dwordx4 v227, s[12:15], s66 offen lds
	s_mov_b32 m0, s40
	s_add_i32 s64, s64, 0x20080
	buffer_load_dwordx4 v229, s[12:15], s66 offen lds
	s_mov_b32 m0, s43
	s_nop 0
	buffer_load_dwordx4 v227, s[12:15], s64 offen lds
	s_mov_b32 m0, s42
	s_nop 0
	buffer_load_dwordx4 v229, s[12:15], s64 offen lds
	s_mov_b32 m0, s41
	s_nop 0
	buffer_load_dwordx4 v199, s[16:19], s65 offen lds
	s_mov_b32 m0, s33
	s_nop 0
	buffer_load_dwordx4 v228, s[16:19], s65 offen lds
	s_waitcnt vmcnt(8)
	s_waitcnt lgkmcnt(0)
	s_setprio 1
	s_barrier
	v_mfma_f32_16x16x32_bf16 v[62:65], v[130:133], v[162:165], v[62:65]
	v_mfma_f32_16x16x32_bf16 v[58:61], v[138:141], v[162:165], v[58:61]
	v_mfma_f32_16x16x32_bf16 v[54:57], v[130:133], v[170:173], v[54:57]
	v_mfma_f32_16x16x32_bf16 v[50:53], v[138:141], v[170:173], v[50:53]
	v_mfma_f32_16x16x32_bf16 v[46:49], v[130:133], v[178:181], v[46:49]
	v_mfma_f32_16x16x32_bf16 v[42:45], v[138:141], v[178:181], v[42:45]
	v_mfma_f32_16x16x32_bf16 v[38:41], v[130:133], v[186:189], v[38:41]
	v_mfma_f32_16x16x32_bf16 v[34:37], v[138:141], v[186:189], v[34:37]
	v_mfma_f32_16x16x32_bf16 v[62:65], v[134:137], v[166:169], v[62:65]
	v_mfma_f32_16x16x32_bf16 v[58:61], v[142:145], v[166:169], v[58:61]
	v_mfma_f32_16x16x32_bf16 v[54:57], v[134:137], v[174:177], v[54:57]
	v_mfma_f32_16x16x32_bf16 v[50:53], v[142:145], v[174:177], v[50:53]
	v_mfma_f32_16x16x32_bf16 v[46:49], v[134:137], v[182:185], v[46:49]
	v_mfma_f32_16x16x32_bf16 v[42:45], v[142:145], v[182:185], v[42:45]
	v_mfma_f32_16x16x32_bf16 v[38:41], v[134:137], v[190:193], v[38:41]
	v_mfma_f32_16x16x32_bf16 v[34:37], v[142:145], v[190:193], v[34:37]
	v_mfma_f32_16x16x32_bf16 v[30:33], v[146:149], v[162:165], v[30:33]
	v_mfma_f32_16x16x32_bf16 v[26:29], v[154:157], v[162:165], v[26:29]
	v_mfma_f32_16x16x32_bf16 v[22:25], v[146:149], v[170:173], v[22:25]
	v_mfma_f32_16x16x32_bf16 v[18:21], v[154:157], v[170:173], v[18:21]
	v_mfma_f32_16x16x32_bf16 v[14:17], v[146:149], v[178:181], v[14:17]
	v_mfma_f32_16x16x32_bf16 v[10:13], v[154:157], v[178:181], v[10:13]
	v_mfma_f32_16x16x32_bf16 v[6:9], v[146:149], v[186:189], v[6:9]
	v_mfma_f32_16x16x32_bf16 v[2:5], v[154:157], v[186:189], v[2:5]
	v_mfma_f32_16x16x32_bf16 v[30:33], v[150:153], v[166:169], v[30:33]
	v_mfma_f32_16x16x32_bf16 v[26:29], v[158:161], v[166:169], v[26:29]
	v_mfma_f32_16x16x32_bf16 v[22:25], v[150:153], v[174:177], v[22:25]
	v_mfma_f32_16x16x32_bf16 v[18:21], v[158:161], v[174:177], v[18:21]
	v_mfma_f32_16x16x32_bf16 v[14:17], v[150:153], v[182:185], v[14:17]
	v_mfma_f32_16x16x32_bf16 v[10:13], v[158:161], v[182:185], v[10:13]
	v_mfma_f32_16x16x32_bf16 v[6:9], v[150:153], v[190:193], v[6:9]
	v_mfma_f32_16x16x32_bf16 v[2:5], v[158:161], v[190:193], v[2:5]
	s_barrier
	s_setprio 0
	s_add_i32 s63, s63, 2
	s_addk_i32 s2, 0x100
	s_addk_i32 s3, 0x100
	s_cmp_gt_u32 s63, 5
	s_cbranch_scc0 .LBB0_779
	v_readlane_b32 s2, v251, 45
	v_readlane_b32 s3, v251, 46
	s_and_b64 vcc, exec, s[2:3]
	s_cbranch_vccz .LBB0_782
	s_barrier

; #define PG8_WAIT_V(n) asm volatile("s_waitcnt vmcnt(" #n ")" ::: "memory")
; template <class Epi, bool ALIGN_EPI, bool SP2, class Hook>
; __device__ __forceinline__ void gemm_phase(LAS unsigned char* lds, const Gemm g, const StaticOrder& S, const Epi& E, Acc& acc, const bool fresh, const Hook& H, const int wave_id) {
;     ...
;         for (int t = t0; t < nt; t += 2) {
;             const bool last = (t == nt - 2);
;             const Src a1 = cA + (size_t)(t + 1) * kstep;
;             const Src a2 = last ? nA : cA + (size_t)(t + 2) * kstep, b2 = last ? nB : cB + (size_t)(t + 2) * kstep;
;             const Src a3 = a2 + kstep, b3 = b2 + kstep;
;             if (last && has_next) H(nxt);
;             if constexpr (SP2) {
;             PG8_TRIP_SP2(PG8_WAIT_V(8));
.LBB0_903:
	s_add_i32 s100, s55, 0xfffe0000
	v_add_u32_e32 v70, 0x10000, v216
	v_add_u32_e32 v118, 0x14000, v216
	ds_read_b128 v[34:37], v70
	ds_read_b128 v[46:49], v70 offset:1024
	ds_read_b128 v[58:61], v70 offset:2048
	ds_read_b128 v[70:73], v70 offset:3072
	ds_read_b128 v[82:85], v118
	ds_read_b128 v[94:97], v118 offset:1024
	ds_read_b128 v[106:109], v118 offset:2048
	ds_read_b128 v[118:121], v118 offset:3072
	s_mov_b32 m0, s41
	s_nop 0
	buffer_load_dwordx4 v0, s[8:11], s100 offen lds
	s_mov_b32 m0, s33
	s_nop 0
	buffer_load_dwordx4 v214, s[8:11], s100 offen lds
	s_mov_b32 m0, s45
	ds_read_b128 v[130:133], v217
	ds_read_b128 v[142:145], v217 offset:1024
	ds_read_b128 v[154:157], v217 offset:2048
	ds_read_b128 v[166:169], v217 offset:3072
	ds_read_b128 v[174:177], v217 offset:4096
	ds_read_b128 v[182:185], v217 offset:5120
	ds_read_b128 v[186:189], v217 offset:6144
	ds_read_b128 v[190:193], v217 offset:7168
	buffer_load_dwordx4 v0, s[8:11], s55 offen lds
	s_mov_b32 m0, s46
	s_nop 0
	buffer_load_dwordx4 v214, s[8:11], s55 offen lds
	s_waitcnt vmcnt(8)
	s_waitcnt lgkmcnt(0)
	s_nop 0
	s_setprio 1
	s_barrier
	v_mfma_f32_16x16x32_bf16 v[178:181], v[34:37], v[130:133], v[178:181]
	v_mfma_f32_16x16x32_bf16 v[170:173], v[58:61], v[130:133], v[170:173]
	v_mfma_f32_16x16x32_bf16 v[150:153], v[34:37], v[154:157], v[150:153]
	v_mfma_f32_16x16x32_bf16 v[146:149], v[58:61], v[154:157], v[146:149]
	v_mfma_f32_16x16x32_bf16 v[126:129], v[34:37], v[174:177], v[126:129]
	v_mfma_f32_16x16x32_bf16 v[122:125], v[58:61], v[174:177], v[122:125]
	v_mfma_f32_16x16x32_bf16 v[102:105], v[34:37], v[186:189], v[102:105]
	v_mfma_f32_16x16x32_bf16 v[98:101], v[58:61], v[186:189], v[98:101]
	v_mfma_f32_16x16x32_bf16 v[178:181], v[46:49], v[142:145], v[178:181]
	v_mfma_f32_16x16x32_bf16 v[170:173], v[70:73], v[142:145], v[170:173]
	v_mfma_f32_16x16x32_bf16 v[150:153], v[46:49], v[166:169], v[150:153]
	v_mfma_f32_16x16x32_bf16 v[146:149], v[70:73], v[166:169], v[146:149]
	v_mfma_f32_16x16x32_bf16 v[126:129], v[46:49], v[182:185], v[126:129]
	v_mfma_f32_16x16x32_bf16 v[122:125], v[70:73], v[182:185], v[122:125]
	v_mfma_f32_16x16x32_bf16 v[102:105], v[46:49], v[190:193], v[102:105]
	v_mfma_f32_16x16x32_bf16 v[98:101], v[70:73], v[190:193], v[98:101]
	v_mfma_f32_16x16x32_bf16 v[162:165], v[82:85], v[130:133], v[162:165]
	v_mfma_f32_16x16x32_bf16 v[138:141], v[82:85], v[154:157], v[138:141]
	v_mfma_f32_16x16x32_bf16 v[134:137], v[106:109], v[154:157], v[134:137]
	v_mfma_f32_16x16x32_bf16 v[114:117], v[82:85], v[174:177], v[114:117]
	v_mfma_f32_16x16x32_bf16 v[110:113], v[106:109], v[174:177], v[110:113]
	v_mfma_f32_16x16x32_bf16 v[90:93], v[82:85], v[186:189], v[90:93]
	v_mfma_f32_16x16x32_bf16 v[86:89], v[106:109], v[186:189], v[86:89]
	v_mfma_f32_16x16x32_bf16 v[162:165], v[94:97], v[142:145], v[162:165]
	v_mfma_f32_16x16x32_bf16 v[130:133], v[106:109], v[130:133], v[158:161]
	v_mfma_f32_16x16x32_bf16 v[138:141], v[94:97], v[166:169], v[138:141]
	v_mfma_f32_16x16x32_bf16 v[134:137], v[118:121], v[166:169], v[134:137]
	v_mfma_f32_16x16x32_bf16 v[114:117], v[94:97], v[182:185], v[114:117]
	v_mfma_f32_16x16x32_bf16 v[110:113], v[118:121], v[182:185], v[110:113]
	v_mfma_f32_16x16x32_bf16 v[90:93], v[94:97], v[190:193], v[90:93]
	v_mfma_f32_16x16x32_bf16 v[86:89], v[118:121], v[190:193], v[86:89]
	v_mfma_f32_16x16x32_bf16 v[130:133], v[118:121], v[142:145], v[130:133]
	s_barrier
	s_setprio 0
	s_add_i32 s12, s55, 0xfffe0080
	s_cmp_eq_u32 s57, 4
	s_cselect_b32 s60, s53, s12
	s_cselect_b32 s13, s29, s77
	s_cselect_b32 s12, s28, s76
	s_cselect_b32 s15, s31, s35
	s_cselect_b32 s14, s30, s34
	s_cselect_b32 s58, s54, s56
	s_cselect_b32 s16, s2, s8
	s_cselect_b32 s17, s3, s9
	s_cselect_b32 s18, s26, s10
	s_cselect_b32 s19, s27, s11
	s_or_b32 s59, s60, 0x80
	s_mov_b32 m0, s92
	ds_read_b128 v[142:145], v217 offset:16384
	ds_read_b128 v[154:157], v217 offset:17408
	ds_read_b128 v[158:161], v217 offset:18432
	ds_read_b128 v[166:169], v217 offset:19456
	ds_read_b128 v[174:177], v217 offset:20480
	ds_read_b128 v[182:185], v217 offset:21504
	ds_read_b128 v[186:189], v217 offset:22528
	ds_read_b128 v[190:193], v217 offset:23552
	buffer_load_dwordx4 v199, s[12:15], s58 offen lds
	s_mov_b32 m0, s93
	s_add_i32 s61, s58, 0x20000
	buffer_load_dwordx4 v215, s[12:15], s58 offen lds
	s_mov_b32 m0, s94
	s_nop 0
	buffer_load_dwordx4 v199, s[12:15], s61 offen lds
	s_mov_b32 m0, s95
	s_nop 0
	buffer_load_dwordx4 v215, s[12:15], s61 offen lds
	s_waitcnt vmcnt(6)
	s_waitcnt lgkmcnt(0)
	s_nop 0
	s_setprio 1
	s_barrier
	v_mfma_f32_16x16x32_bf16 v[78:81], v[34:37], v[142:145], v[78:81]
	v_mfma_f32_16x16x32_bf16 v[74:77], v[58:61], v[142:145], v[74:77]
	v_mfma_f32_16x16x32_bf16 v[54:57], v[34:37], v[158:161], v[54:57]
	v_mfma_f32_16x16x32_bf16 v[50:53], v[58:61], v[158:161], v[50:53]
	v_mfma_f32_16x16x32_bf16 v[30:33], v[34:37], v[174:177], v[30:33]
	v_mfma_f32_16x16x32_bf16 v[26:29], v[58:61], v[174:177], v[26:29]
	v_mfma_f32_16x16x32_bf16 v[14:17], v[34:37], v[186:189], v[14:17]
	v_mfma_f32_16x16x32_bf16 v[10:13], v[58:61], v[186:189], v[10:13]
	v_mfma_f32_16x16x32_bf16 v[78:81], v[46:49], v[154:157], v[78:81]
	v_mfma_f32_16x16x32_bf16 v[74:77], v[70:73], v[154:157], v[74:77]
	v_mfma_f32_16x16x32_bf16 v[54:57], v[46:49], v[166:169], v[54:57]
	v_mfma_f32_16x16x32_bf16 v[50:53], v[70:73], v[166:169], v[50:53]
	v_mfma_f32_16x16x32_bf16 v[30:33], v[46:49], v[182:185], v[30:33]
	v_mfma_f32_16x16x32_bf16 v[26:29], v[70:73], v[182:185], v[26:29]
	v_mfma_f32_16x16x32_bf16 v[14:17], v[46:49], v[190:193], v[14:17]
	v_mfma_f32_16x16x32_bf16 v[10:13], v[70:73], v[190:193], v[10:13]
	v_mfma_f32_16x16x32_bf16 v[42:45], v[82:85], v[158:161], v[42:45]
	v_mfma_f32_16x16x32_bf16 v[38:41], v[106:109], v[158:161], v[38:41]
	v_mfma_f32_16x16x32_bf16 v[22:25], v[82:85], v[174:177], v[22:25]
	v_mfma_f32_16x16x32_bf16 v[18:21], v[106:109], v[174:177], v[18:21]
	v_mfma_f32_16x16x32_bf16 v[6:9], v[82:85], v[186:189], v[6:9]
	v_mfma_f32_16x16x32_bf16 v[2:5], v[106:109], v[186:189], v[2:5]
	v_mfma_f32_16x16x32_bf16 v[34:37], v[82:85], v[142:145], v[66:69]
	v_mfma_f32_16x16x32_bf16 v[46:49], v[106:109], v[142:145], v[62:65]
	v_mfma_f32_16x16x32_bf16 v[42:45], v[94:97], v[166:169], v[42:45]
	v_mfma_f32_16x16x32_bf16 v[38:41], v[118:121], v[166:169], v[38:41]
	v_mfma_f32_16x16x32_bf16 v[22:25], v[94:97], v[182:185], v[22:25]
	v_mfma_f32_16x16x32_bf16 v[18:21], v[118:121], v[182:185], v[18:21]
	v_mfma_f32_16x16x32_bf16 v[6:9], v[94:97], v[190:193], v[6:9]
	v_mfma_f32_16x16x32_bf16 v[2:5], v[118:121], v[190:193], v[2:5]
	v_mfma_f32_16x16x32_bf16 v[34:37], v[94:97], v[154:157], v[34:37]
	v_mfma_f32_16x16x32_bf16 v[46:49], v[118:121], v[154:157], v[46:49]
	s_barrier
; #define PG8_STAGE(bufoff, gbase, voff) do { const Src _g = (gbase); _Pragma("unroll") for (int _i = 0; _i < 2; ++_i) \
;         __builtin_amdgcn_raw_ptr_buffer_load_lds(_g.r, (LAS unsigned*)(lds + (bufoff) + ldsw + _i * 8192), 16, (voff)[_i], _g.o, 0, 0); } while (0)
; #define PG8_WAIT_V(n) asm volatile("s_waitcnt vmcnt(" #n ")" ::: "memory")
; template <class Epi, bool ALIGN_EPI, bool SP2, class Hook>
; __device__ __forceinline__ void gemm_phase(LAS unsigned char* lds, const Gemm g, const StaticOrder& S, const Epi& E, Acc& acc, const bool fresh, const Hook& H, const int wave_id) {
;     ...
;         for (int t = t0; t < nt; t += 2) {
;             const bool last = (t == nt - 2);
;             const Src a1 = cA + (size_t)(t + 1) * kstep;
;             const Src a2 = last ? nA : cA + (size_t)(t + 2) * kstep, b2 = last ? nB : cB + (size_t)(t + 2) * kstep;
;             const Src a3 = a2 + kstep, b3 = b2 + kstep;
;             if (last && has_next) H(nxt);
;             if constexpr (SP2) {
;             PG8_TRIP_SP2(PG8_WAIT_V(8));
;             } else {
;             PG8_LDB(B0, 0, 0); PG8_SCHED; PG8_LDA(At, 0, 0); PG8_STAGE(PG8_SA(1, 1), a1 + hstepA, voffA);
;             PG8_WAIT_L(8); PG8_BAR; PG8_WAIT_L(0); PG8_MMA(0, 0, At, B0); PG8_BAR; PG8_SCHED;
;             PG8_LDB(B1, 0, 1); PG8_STAGE(PG8_SB(0, 0), b2, voffB);
;             PG8_BAR; PG8_WAIT_L(0); PG8_MMA(0, 1, At, B1); PG8_BAR;
;             PG8_LDA(At, 0, 1); PG8_STAGE(PG8_SA(0, 0), a2, voffA);
;             PG8_BAR; PG8_WAIT_L(0); PG8_MMA(1, 0, At, B0); PG8_BAR; PG8_SCHED;
;             PG8_STAGE(PG8_SB(0, 1), b2 + hstep, voffB);
;             PG8_WAIT_V(6); PG8_BAR; PG8_MMA(1, 1, At, B1); PG8_BAR;
;             PG8_LDB(B0, 1, 0); PG8_SCHED; PG8_LDA(At, 1, 0); PG8_STAGE(PG8_SA(0, 1), a2 + hstepA, voffA);
;             PG8_WAIT_L(8); PG8_BAR; PG8_WAIT_L(0); PG8_MMA(0, 0, At, B0); PG8_BAR; PG8_SCHED;
;             PG8_LDB(B1, 1, 1); PG8_STAGE(PG8_SB(1, 0), b3, voffB);
;             PG8_BAR; PG8_WAIT_L(0); PG8_MMA(0, 1, At, B1); PG8_BAR;
;             PG8_LDA(At, 1, 1); PG8_STAGE(PG8_SA(1, 0), a3, voffA);
;             PG8_BAR; PG8_WAIT_L(0); PG8_MMA(1, 0, At, B0); PG8_BAR; PG8_SCHED;
;             PG8_STAGE(PG8_SB(1, 1), b3 + hstep, voffB);
;             PG8_WAIT_V(6); PG8_BAR; PG8_MMA(1, 1, At, B1); PG8_BAR;
;             }
;         }
;         if constexpr (ALIGN_EPI) { if (wr == 0) PG8_BAR; }
	s_setprio 0
	s_mov_b32 m0, s44
	s_nop 0
	buffer_load_dwordx4 v0, s[16:19], s60 offen lds
	s_mov_b32 m0, s36
	s_nop 0
	buffer_load_dwordx4 v214, s[16:19], s60 offen lds
	v_add_u32_e32 v70, 0x18000, v216
	v_add_u32_e32 v118, 0x1c000, v216
	ds_read_b128 v[58:61], v70
	ds_read_b128 v[62:65], v70 offset:1024
	ds_read_b128 v[66:69], v70 offset:2048
	ds_read_b128 v[70:73], v70 offset:3072
	ds_read_b128 v[82:85], v118
	ds_read_b128 v[94:97], v118 offset:1024
	ds_read_b128 v[106:109], v118 offset:2048
	ds_read_b128 v[118:121], v118 offset:3072
	s_add_i32 s60, s60, 0x20000
	s_mov_b32 m0, s37
	ds_read_b128 v[142:145], v217 offset:32768
	ds_read_b128 v[154:157], v217 offset:33792
	ds_read_b128 v[166:169], v217 offset:34816
	ds_read_b128 v[174:177], v217 offset:35840
	ds_read_b128 v[182:185], v217 offset:36864
	ds_read_b128 v[186:189], v217 offset:37888
	ds_read_b128 v[190:193], v217 offset:38912
	ds_read_b128 v[194:197], v217 offset:39936
	buffer_load_dwordx4 v0, s[16:19], s60 offen lds
	s_mov_b32 m0, s38
	s_nop 0
	buffer_load_dwordx4 v214, s[16:19], s60 offen lds
	s_waitcnt vmcnt(8)
	s_waitcnt lgkmcnt(0)
	s_nop 0
	s_setprio 1
	s_barrier
	v_mfma_f32_16x16x32_bf16 v[158:161], v[58:61], v[142:145], v[178:181]
	v_mfma_f32_16x16x32_bf16 v[178:181], v[62:65], v[154:157], v[158:161]
	v_mfma_f32_16x16x32_bf16 v[158:161], v[66:69], v[142:145], v[170:173]
	v_mfma_f32_16x16x32_bf16 v[150:153], v[58:61], v[166:169], v[150:153]
	v_mfma_f32_16x16x32_bf16 v[146:149], v[66:69], v[166:169], v[146:149]
	v_mfma_f32_16x16x32_bf16 v[126:129], v[58:61], v[182:185], v[126:129]
	v_mfma_f32_16x16x32_bf16 v[122:125], v[66:69], v[182:185], v[122:125]
	v_mfma_f32_16x16x32_bf16 v[102:105], v[58:61], v[190:193], v[102:105]
	v_mfma_f32_16x16x32_bf16 v[98:101], v[66:69], v[190:193], v[98:101]
	v_mfma_f32_16x16x32_bf16 v[170:173], v[70:73], v[154:157], v[158:161]
	v_mfma_f32_16x16x32_bf16 v[150:153], v[62:65], v[174:177], v[150:153]
	v_mfma_f32_16x16x32_bf16 v[146:149], v[70:73], v[174:177], v[146:149]
	v_mfma_f32_16x16x32_bf16 v[126:129], v[62:65], v[186:189], v[126:129]
	v_mfma_f32_16x16x32_bf16 v[122:125], v[70:73], v[186:189], v[122:125]
	v_mfma_f32_16x16x32_bf16 v[102:105], v[62:65], v[194:197], v[102:105]
	v_mfma_f32_16x16x32_bf16 v[98:101], v[70:73], v[194:197], v[98:101]
	v_mfma_f32_16x16x32_bf16 v[158:161], v[82:85], v[142:145], v[162:165]
	v_mfma_f32_16x16x32_bf16 v[130:133], v[106:109], v[142:145], v[130:133]
	v_mfma_f32_16x16x32_bf16 v[162:165], v[94:97], v[154:157], v[158:161]
	v_mfma_f32_16x16x32_bf16 v[158:161], v[118:121], v[154:157], v[130:133]
	v_mfma_f32_16x16x32_bf16 v[130:133], v[82:85], v[166:169], v[138:141]
	v_mfma_f32_16x16x32_bf16 v[138:141], v[94:97], v[174:177], v[130:133]
	v_mfma_f32_16x16x32_bf16 v[130:133], v[106:109], v[166:169], v[134:137]
	v_mfma_f32_16x16x32_bf16 v[114:117], v[82:85], v[182:185], v[114:117]
	v_mfma_f32_16x16x32_bf16 v[110:113], v[106:109], v[182:185], v[110:113]
	v_mfma_f32_16x16x32_bf16 v[90:93], v[82:85], v[190:193], v[90:93]
	v_mfma_f32_16x16x32_bf16 v[86:89], v[106:109], v[190:193], v[86:89]
	v_mfma_f32_16x16x32_bf16 v[134:137], v[118:121], v[174:177], v[130:133]
	v_mfma_f32_16x16x32_bf16 v[114:117], v[94:97], v[186:189], v[114:117]
	v_mfma_f32_16x16x32_bf16 v[110:113], v[118:121], v[186:189], v[110:113]
	v_mfma_f32_16x16x32_bf16 v[90:93], v[94:97], v[194:197], v[90:93]
	v_mfma_f32_16x16x32_bf16 v[86:89], v[118:121], v[194:197], v[86:89]
	s_barrier
	s_setprio 0
	s_mov_b32 m0, s39
	s_or_b32 s60, s58, 0x80
	ds_read_b128 v[130:133], v217 offset:49152
	ds_read_b128 v[142:145], v217 offset:50176
	ds_read_b128 v[154:157], v217 offset:51200
	ds_read_b128 v[166:169], v217 offset:52224
	ds_read_b128 v[174:177], v217 offset:53248
	ds_read_b128 v[182:185], v217 offset:54272
	ds_read_b128 v[186:189], v217 offset:55296
	ds_read_b128 v[190:193], v217 offset:56320
	buffer_load_dwordx4 v199, s[12:15], s60 offen lds
	s_mov_b32 m0, s40
	s_add_i32 s58, s58, 0x20080
	buffer_load_dwordx4 v215, s[12:15], s60 offen lds
	s_mov_b32 m0, s43
	s_nop 0
	buffer_load_dwordx4 v199, s[12:15], s58 offen lds
	s_mov_b32 m0, s42
	s_nop 0
	buffer_load_dwordx4 v215, s[12:15], s58 offen lds
	s_add_i32 s57, s57, 2
	s_addk_i32 s55, 0x100
	s_addk_i32 s56, 0x100
	s_cmp_gt_u32 s57, 5
	s_waitcnt vmcnt(6)
	s_waitcnt lgkmcnt(0)
	s_setprio 1
	s_barrier
	v_mfma_f32_16x16x32_bf16 v[78:81], v[58:61], v[130:133], v[78:81]
	v_mfma_f32_16x16x32_bf16 v[74:77], v[66:69], v[130:133], v[74:77]
	v_mfma_f32_16x16x32_bf16 v[54:57], v[58:61], v[154:157], v[54:57]
	v_mfma_f32_16x16x32_bf16 v[50:53], v[66:69], v[154:157], v[50:53]
	v_mfma_f32_16x16x32_bf16 v[30:33], v[58:61], v[174:177], v[30:33]
	v_mfma_f32_16x16x32_bf16 v[26:29], v[66:69], v[174:177], v[26:29]
	v_mfma_f32_16x16x32_bf16 v[14:17], v[58:61], v[186:189], v[14:17]
	v_mfma_f32_16x16x32_bf16 v[10:13], v[66:69], v[186:189], v[10:13]
	v_mfma_f32_16x16x32_bf16 v[78:81], v[62:65], v[142:145], v[78:81]
	v_mfma_f32_16x16x32_bf16 v[74:77], v[70:73], v[142:145], v[74:77]
	v_mfma_f32_16x16x32_bf16 v[54:57], v[62:65], v[166:169], v[54:57]
	v_mfma_f32_16x16x32_bf16 v[50:53], v[70:73], v[166:169], v[50:53]
	v_mfma_f32_16x16x32_bf16 v[30:33], v[62:65], v[182:185], v[30:33]
	v_mfma_f32_16x16x32_bf16 v[26:29], v[70:73], v[182:185], v[26:29]
	v_mfma_f32_16x16x32_bf16 v[14:17], v[62:65], v[190:193], v[14:17]
	v_mfma_f32_16x16x32_bf16 v[10:13], v[70:73], v[190:193], v[10:13]
	v_mfma_f32_16x16x32_bf16 v[34:37], v[82:85], v[130:133], v[34:37]
	v_mfma_f32_16x16x32_bf16 v[66:69], v[94:97], v[142:145], v[34:37]
	v_mfma_f32_16x16x32_bf16 v[34:37], v[106:109], v[130:133], v[46:49]
	v_mfma_f32_16x16x32_bf16 v[62:65], v[118:121], v[142:145], v[34:37]
	v_mfma_f32_16x16x32_bf16 v[34:37], v[82:85], v[154:157], v[42:45]
	v_mfma_f32_16x16x32_bf16 v[42:45], v[94:97], v[166:169], v[34:37]
	v_mfma_f32_16x16x32_bf16 v[34:37], v[106:109], v[154:157], v[38:41]
	v_mfma_f32_16x16x32_bf16 v[22:25], v[82:85], v[174:177], v[22:25]
	v_mfma_f32_16x16x32_bf16 v[18:21], v[106:109], v[174:177], v[18:21]
	v_mfma_f32_16x16x32_bf16 v[6:9], v[82:85], v[186:189], v[6:9]
	v_mfma_f32_16x16x32_bf16 v[2:5], v[106:109], v[186:189], v[2:5]
	v_mfma_f32_16x16x32_bf16 v[38:41], v[118:121], v[166:169], v[34:37]
	v_mfma_f32_16x16x32_bf16 v[22:25], v[94:97], v[182:185], v[22:25]
	v_mfma_f32_16x16x32_bf16 v[18:21], v[118:121], v[182:185], v[18:21]
	v_mfma_f32_16x16x32_bf16 v[6:9], v[94:97], v[190:193], v[6:9]
	v_mfma_f32_16x16x32_bf16 v[2:5], v[118:121], v[190:193], v[2:5]
	s_barrier
	s_setprio 0
	s_cbranch_scc0 .LBB0_903
	s_mov_b32 m0, s41
	s_nop 0
	buffer_load_dwordx4 v0, s[16:19], s59 offen lds
	s_mov_b32 m0, s33
	s_nop 0
	buffer_load_dwordx4 v214, s[16:19], s59 offen lds
	v_readlane_b32 s8, v251, 45
	v_readlane_b32 s9, v251, 46
	s_and_b64 vcc, exec, s[8:9]
	s_cbranch_vccz .LBB0_906
	s_barrier

; template <class Epi, bool ALIGN_EPI, bool SP2, class Hook>
; __device__ __forceinline__ void gemm_phase(LAS unsigned char* lds, const Gemm g, const StaticOrder& S, const Epi& E, Acc& acc, const bool fresh, const Hook& H, const int wave_id) {
;     ...
;             const Src a1 = cA + (size_t)(t + 1) * kstep;
;             const Src a2 = last ? nA : cA + (size_t)(t + 2) * kstep, b2 = last ? nB : cB + (size_t)(t + 2) * kstep;
;             const Src a3 = a2 + kstep, b3 = b2 + kstep;
.LBB0_1029:
.LBB0_1030:
	v_add_u32_e32 v0, 0x10000, v230
	ds_read_b128 v[130:133], v0
	ds_read_b128 v[134:137], v0 offset:1024
	ds_read_b128 v[138:141], v0 offset:2048
	ds_read_b128 v[142:145], v0 offset:3072
	v_add_u32_e32 v0, 0x14000, v230
	ds_read_b128 v[146:149], v0
	ds_read_b128 v[150:153], v0 offset:1024
	ds_read_b128 v[154:157], v0 offset:2048
	ds_read_b128 v[158:161], v0 offset:3072
	s_lshl_b32 s55, s20, 7
	s_add_i32 s18, s73, s55
	s_and_b64 s[12:13], s[16:17], exec
	s_cselect_b32 s13, s31, s9
	s_cselect_b32 s12, s30, s8
	s_cselect_b32 s15, s35, s11
	s_cselect_b32 s14, s34, s10
	s_cselect_b32 s56, s68, s18
	s_add_i32 s21, s74, s55
	s_and_b64 s[16:17], s[16:17], exec
	s_cselect_b32 s54, s69, s21
	s_cselect_b32 s17, s51, s77
	s_cselect_b32 s16, s50, s76
	s_cselect_b32 s19, s53, s7
	s_cselect_b32 s18, s52, s6
	s_or_b32 s21, s56, 0x80
	s_or_b32 s57, s54, 0x80
	s_add_i32 s55, s55, s75
	s_add_i32 s100, s55, 0xfffe0000
	s_mov_b32 m0, s41
	s_nop 0
	buffer_load_dwordx4 v199, s[8:11], s100 offen lds
	s_mov_b32 m0, s33
	s_nop 0
	buffer_load_dwordx4 v228, s[8:11], s100 offen lds
	s_mov_b32 m0, s45
	ds_read_b128 v[162:165], v231
	ds_read_b128 v[166:169], v231 offset:1024
	ds_read_b128 v[170:173], v231 offset:2048
	ds_read_b128 v[174:177], v231 offset:3072
	ds_read_b128 v[178:181], v231 offset:4096
	ds_read_b128 v[182:185], v231 offset:5120
	ds_read_b128 v[186:189], v231 offset:6144
	ds_read_b128 v[190:193], v231 offset:7168
	buffer_load_dwordx4 v199, s[8:11], s55 offen lds
	s_mov_b32 m0, s46
	s_nop 0
	buffer_load_dwordx4 v228, s[8:11], s55 offen lds
	s_waitcnt vmcnt(8)
	s_waitcnt lgkmcnt(0)
	s_setprio 1
	s_barrier
	v_mfma_f32_16x16x32_bf16 v[126:129], v[130:133], v[162:165], v[126:129]
	v_mfma_f32_16x16x32_bf16 v[122:125], v[138:141], v[162:165], v[122:125]
	v_mfma_f32_16x16x32_bf16 v[118:121], v[130:133], v[170:173], v[118:121]
	v_mfma_f32_16x16x32_bf16 v[114:117], v[138:141], v[170:173], v[114:117]
	v_mfma_f32_16x16x32_bf16 v[110:113], v[130:133], v[178:181], v[110:113]
	v_mfma_f32_16x16x32_bf16 v[106:109], v[138:141], v[178:181], v[106:109]
	v_mfma_f32_16x16x32_bf16 v[102:105], v[130:133], v[186:189], v[102:105]
	v_mfma_f32_16x16x32_bf16 v[98:101], v[138:141], v[186:189], v[98:101]
	v_mfma_f32_16x16x32_bf16 v[126:129], v[134:137], v[166:169], v[126:129]
	v_mfma_f32_16x16x32_bf16 v[122:125], v[142:145], v[166:169], v[122:125]
	v_mfma_f32_16x16x32_bf16 v[118:121], v[134:137], v[174:177], v[118:121]
	v_mfma_f32_16x16x32_bf16 v[114:117], v[142:145], v[174:177], v[114:117]
	v_mfma_f32_16x16x32_bf16 v[110:113], v[134:137], v[182:185], v[110:113]
	v_mfma_f32_16x16x32_bf16 v[106:109], v[142:145], v[182:185], v[106:109]
	v_mfma_f32_16x16x32_bf16 v[102:105], v[134:137], v[190:193], v[102:105]
	v_mfma_f32_16x16x32_bf16 v[98:101], v[142:145], v[190:193], v[98:101]
	v_mfma_f32_16x16x32_bf16 v[94:97], v[146:149], v[162:165], v[94:97]
	v_mfma_f32_16x16x32_bf16 v[90:93], v[154:157], v[162:165], v[90:93]
	v_mfma_f32_16x16x32_bf16 v[86:89], v[146:149], v[170:173], v[86:89]
	v_mfma_f32_16x16x32_bf16 v[82:85], v[154:157], v[170:173], v[82:85]
	v_mfma_f32_16x16x32_bf16 v[78:81], v[146:149], v[178:181], v[78:81]
	v_mfma_f32_16x16x32_bf16 v[74:77], v[154:157], v[178:181], v[74:77]
	v_mfma_f32_16x16x32_bf16 v[70:73], v[146:149], v[186:189], v[70:73]
	v_mfma_f32_16x16x32_bf16 v[66:69], v[154:157], v[186:189], v[66:69]
	v_mfma_f32_16x16x32_bf16 v[94:97], v[150:153], v[166:169], v[94:97]
	v_mfma_f32_16x16x32_bf16 v[90:93], v[158:161], v[166:169], v[90:93]
	v_mfma_f32_16x16x32_bf16 v[86:89], v[150:153], v[174:177], v[86:89]
	v_mfma_f32_16x16x32_bf16 v[82:85], v[158:161], v[174:177], v[82:85]
	v_mfma_f32_16x16x32_bf16 v[78:81], v[150:153], v[182:185], v[78:81]
	v_mfma_f32_16x16x32_bf16 v[74:77], v[158:161], v[182:185], v[74:77]
	v_mfma_f32_16x16x32_bf16 v[70:73], v[150:153], v[190:193], v[70:73]
	v_mfma_f32_16x16x32_bf16 v[66:69], v[158:161], v[190:193], v[66:69]
	s_barrier
	s_setprio 0
	s_mov_b32 m0, s92
	ds_read_b128 v[162:165], v231 offset:16384
	ds_read_b128 v[166:169], v231 offset:17408
	ds_read_b128 v[170:173], v231 offset:18432
	ds_read_b128 v[174:177], v231 offset:19456
	ds_read_b128 v[178:181], v231 offset:20480
	ds_read_b128 v[182:185], v231 offset:21504
	ds_read_b128 v[186:189], v231 offset:22528
	ds_read_b128 v[190:193], v231 offset:23552
	buffer_load_dwordx4 v227, s[16:19], s54 offen lds
	s_mov_b32 m0, s93
	s_add_i32 s55, s54, 0x20000
	buffer_load_dwordx4 v229, s[16:19], s54 offen lds
	s_mov_b32 m0, s94
	s_nop 0
	buffer_load_dwordx4 v227, s[16:19], s55 offen lds
	s_mov_b32 m0, s95
	s_nop 0
	buffer_load_dwordx4 v229, s[16:19], s55 offen lds
	s_waitcnt vmcnt(6)
	s_waitcnt lgkmcnt(0)
	s_setprio 1
	s_barrier
	v_mfma_f32_16x16x32_bf16 v[62:65], v[130:133], v[162:165], v[62:65]
	v_mfma_f32_16x16x32_bf16 v[58:61], v[138:141], v[162:165], v[58:61]
	v_mfma_f32_16x16x32_bf16 v[54:57], v[130:133], v[170:173], v[54:57]
	v_mfma_f32_16x16x32_bf16 v[50:53], v[138:141], v[170:173], v[50:53]
	v_mfma_f32_16x16x32_bf16 v[46:49], v[130:133], v[178:181], v[46:49]
	v_mfma_f32_16x16x32_bf16 v[42:45], v[138:141], v[178:181], v[42:45]
	v_mfma_f32_16x16x32_bf16 v[38:41], v[130:133], v[186:189], v[38:41]
	v_mfma_f32_16x16x32_bf16 v[34:37], v[138:141], v[186:189], v[34:37]
	v_mfma_f32_16x16x32_bf16 v[62:65], v[134:137], v[166:169], v[62:65]
	v_mfma_f32_16x16x32_bf16 v[58:61], v[142:145], v[166:169], v[58:61]
	v_mfma_f32_16x16x32_bf16 v[54:57], v[134:137], v[174:177], v[54:57]
	v_mfma_f32_16x16x32_bf16 v[50:53], v[142:145], v[174:177], v[50:53]
	v_mfma_f32_16x16x32_bf16 v[46:49], v[134:137], v[182:185], v[46:49]
	v_mfma_f32_16x16x32_bf16 v[42:45], v[142:145], v[182:185], v[42:45]
	v_mfma_f32_16x16x32_bf16 v[38:41], v[134:137], v[190:193], v[38:41]
	v_mfma_f32_16x16x32_bf16 v[34:37], v[142:145], v[190:193], v[34:37]
	v_mfma_f32_16x16x32_bf16 v[30:33], v[146:149], v[162:165], v[30:33]
	v_mfma_f32_16x16x32_bf16 v[26:29], v[154:157], v[162:165], v[26:29]
	v_mfma_f32_16x16x32_bf16 v[22:25], v[146:149], v[170:173], v[22:25]
	v_mfma_f32_16x16x32_bf16 v[18:21], v[154:157], v[170:173], v[18:21]
	v_mfma_f32_16x16x32_bf16 v[14:17], v[146:149], v[178:181], v[14:17]
	v_mfma_f32_16x16x32_bf16 v[10:13], v[154:157], v[178:181], v[10:13]
	v_mfma_f32_16x16x32_bf16 v[6:9], v[146:149], v[186:189], v[6:9]
	v_mfma_f32_16x16x32_bf16 v[2:5], v[154:157], v[186:189], v[2:5]
	v_mfma_f32_16x16x32_bf16 v[30:33], v[150:153], v[166:169], v[30:33]
	v_mfma_f32_16x16x32_bf16 v[26:29], v[158:161], v[166:169], v[26:29]
	v_mfma_f32_16x16x32_bf16 v[22:25], v[150:153], v[174:177], v[22:25]
	v_mfma_f32_16x16x32_bf16 v[18:21], v[158:161], v[174:177], v[18:21]
	v_mfma_f32_16x16x32_bf16 v[14:17], v[150:153], v[182:185], v[14:17]
	v_mfma_f32_16x16x32_bf16 v[10:13], v[158:161], v[182:185], v[10:13]
	v_mfma_f32_16x16x32_bf16 v[6:9], v[150:153], v[190:193], v[6:9]
	v_mfma_f32_16x16x32_bf16 v[2:5], v[158:161], v[190:193], v[2:5]
	s_barrier
	s_setprio 0
	s_mov_b32 m0, s44
	s_nop 0
	buffer_load_dwordx4 v199, s[12:15], s56 offen lds
	s_mov_b32 m0, s36
	s_nop 0
	buffer_load_dwordx4 v228, s[12:15], s56 offen lds
	v_add_u32_e32 v0, 0x18000, v230
	ds_read_b128 v[130:133], v0
	ds_read_b128 v[134:137], v0 offset:1024
	ds_read_b128 v[138:141], v0 offset:2048
	ds_read_b128 v[142:145], v0 offset:3072
	v_add_u32_e32 v0, 0x1c000, v230
	ds_read_b128 v[146:149], v0
	ds_read_b128 v[150:153], v0 offset:1024
	ds_read_b128 v[154:157], v0 offset:2048
	ds_read_b128 v[158:161], v0 offset:3072
	s_add_i32 s56, s56, 0x20000
	s_mov_b32 m0, s37
	ds_read_b128 v[162:165], v231 offset:32768
	ds_read_b128 v[166:169], v231 offset:33792
	ds_read_b128 v[170:173], v231 offset:34816
	ds_read_b128 v[174:177], v231 offset:35840
	ds_read_b128 v[178:181], v231 offset:36864
	ds_read_b128 v[182:185], v231 offset:37888
	ds_read_b128 v[186:189], v231 offset:38912
	ds_read_b128 v[190:193], v231 offset:39936
	buffer_load_dwordx4 v199, s[12:15], s56 offen lds
	s_mov_b32 m0, s38
	s_nop 0
	buffer_load_dwordx4 v228, s[12:15], s56 offen lds
	s_waitcnt vmcnt(8)
	s_waitcnt lgkmcnt(0)
	s_nop 0
	s_setprio 1
	s_barrier
	v_mfma_f32_16x16x32_bf16 v[126:129], v[130:133], v[162:165], v[126:129]
	v_mfma_f32_16x16x32_bf16 v[122:125], v[138:141], v[162:165], v[122:125]
	v_mfma_f32_16x16x32_bf16 v[118:121], v[130:133], v[170:173], v[118:121]
	v_mfma_f32_16x16x32_bf16 v[114:117], v[138:141], v[170:173], v[114:117]
	v_mfma_f32_16x16x32_bf16 v[110:113], v[130:133], v[178:181], v[110:113]
	v_mfma_f32_16x16x32_bf16 v[106:109], v[138:141], v[178:181], v[106:109]
	v_mfma_f32_16x16x32_bf16 v[102:105], v[130:133], v[186:189], v[102:105]
	v_mfma_f32_16x16x32_bf16 v[98:101], v[138:141], v[186:189], v[98:101]
	v_mfma_f32_16x16x32_bf16 v[126:129], v[134:137], v[166:169], v[126:129]
	v_mfma_f32_16x16x32_bf16 v[122:125], v[142:145], v[166:169], v[122:125]
	v_mfma_f32_16x16x32_bf16 v[118:121], v[134:137], v[174:177], v[118:121]
	v_mfma_f32_16x16x32_bf16 v[114:117], v[142:145], v[174:177], v[114:117]
	v_mfma_f32_16x16x32_bf16 v[110:113], v[134:137], v[182:185], v[110:113]
	v_mfma_f32_16x16x32_bf16 v[106:109], v[142:145], v[182:185], v[106:109]
	v_mfma_f32_16x16x32_bf16 v[102:105], v[134:137], v[190:193], v[102:105]
	v_mfma_f32_16x16x32_bf16 v[98:101], v[142:145], v[190:193], v[98:101]
	v_mfma_f32_16x16x32_bf16 v[94:97], v[146:149], v[162:165], v[94:97]
	v_mfma_f32_16x16x32_bf16 v[90:93], v[154:157], v[162:165], v[90:93]
	v_mfma_f32_16x16x32_bf16 v[86:89], v[146:149], v[170:173], v[86:89]
	v_mfma_f32_16x16x32_bf16 v[82:85], v[154:157], v[170:173], v[82:85]
	v_mfma_f32_16x16x32_bf16 v[78:81], v[146:149], v[178:181], v[78:81]
	v_mfma_f32_16x16x32_bf16 v[74:77], v[154:157], v[178:181], v[74:77]
	v_mfma_f32_16x16x32_bf16 v[70:73], v[146:149], v[186:189], v[70:73]
	v_mfma_f32_16x16x32_bf16 v[66:69], v[154:157], v[186:189], v[66:69]
	v_mfma_f32_16x16x32_bf16 v[94:97], v[150:153], v[166:169], v[94:97]
	v_mfma_f32_16x16x32_bf16 v[90:93], v[158:161], v[166:169], v[90:93]
	v_mfma_f32_16x16x32_bf16 v[86:89], v[150:153], v[174:177], v[86:89]
	v_mfma_f32_16x16x32_bf16 v[82:85], v[158:161], v[174:177], v[82:85]
	v_mfma_f32_16x16x32_bf16 v[78:81], v[150:153], v[182:185], v[78:81]
	v_mfma_f32_16x16x32_bf16 v[74:77], v[158:161], v[182:185], v[74:77]
	v_mfma_f32_16x16x32_bf16 v[70:73], v[150:153], v[190:193], v[70:73]
	v_mfma_f32_16x16x32_bf16 v[66:69], v[158:161], v[190:193], v[66:69]
	s_barrier
	s_setprio 0
	s_mov_b32 m0, s39
	ds_read_b128 v[162:165], v231 offset:49152
	ds_read_b128 v[166:169], v231 offset:50176
	ds_read_b128 v[170:173], v231 offset:51200
	ds_read_b128 v[174:177], v231 offset:52224
	ds_read_b128 v[178:181], v231 offset:53248
	ds_read_b128 v[182:185], v231 offset:54272
	ds_read_b128 v[186:189], v231 offset:55296
	ds_read_b128 v[190:193], v231 offset:56320
	buffer_load_dwordx4 v227, s[16:19], s57 offen lds
	s_mov_b32 m0, s40
	s_add_i32 s54, s54, 0x20080
	buffer_load_dwordx4 v229, s[16:19], s57 offen lds
	s_mov_b32 m0, s43
	s_nop 0
	buffer_load_dwordx4 v227, s[16:19], s54 offen lds
	s_mov_b32 m0, s42
	s_nop 0
	buffer_load_dwordx4 v229, s[16:19], s54 offen lds
	s_waitcnt vmcnt(6)
	s_waitcnt lgkmcnt(0)
	s_setprio 1
	s_barrier
	v_mfma_f32_16x16x32_bf16 v[62:65], v[130:133], v[162:165], v[62:65]
	v_mfma_f32_16x16x32_bf16 v[58:61], v[138:141], v[162:165], v[58:61]
	v_mfma_f32_16x16x32_bf16 v[54:57], v[130:133], v[170:173], v[54:57]
	v_mfma_f32_16x16x32_bf16 v[50:53], v[138:141], v[170:173], v[50:53]
	v_mfma_f32_16x16x32_bf16 v[46:49], v[130:133], v[178:181], v[46:49]
	v_mfma_f32_16x16x32_bf16 v[42:45], v[138:141], v[178:181], v[42:45]
	v_mfma_f32_16x16x32_bf16 v[38:41], v[130:133], v[186:189], v[38:41]
	v_mfma_f32_16x16x32_bf16 v[34:37], v[138:141], v[186:189], v[34:37]
	v_mfma_f32_16x16x32_bf16 v[62:65], v[134:137], v[166:169], v[62:65]
	v_mfma_f32_16x16x32_bf16 v[58:61], v[142:145], v[166:169], v[58:61]
	v_mfma_f32_16x16x32_bf16 v[54:57], v[134:137], v[174:177], v[54:57]
	v_mfma_f32_16x16x32_bf16 v[50:53], v[142:145], v[174:177], v[50:53]
	v_mfma_f32_16x16x32_bf16 v[46:49], v[134:137], v[182:185], v[46:49]
	v_mfma_f32_16x16x32_bf16 v[42:45], v[142:145], v[182:185], v[42:45]
	v_mfma_f32_16x16x32_bf16 v[38:41], v[134:137], v[190:193], v[38:41]
	v_mfma_f32_16x16x32_bf16 v[34:37], v[142:145], v[190:193], v[34:37]
	v_mfma_f32_16x16x32_bf16 v[30:33], v[146:149], v[162:165], v[30:33]
	v_mfma_f32_16x16x32_bf16 v[26:29], v[154:157], v[162:165], v[26:29]
	v_mfma_f32_16x16x32_bf16 v[22:25], v[146:149], v[170:173], v[22:25]
	v_mfma_f32_16x16x32_bf16 v[18:21], v[154:157], v[170:173], v[18:21]
	v_mfma_f32_16x16x32_bf16 v[14:17], v[146:149], v[178:181], v[14:17]
	v_mfma_f32_16x16x32_bf16 v[10:13], v[154:157], v[178:181], v[10:13]
	v_mfma_f32_16x16x32_bf16 v[6:9], v[146:149], v[186:189], v[6:9]
	v_mfma_f32_16x16x32_bf16 v[2:5], v[154:157], v[186:189], v[2:5]
	v_mfma_f32_16x16x32_bf16 v[30:33], v[150:153], v[166:169], v[30:33]
	v_mfma_f32_16x16x32_bf16 v[26:29], v[158:161], v[166:169], v[26:29]
	v_mfma_f32_16x16x32_bf16 v[22:25], v[150:153], v[174:177], v[22:25]
	v_mfma_f32_16x16x32_bf16 v[18:21], v[158:161], v[174:177], v[18:21]
	v_mfma_f32_16x16x32_bf16 v[14:17], v[150:153], v[182:185], v[14:17]
	v_mfma_f32_16x16x32_bf16 v[10:13], v[158:161], v[182:185], v[10:13]
	v_mfma_f32_16x16x32_bf16 v[6:9], v[150:153], v[190:193], v[6:9]
	v_mfma_f32_16x16x32_bf16 v[2:5], v[158:161], v[190:193], v[2:5]
	s_barrier
	s_setprio 0
	s_add_i32 s101, s20, 2
	s_cmp_gt_u32 s20, 5
	s_cbranch_scc1 .LBB0_1032
	s_mov_b32 s20, s101
	s_branch .LBB0_951

; template <class Epi, bool ALIGN_EPI, bool SP2, class Hook>
; __device__ __forceinline__ void gemm_phase(LAS unsigned char* lds, const Gemm g, const StaticOrder& S, const Epi& E, Acc& acc, const bool fresh, const Hook& H, const int wave_id) {
;     ...
;             const Src a1 = cA + (size_t)(t + 1) * kstep;
;             const Src a2 = last ? nA : cA + (size_t)(t + 2) * kstep, b2 = last ? nB : cB + (size_t)(t + 2) * kstep;
;             const Src a3 = a2 + kstep, b3 = b2 + kstep;
.LBB0_1235:
	s_add_i32 s100, s2, 0xfffc0000
	v_add_u32_e32 v142, 0x10000, v161
	v_add_u32_e32 v163, 0x14000, v161
	ds_read_b128 v[130:133], v142
	ds_read_b128 v[134:137], v142 offset:1024
	ds_read_b128 v[138:141], v142 offset:2048
	ds_read_b128 v[142:145], v142 offset:3072
	ds_read_b128 v[146:149], v163
	ds_read_b128 v[150:153], v163 offset:1024
	ds_read_b128 v[154:157], v163 offset:2048
	ds_read_b128 v[164:167], v163 offset:3072
	s_mov_b32 m0, s41
	s_nop 0
	buffer_load_dwordx4 v0, s[12:15], s100 offen lds
	s_mov_b32 m0, s33
	s_nop 0
	buffer_load_dwordx4 v159, s[12:15], s100 offen lds
	s_mov_b32 m0, s45
	ds_read_b128 v[168:171], v162
	ds_read_b128 v[172:175], v162 offset:1024
	ds_read_b128 v[176:179], v162 offset:2048
	ds_read_b128 v[180:183], v162 offset:3072
	ds_read_b128 v[184:187], v162 offset:4096
	ds_read_b128 v[188:191], v162 offset:5120
	ds_read_b128 v[192:195], v162 offset:6144
	ds_read_b128 v[200:203], v162 offset:7168
	buffer_load_dwordx4 v0, s[12:15], s2 offen lds
	s_mov_b32 m0, s46
	s_nop 0
	buffer_load_dwordx4 v159, s[12:15], s2 offen lds
	s_waitcnt vmcnt(8)
	s_waitcnt lgkmcnt(0)
	s_nop 0
	s_setprio 1
	s_barrier
	v_mfma_f32_16x16x32_bf16 v[126:129], v[130:133], v[168:171], v[126:129]
	v_mfma_f32_16x16x32_bf16 v[122:125], v[138:141], v[168:171], v[122:125]
	v_mfma_f32_16x16x32_bf16 v[110:113], v[130:133], v[176:179], v[110:113]
	v_mfma_f32_16x16x32_bf16 v[106:109], v[138:141], v[176:179], v[106:109]
	v_mfma_f32_16x16x32_bf16 v[94:97], v[130:133], v[184:187], v[94:97]
	v_mfma_f32_16x16x32_bf16 v[90:93], v[138:141], v[184:187], v[90:93]
	v_mfma_f32_16x16x32_bf16 v[78:81], v[130:133], v[192:195], v[78:81]
	v_mfma_f32_16x16x32_bf16 v[74:77], v[138:141], v[192:195], v[74:77]
	v_mfma_f32_16x16x32_bf16 v[126:129], v[134:137], v[172:175], v[126:129]
	v_mfma_f32_16x16x32_bf16 v[122:125], v[142:145], v[172:175], v[122:125]
	v_mfma_f32_16x16x32_bf16 v[110:113], v[134:137], v[180:183], v[110:113]
	v_mfma_f32_16x16x32_bf16 v[106:109], v[142:145], v[180:183], v[106:109]
	v_mfma_f32_16x16x32_bf16 v[94:97], v[134:137], v[188:191], v[94:97]
	v_mfma_f32_16x16x32_bf16 v[90:93], v[142:145], v[188:191], v[90:93]
	v_mfma_f32_16x16x32_bf16 v[78:81], v[134:137], v[200:203], v[78:81]
	v_mfma_f32_16x16x32_bf16 v[74:77], v[142:145], v[200:203], v[74:77]
	v_mfma_f32_16x16x32_bf16 v[118:121], v[146:149], v[168:171], v[118:121]
	v_mfma_f32_16x16x32_bf16 v[114:117], v[154:157], v[168:171], v[114:117]
	v_mfma_f32_16x16x32_bf16 v[102:105], v[146:149], v[176:179], v[102:105]
	v_mfma_f32_16x16x32_bf16 v[98:101], v[154:157], v[176:179], v[98:101]
	v_mfma_f32_16x16x32_bf16 v[86:89], v[146:149], v[184:187], v[86:89]
	v_mfma_f32_16x16x32_bf16 v[82:85], v[154:157], v[184:187], v[82:85]
	v_mfma_f32_16x16x32_bf16 v[70:73], v[146:149], v[192:195], v[70:73]
	v_mfma_f32_16x16x32_bf16 v[66:69], v[154:157], v[192:195], v[66:69]
	v_mfma_f32_16x16x32_bf16 v[118:121], v[150:153], v[172:175], v[118:121]
	v_mfma_f32_16x16x32_bf16 v[114:117], v[164:167], v[172:175], v[114:117]
	v_mfma_f32_16x16x32_bf16 v[102:105], v[150:153], v[180:183], v[102:105]
	v_mfma_f32_16x16x32_bf16 v[98:101], v[164:167], v[180:183], v[98:101]
	v_mfma_f32_16x16x32_bf16 v[86:89], v[150:153], v[188:191], v[86:89]
	v_mfma_f32_16x16x32_bf16 v[82:85], v[164:167], v[188:191], v[82:85]
	v_mfma_f32_16x16x32_bf16 v[70:73], v[150:153], v[200:203], v[70:73]
	v_mfma_f32_16x16x32_bf16 v[66:69], v[164:167], v[200:203], v[66:69]
	s_barrier
	s_setprio 0
	s_add_i32 s16, s2, 0xfffc0080
	s_cmp_eq_u32 s59, 12
	s_cselect_b32 s62, s55, s16
	s_cselect_b32 s17, s31, s9
	s_cselect_b32 s16, s30, s8
	s_cselect_b32 s19, s35, s51
	s_cselect_b32 s18, s34, s50
	s_cselect_b32 s60, s56, s3
	s_cselect_b32 s20, s26, s12
	s_cselect_b32 s21, s27, s13
	s_cselect_b32 s22, s28, s14
	s_cselect_b32 s23, s29, s15
	s_or_b32 s61, s62, 0x80
	s_mov_b32 m0, s92
	ds_read_b128 v[168:171], v162 offset:16384
	ds_read_b128 v[172:175], v162 offset:17408
	ds_read_b128 v[176:179], v162 offset:18432
	ds_read_b128 v[180:183], v162 offset:19456
	ds_read_b128 v[184:187], v162 offset:20480
	ds_read_b128 v[188:191], v162 offset:21504
	ds_read_b128 v[192:195], v162 offset:22528
	ds_read_b128 v[200:203], v162 offset:23552
	buffer_load_dwordx4 v158, s[16:19], s60 offen lds
	s_mov_b32 m0, s93
	s_add_i32 s63, s60, 0x40000
	buffer_load_dwordx4 v160, s[16:19], s60 offen lds
	s_mov_b32 m0, s94
	s_nop 0
	buffer_load_dwordx4 v158, s[16:19], s63 offen lds
	s_mov_b32 m0, s95
	s_nop 0
	buffer_load_dwordx4 v160, s[16:19], s63 offen lds
	s_waitcnt vmcnt(6)
	s_waitcnt lgkmcnt(0)
	s_nop 0
	s_setprio 1
	s_barrier
	v_mfma_f32_16x16x32_bf16 v[62:65], v[130:133], v[168:171], v[62:65]
	v_mfma_f32_16x16x32_bf16 v[58:61], v[138:141], v[168:171], v[58:61]
	v_mfma_f32_16x16x32_bf16 v[46:49], v[130:133], v[176:179], v[46:49]
	v_mfma_f32_16x16x32_bf16 v[42:45], v[138:141], v[176:179], v[42:45]
	v_mfma_f32_16x16x32_bf16 v[30:33], v[130:133], v[184:187], v[30:33]
	v_mfma_f32_16x16x32_bf16 v[26:29], v[138:141], v[184:187], v[26:29]
	v_mfma_f32_16x16x32_bf16 v[14:17], v[130:133], v[192:195], v[14:17]
	v_mfma_f32_16x16x32_bf16 v[10:13], v[138:141], v[192:195], v[10:13]
	v_mfma_f32_16x16x32_bf16 v[62:65], v[134:137], v[172:175], v[62:65]
	v_mfma_f32_16x16x32_bf16 v[58:61], v[142:145], v[172:175], v[58:61]
	v_mfma_f32_16x16x32_bf16 v[46:49], v[134:137], v[180:183], v[46:49]
	v_mfma_f32_16x16x32_bf16 v[42:45], v[142:145], v[180:183], v[42:45]
	v_mfma_f32_16x16x32_bf16 v[30:33], v[134:137], v[188:191], v[30:33]
	v_mfma_f32_16x16x32_bf16 v[26:29], v[142:145], v[188:191], v[26:29]
	v_mfma_f32_16x16x32_bf16 v[14:17], v[134:137], v[200:203], v[14:17]
	v_mfma_f32_16x16x32_bf16 v[10:13], v[142:145], v[200:203], v[10:13]
	v_mfma_f32_16x16x32_bf16 v[54:57], v[146:149], v[168:171], v[54:57]
	v_mfma_f32_16x16x32_bf16 v[50:53], v[154:157], v[168:171], v[50:53]
	v_mfma_f32_16x16x32_bf16 v[38:41], v[146:149], v[176:179], v[38:41]
	v_mfma_f32_16x16x32_bf16 v[34:37], v[154:157], v[176:179], v[34:37]
	v_mfma_f32_16x16x32_bf16 v[22:25], v[146:149], v[184:187], v[22:25]
	v_mfma_f32_16x16x32_bf16 v[18:21], v[154:157], v[184:187], v[18:21]
	v_mfma_f32_16x16x32_bf16 v[6:9], v[146:149], v[192:195], v[6:9]
	v_mfma_f32_16x16x32_bf16 v[2:5], v[154:157], v[192:195], v[2:5]
	v_mfma_f32_16x16x32_bf16 v[54:57], v[150:153], v[172:175], v[54:57]
	v_mfma_f32_16x16x32_bf16 v[50:53], v[164:167], v[172:175], v[50:53]
	v_mfma_f32_16x16x32_bf16 v[38:41], v[150:153], v[180:183], v[38:41]
	v_mfma_f32_16x16x32_bf16 v[34:37], v[164:167], v[180:183], v[34:37]
	v_mfma_f32_16x16x32_bf16 v[22:25], v[150:153], v[188:191], v[22:25]
	v_mfma_f32_16x16x32_bf16 v[18:21], v[164:167], v[188:191], v[18:21]
	v_mfma_f32_16x16x32_bf16 v[6:9], v[150:153], v[200:203], v[6:9]
	v_mfma_f32_16x16x32_bf16 v[2:5], v[164:167], v[200:203], v[2:5]
	s_barrier
	s_setprio 0
	s_mov_b32 m0, s44
	s_nop 0
	buffer_load_dwordx4 v0, s[20:23], s62 offen lds
	s_mov_b32 m0, s36
	s_nop 0
	buffer_load_dwordx4 v159, s[20:23], s62 offen lds
	v_add_u32_e32 v142, 0x18000, v161
	v_add_u32_e32 v163, 0x1c000, v161
	ds_read_b128 v[130:133], v142
	ds_read_b128 v[134:137], v142 offset:1024
	ds_read_b128 v[138:141], v142 offset:2048
	ds_read_b128 v[142:145], v142 offset:3072
	ds_read_b128 v[146:149], v163
	ds_read_b128 v[150:153], v163 offset:1024
	ds_read_b128 v[154:157], v163 offset:2048
	ds_read_b128 v[164:167], v163 offset:3072
	s_add_i32 s62, s62, 0x40000
	s_mov_b32 m0, s37
	ds_read_b128 v[168:171], v162 offset:32768
	ds_read_b128 v[172:175], v162 offset:33792
	ds_read_b128 v[176:179], v162 offset:34816
	ds_read_b128 v[180:183], v162 offset:35840
	ds_read_b128 v[184:187], v162 offset:36864
	ds_read_b128 v[188:191], v162 offset:37888
	ds_read_b128 v[192:195], v162 offset:38912
	ds_read_b128 v[200:203], v162 offset:39936
	buffer_load_dwordx4 v0, s[20:23], s62 offen lds
	s_mov_b32 m0, s38
	s_nop 0
	buffer_load_dwordx4 v159, s[20:23], s62 offen lds
	s_waitcnt vmcnt(8)
	s_waitcnt lgkmcnt(0)
	s_nop 0
	s_setprio 1
	s_barrier
	v_mfma_f32_16x16x32_bf16 v[126:129], v[130:133], v[168:171], v[126:129]
	v_mfma_f32_16x16x32_bf16 v[122:125], v[138:141], v[168:171], v[122:125]
	v_mfma_f32_16x16x32_bf16 v[110:113], v[130:133], v[176:179], v[110:113]
	v_mfma_f32_16x16x32_bf16 v[106:109], v[138:141], v[176:179], v[106:109]
	v_mfma_f32_16x16x32_bf16 v[94:97], v[130:133], v[184:187], v[94:97]
	v_mfma_f32_16x16x32_bf16 v[90:93], v[138:141], v[184:187], v[90:93]
	v_mfma_f32_16x16x32_bf16 v[78:81], v[130:133], v[192:195], v[78:81]
	v_mfma_f32_16x16x32_bf16 v[74:77], v[138:141], v[192:195], v[74:77]
	v_mfma_f32_16x16x32_bf16 v[126:129], v[134:137], v[172:175], v[126:129]
	v_mfma_f32_16x16x32_bf16 v[122:125], v[142:145], v[172:175], v[122:125]
	v_mfma_f32_16x16x32_bf16 v[110:113], v[134:137], v[180:183], v[110:113]
	v_mfma_f32_16x16x32_bf16 v[106:109], v[142:145], v[180:183], v[106:109]
	v_mfma_f32_16x16x32_bf16 v[94:97], v[134:137], v[188:191], v[94:97]
	v_mfma_f32_16x16x32_bf16 v[90:93], v[142:145], v[188:191], v[90:93]
	v_mfma_f32_16x16x32_bf16 v[78:81], v[134:137], v[200:203], v[78:81]
	v_mfma_f32_16x16x32_bf16 v[74:77], v[142:145], v[200:203], v[74:77]
	v_mfma_f32_16x16x32_bf16 v[118:121], v[146:149], v[168:171], v[118:121]
	v_mfma_f32_16x16x32_bf16 v[114:117], v[154:157], v[168:171], v[114:117]
	v_mfma_f32_16x16x32_bf16 v[102:105], v[146:149], v[176:179], v[102:105]
	v_mfma_f32_16x16x32_bf16 v[98:101], v[154:157], v[176:179], v[98:101]
	v_mfma_f32_16x16x32_bf16 v[86:89], v[146:149], v[184:187], v[86:89]
	v_mfma_f32_16x16x32_bf16 v[82:85], v[154:157], v[184:187], v[82:85]
	v_mfma_f32_16x16x32_bf16 v[70:73], v[146:149], v[192:195], v[70:73]
	v_mfma_f32_16x16x32_bf16 v[66:69], v[154:157], v[192:195], v[66:69]
	v_mfma_f32_16x16x32_bf16 v[118:121], v[150:153], v[172:175], v[118:121]
	v_mfma_f32_16x16x32_bf16 v[114:117], v[164:167], v[172:175], v[114:117]
	v_mfma_f32_16x16x32_bf16 v[102:105], v[150:153], v[180:183], v[102:105]
	v_mfma_f32_16x16x32_bf16 v[98:101], v[164:167], v[180:183], v[98:101]
	v_mfma_f32_16x16x32_bf16 v[86:89], v[150:153], v[188:191], v[86:89]
	v_mfma_f32_16x16x32_bf16 v[82:85], v[164:167], v[188:191], v[82:85]
	v_mfma_f32_16x16x32_bf16 v[70:73], v[150:153], v[200:203], v[70:73]
	v_mfma_f32_16x16x32_bf16 v[66:69], v[164:167], v[200:203], v[66:69]
	s_barrier
	s_setprio 0
	s_mov_b32 m0, s39
	s_or_b32 s62, s60, 0x80
	ds_read_b128 v[168:171], v162 offset:49152
	ds_read_b128 v[172:175], v162 offset:50176
	ds_read_b128 v[176:179], v162 offset:51200
	ds_read_b128 v[180:183], v162 offset:52224
	ds_read_b128 v[184:187], v162 offset:53248
	ds_read_b128 v[188:191], v162 offset:54272
	ds_read_b128 v[192:195], v162 offset:55296
	ds_read_b128 v[200:203], v162 offset:56320
	buffer_load_dwordx4 v158, s[16:19], s62 offen lds
	s_mov_b32 m0, s40
	s_add_i32 s60, s60, 0x40080
	buffer_load_dwordx4 v160, s[16:19], s62 offen lds
	s_mov_b32 m0, s43
	s_nop 0
	buffer_load_dwordx4 v158, s[16:19], s60 offen lds
	s_mov_b32 m0, s42
	s_nop 0
	buffer_load_dwordx4 v160, s[16:19], s60 offen lds
	s_add_i32 s59, s59, 2
	s_addk_i32 s2, 0x100
	s_addk_i32 s3, 0x100
	s_cmp_gt_u32 s59, 13
	s_waitcnt vmcnt(6)
	s_waitcnt lgkmcnt(0)
	s_setprio 1
	s_barrier
	v_mfma_f32_16x16x32_bf16 v[62:65], v[130:133], v[168:171], v[62:65]
	v_mfma_f32_16x16x32_bf16 v[58:61], v[138:141], v[168:171], v[58:61]
	v_mfma_f32_16x16x32_bf16 v[46:49], v[130:133], v[176:179], v[46:49]
	v_mfma_f32_16x16x32_bf16 v[42:45], v[138:141], v[176:179], v[42:45]
	v_mfma_f32_16x16x32_bf16 v[30:33], v[130:133], v[184:187], v[30:33]
	v_mfma_f32_16x16x32_bf16 v[26:29], v[138:141], v[184:187], v[26:29]
	v_mfma_f32_16x16x32_bf16 v[14:17], v[130:133], v[192:195], v[14:17]
	v_mfma_f32_16x16x32_bf16 v[10:13], v[138:141], v[192:195], v[10:13]
	v_mfma_f32_16x16x32_bf16 v[62:65], v[134:137], v[172:175], v[62:65]
	v_mfma_f32_16x16x32_bf16 v[58:61], v[142:145], v[172:175], v[58:61]
	v_mfma_f32_16x16x32_bf16 v[46:49], v[134:137], v[180:183], v[46:49]
	v_mfma_f32_16x16x32_bf16 v[42:45], v[142:145], v[180:183], v[42:45]
	v_mfma_f32_16x16x32_bf16 v[30:33], v[134:137], v[188:191], v[30:33]
	v_mfma_f32_16x16x32_bf16 v[26:29], v[142:145], v[188:191], v[26:29]
	v_mfma_f32_16x16x32_bf16 v[14:17], v[134:137], v[200:203], v[14:17]
	v_mfma_f32_16x16x32_bf16 v[10:13], v[142:145], v[200:203], v[10:13]
	v_mfma_f32_16x16x32_bf16 v[54:57], v[146:149], v[168:171], v[54:57]
	v_mfma_f32_16x16x32_bf16 v[50:53], v[154:157], v[168:171], v[50:53]
	v_mfma_f32_16x16x32_bf16 v[38:41], v[146:149], v[176:179], v[38:41]
	v_mfma_f32_16x16x32_bf16 v[34:37], v[154:157], v[176:179], v[34:37]
	v_mfma_f32_16x16x32_bf16 v[22:25], v[146:149], v[184:187], v[22:25]
	v_mfma_f32_16x16x32_bf16 v[18:21], v[154:157], v[184:187], v[18:21]
	v_mfma_f32_16x16x32_bf16 v[6:9], v[146:149], v[192:195], v[6:9]
	v_mfma_f32_16x16x32_bf16 v[2:5], v[154:157], v[192:195], v[2:5]
	v_mfma_f32_16x16x32_bf16 v[54:57], v[150:153], v[172:175], v[54:57]
	v_mfma_f32_16x16x32_bf16 v[50:53], v[164:167], v[172:175], v[50:53]
	v_mfma_f32_16x16x32_bf16 v[38:41], v[150:153], v[180:183], v[38:41]
	v_mfma_f32_16x16x32_bf16 v[34:37], v[164:167], v[180:183], v[34:37]
	v_mfma_f32_16x16x32_bf16 v[22:25], v[150:153], v[188:191], v[22:25]
	v_mfma_f32_16x16x32_bf16 v[18:21], v[164:167], v[188:191], v[18:21]
	v_mfma_f32_16x16x32_bf16 v[6:9], v[150:153], v[200:203], v[6:9]
	v_mfma_f32_16x16x32_bf16 v[2:5], v[164:167], v[200:203], v[2:5]
	s_barrier
	s_setprio 0
	s_cbranch_scc0 .LBB0_1235
	s_mov_b32 m0, s41
	s_nop 0
	buffer_load_dwordx4 v0, s[20:23], s61 offen lds
	s_mov_b32 m0, s33
	s_nop 0
	buffer_load_dwordx4 v159, s[20:23], s61 offen lds
	v_readlane_b32 s2, v251, 45
	v_readlane_b32 s3, v251, 46
	s_and_b64 vcc, exec, s[2:3]
	s_cbranch_vccz .LBB0_1238
	s_barrier

; #define PG8_WAIT_V(n) asm volatile("s_waitcnt vmcnt(" #n ")" ::: "memory")
; template <class Epi, bool ALIGN_EPI, bool SP2, class Hook>
; __device__ __forceinline__ void gemm_phase(LAS unsigned char* lds, const Gemm g, const StaticOrder& S, const Epi& E, Acc& acc, const bool fresh, const Hook& H, const int wave_id) {
;     ...
;         if constexpr (SP2 && Epi::NSTORE > 0) {
;             const Src a1 = cA + kstep, a2 = cA + 2 * kstep, b2 = cB + 2 * kstep, a3 = a2 + kstep, b3 = b2 + kstep;
;             if constexpr (Epi::NSTORE == 16) PG8_TRIP_SP2(PG8_WAIT_V(24)); else PG8_TRIP_SP2(PG8_WAIT_V(16));
;             t0 = 2;
.LBB0_1452:
	ds_read_b128 v[2:5], v138
	ds_read_b128 v[6:9], v138 offset:1024
	ds_read_b128 v[10:13], v138 offset:2048
	ds_read_b128 v[14:17], v138 offset:3072
	ds_read_b128 v[18:21], v139
	ds_read_b128 v[22:25], v139 offset:1024
	ds_read_b128 v[26:29], v139 offset:2048
	ds_read_b128 v[30:33], v139 offset:3072
	s_or_b32 s3, s50, 0x100
	s_or_b32 s2, s50, 0x180
	s_or_b32 s12, s51, 0x100
	s_or_b32 s13, s50, 0x40080
	s_mov_b32 m0, s45
	ds_read_b128 v[34:37], v137
	ds_read_b128 v[38:41], v137 offset:1024
	ds_read_b128 v[42:45], v137 offset:2048
	ds_read_b128 v[46:49], v137 offset:3072
	ds_read_b128 v[50:53], v137 offset:4096
	ds_read_b128 v[54:57], v137 offset:5120
	ds_read_b128 v[58:61], v137 offset:6144
	ds_read_b128 v[62:65], v137 offset:7168
	buffer_load_dwordx4 v132, s[4:7], s13 offen lds
	s_mov_b32 m0, s46
	s_nop 0
	buffer_load_dwordx4 v134, s[4:7], s13 offen lds
	s_waitcnt vmcnt(16)
	s_waitcnt lgkmcnt(0)
	s_setprio 1
	s_barrier
	v_mfma_f32_16x16x32_bf16 v[90:93], v[2:5], v[58:61], 0
	v_mfma_f32_16x16x32_bf16 v[66:69], v[2:5], v[34:37], 0
	v_mfma_f32_16x16x32_bf16 v[70:73], v[10:13], v[34:37], 0
	v_mfma_f32_16x16x32_bf16 v[74:77], v[2:5], v[42:45], 0
	v_mfma_f32_16x16x32_bf16 v[78:81], v[10:13], v[42:45], 0
	v_mfma_f32_16x16x32_bf16 v[82:85], v[2:5], v[50:53], 0
	v_mfma_f32_16x16x32_bf16 v[86:89], v[10:13], v[50:53], 0
	v_mfma_f32_16x16x32_bf16 v[96:99], v[6:9], v[62:65], v[90:93]
	v_mfma_f32_16x16x32_bf16 v[90:93], v[10:13], v[58:61], 0
	v_mfma_f32_16x16x32_bf16 v[66:69], v[6:9], v[38:41], v[66:69]
	v_mfma_f32_16x16x32_bf16 v[70:73], v[14:17], v[38:41], v[70:73]
	v_mfma_f32_16x16x32_bf16 v[74:77], v[6:9], v[46:49], v[74:77]
	v_mfma_f32_16x16x32_bf16 v[78:81], v[14:17], v[46:49], v[78:81]
	v_mfma_f32_16x16x32_bf16 v[82:85], v[6:9], v[54:57], v[82:85]
	v_mfma_f32_16x16x32_bf16 v[86:89], v[14:17], v[54:57], v[86:89]
	v_mfma_f32_16x16x32_bf16 v[104:107], v[14:17], v[62:65], v[90:93]
	v_mfma_f32_16x16x32_bf16 v[90:93], v[18:21], v[34:37], 0
	v_mfma_f32_16x16x32_bf16 v[34:37], v[26:29], v[34:37], 0
	v_mfma_f32_16x16x32_bf16 v[112:115], v[22:25], v[38:41], v[90:93]
	v_mfma_f32_16x16x32_bf16 v[34:37], v[30:33], v[38:41], v[34:37]
	v_mfma_f32_16x16x32_bf16 v[38:41], v[18:21], v[42:45], 0
	v_mfma_f32_16x16x32_bf16 v[42:45], v[26:29], v[42:45], 0
	v_mfma_f32_16x16x32_bf16 v[38:41], v[22:25], v[46:49], v[38:41]
	v_mfma_f32_16x16x32_bf16 v[42:45], v[30:33], v[46:49], v[42:45]
	v_mfma_f32_16x16x32_bf16 v[46:49], v[18:21], v[50:53], 0
	v_mfma_f32_16x16x32_bf16 v[50:53], v[26:29], v[50:53], 0
	v_mfma_f32_16x16x32_bf16 v[46:49], v[22:25], v[54:57], v[46:49]
	v_mfma_f32_16x16x32_bf16 v[50:53], v[30:33], v[54:57], v[50:53]
	v_mfma_f32_16x16x32_bf16 v[54:57], v[18:21], v[58:61], 0
	v_mfma_f32_16x16x32_bf16 v[58:61], v[26:29], v[58:61], 0
	v_mfma_f32_16x16x32_bf16 v[54:57], v[22:25], v[62:65], v[54:57]
	v_mfma_f32_16x16x32_bf16 v[58:61], v[30:33], v[62:65], v[58:61]
	s_barrier
	s_setprio 0
	s_mov_b32 m0, s92
	ds_read_b128 v[62:65], v137 offset:16384
	ds_read_b128 v[90:93], v137 offset:17408
	ds_read_b128 v[100:103], v137 offset:18432
	ds_read_b128 v[108:111], v137 offset:19456
	ds_read_b128 v[116:119], v137 offset:20480
	ds_read_b128 v[120:123], v137 offset:21504
	ds_read_b128 v[124:127], v137 offset:22528
	ds_read_b128 v[128:131], v137 offset:23552
	buffer_load_dwordx4 v133, s[8:11], s12 offen lds
	s_mov_b32 m0, s93
	s_nop 0
	buffer_load_dwordx4 v135, s[8:11], s12 offen lds
	s_or_b32 s12, s51, 0x40100
	s_mov_b32 m0, s94
	s_nop 0
	buffer_load_dwordx4 v133, s[8:11], s12 offen lds
	s_mov_b32 m0, s95
	s_nop 0
	buffer_load_dwordx4 v135, s[8:11], s12 offen lds
	s_waitcnt vmcnt(14)
	s_waitcnt lgkmcnt(0)
	s_nop 0
	s_setprio 1
	s_barrier
	v_mfma_f32_16x16x32_bf16 v[142:145], v[2:5], v[62:65], 0
	v_mfma_f32_16x16x32_bf16 v[150:153], v[2:5], v[100:103], 0
	v_mfma_f32_16x16x32_bf16 v[158:161], v[2:5], v[116:119], 0
	v_mfma_f32_16x16x32_bf16 v[2:5], v[2:5], v[124:127], 0
	v_mfma_f32_16x16x32_bf16 v[142:145], v[6:9], v[90:93], v[142:145]
	v_mfma_f32_16x16x32_bf16 v[150:153], v[6:9], v[108:111], v[150:153]
	v_mfma_f32_16x16x32_bf16 v[158:161], v[6:9], v[120:123], v[158:161]
	v_mfma_f32_16x16x32_bf16 v[2:5], v[6:9], v[128:131], v[2:5]
	v_mfma_f32_16x16x32_bf16 v[6:9], v[10:13], v[124:127], 0
	v_mfma_f32_16x16x32_bf16 v[146:149], v[10:13], v[62:65], 0
	v_mfma_f32_16x16x32_bf16 v[154:157], v[10:13], v[100:103], 0
	v_mfma_f32_16x16x32_bf16 v[162:165], v[10:13], v[116:119], 0
	v_mfma_f32_16x16x32_bf16 v[6:9], v[14:17], v[128:131], v[6:9]
	v_mfma_f32_16x16x32_bf16 v[146:149], v[14:17], v[90:93], v[146:149]
	v_mfma_f32_16x16x32_bf16 v[154:157], v[14:17], v[108:111], v[154:157]
	v_mfma_f32_16x16x32_bf16 v[162:165], v[14:17], v[120:123], v[162:165]
	v_mfma_f32_16x16x32_bf16 v[10:13], v[18:21], v[62:65], 0
	v_mfma_f32_16x16x32_bf16 v[166:169], v[22:25], v[90:93], v[10:13]
	v_mfma_f32_16x16x32_bf16 v[10:13], v[26:29], v[62:65], 0
	v_mfma_f32_16x16x32_bf16 v[170:173], v[30:33], v[90:93], v[10:13]
	v_mfma_f32_16x16x32_bf16 v[10:13], v[18:21], v[100:103], 0
	v_mfma_f32_16x16x32_bf16 v[174:177], v[22:25], v[108:111], v[10:13]
	v_mfma_f32_16x16x32_bf16 v[10:13], v[26:29], v[100:103], 0
	v_mfma_f32_16x16x32_bf16 v[178:181], v[30:33], v[108:111], v[10:13]
	v_mfma_f32_16x16x32_bf16 v[10:13], v[18:21], v[116:119], 0
	v_mfma_f32_16x16x32_bf16 v[182:185], v[22:25], v[120:123], v[10:13]
	v_mfma_f32_16x16x32_bf16 v[10:13], v[26:29], v[116:119], 0
	v_mfma_f32_16x16x32_bf16 v[186:189], v[30:33], v[120:123], v[10:13]
	v_mfma_f32_16x16x32_bf16 v[10:13], v[18:21], v[124:127], 0
	v_mfma_f32_16x16x32_bf16 v[16:19], v[22:25], v[128:131], v[10:13]
	v_mfma_f32_16x16x32_bf16 v[10:13], v[26:29], v[124:127], 0
	v_mfma_f32_16x16x32_bf16 v[190:193], v[30:33], v[128:131], v[10:13]
	s_barrier
; #define PG8_WAIT_V(n) asm volatile("s_waitcnt vmcnt(" #n ")" ::: "memory")
; template <class Epi, bool ALIGN_EPI, bool SP2, class Hook>
; __device__ __forceinline__ void gemm_phase(LAS unsigned char* lds, const Gemm g, const StaticOrder& S, const Epi& E, Acc& acc, const bool fresh, const Hook& H, const int wave_id) {
;     ...
;         if constexpr (SP2 && Epi::NSTORE > 0) {
;             const Src a1 = cA + kstep, a2 = cA + 2 * kstep, b2 = cB + 2 * kstep, a3 = a2 + kstep, b3 = b2 + kstep;
;             if constexpr (Epi::NSTORE == 16) PG8_TRIP_SP2(PG8_WAIT_V(24)); else PG8_TRIP_SP2(PG8_WAIT_V(16));
;             t0 = 2;
	s_setprio 0
	s_mov_b32 m0, s44
	s_nop 0
	buffer_load_dwordx4 v132, s[4:7], s3 offen lds
	s_mov_b32 m0, s36
	s_nop 0
	buffer_load_dwordx4 v134, s[4:7], s3 offen lds
	s_nop 4
	ds_read_b128 v[10:13], v140
	ds_read_b128 v[24:27], v140 offset:1024
	ds_read_b128 v[194:197], v140 offset:2048
	ds_read_b128 v[200:203], v140 offset:3072
	ds_read_b128 v[204:207], v141
	ds_read_b128 v[208:211], v141 offset:1024
	ds_read_b128 v[212:215], v141 offset:2048
	ds_read_b128 v[138:141], v141 offset:3072
	s_or_b32 s3, s50, 0x40100
	s_mov_b32 m0, s37
	ds_read_b128 v[20:23], v137 offset:32768
	ds_read_b128 v[28:31], v137 offset:33792
	ds_read_b128 v[216:219], v137 offset:34816
	ds_read_b128 v[220:223], v137 offset:35840
	ds_read_b128 v[228:231], v137 offset:36864
	ds_read_b128 v[232:235], v137 offset:37888
	ds_read_b128 v[236:239], v137 offset:38912
	ds_read_b128 v[240:243], v137 offset:39936
	buffer_load_dwordx4 v132, s[4:7], s3 offen lds
	s_mov_b32 m0, s38
	s_nop 0
	buffer_load_dwordx4 v134, s[4:7], s3 offen lds
	s_waitcnt vmcnt(8)
	s_waitcnt lgkmcnt(0)
	s_setprio 1
	s_barrier
	v_mfma_f32_16x16x32_bf16 v[62:65], v[10:13], v[20:23], v[66:69]
	v_mfma_f32_16x16x32_bf16 v[124:127], v[24:27], v[28:31], v[62:65]
	v_mfma_f32_16x16x32_bf16 v[62:65], v[194:197], v[20:23], v[70:73]
	v_mfma_f32_16x16x32_bf16 v[116:119], v[200:203], v[28:31], v[62:65]
	v_mfma_f32_16x16x32_bf16 v[62:65], v[10:13], v[216:219], v[74:77]
	v_mfma_f32_16x16x32_bf16 v[108:111], v[24:27], v[220:223], v[62:65]
	v_mfma_f32_16x16x32_bf16 v[62:65], v[194:197], v[216:219], v[78:81]
	v_mfma_f32_16x16x32_bf16 v[100:103], v[200:203], v[220:223], v[62:65]
	v_mfma_f32_16x16x32_bf16 v[62:65], v[10:13], v[228:231], v[82:85]
	v_mfma_f32_16x16x32_bf16 v[92:95], v[24:27], v[232:235], v[62:65]
	v_mfma_f32_16x16x32_bf16 v[62:65], v[194:197], v[228:231], v[86:89]
	v_mfma_f32_16x16x32_bf16 v[84:87], v[200:203], v[232:235], v[62:65]
	v_mfma_f32_16x16x32_bf16 v[62:65], v[10:13], v[236:239], v[96:99]
	v_mfma_f32_16x16x32_bf16 v[76:79], v[24:27], v[240:243], v[62:65]
	v_mfma_f32_16x16x32_bf16 v[62:65], v[194:197], v[236:239], v[104:107]
	v_mfma_f32_16x16x32_bf16 v[64:67], v[200:203], v[240:243], v[62:65]
	v_mfma_f32_16x16x32_bf16 v[68:71], v[204:207], v[20:23], v[112:115]
	v_mfma_f32_16x16x32_bf16 v[20:23], v[212:215], v[20:23], v[34:37]
	v_mfma_f32_16x16x32_bf16 v[120:123], v[138:141], v[28:31], v[20:23]
	v_mfma_f32_16x16x32_bf16 v[20:23], v[204:207], v[216:219], v[38:41]
	v_mfma_f32_16x16x32_bf16 v[112:115], v[208:211], v[220:223], v[20:23]
	v_mfma_f32_16x16x32_bf16 v[20:23], v[212:215], v[216:219], v[42:45]
	v_mfma_f32_16x16x32_bf16 v[104:107], v[138:141], v[220:223], v[20:23]
	v_mfma_f32_16x16x32_bf16 v[20:23], v[204:207], v[228:231], v[46:49]
	v_mfma_f32_16x16x32_bf16 v[96:99], v[208:211], v[232:235], v[20:23]
	v_mfma_f32_16x16x32_bf16 v[20:23], v[212:215], v[228:231], v[50:53]
	v_mfma_f32_16x16x32_bf16 v[88:91], v[138:141], v[232:235], v[20:23]
	v_mfma_f32_16x16x32_bf16 v[20:23], v[204:207], v[236:239], v[54:57]
	v_mfma_f32_16x16x32_bf16 v[80:83], v[208:211], v[240:243], v[20:23]
	v_mfma_f32_16x16x32_bf16 v[20:23], v[212:215], v[236:239], v[58:61]
	v_mfma_f32_16x16x32_bf16 v[128:131], v[208:211], v[28:31], v[68:71]
	v_mfma_f32_16x16x32_bf16 v[68:71], v[138:141], v[240:243], v[20:23]
	s_barrier
	s_setprio 0
	s_mov_b32 m0, s39
	s_or_b32 s3, s51, 0x180
	ds_read_b128 v[32:35], v137 offset:49152
	ds_read_b128 v[40:43], v137 offset:50176
	ds_read_b128 v[216:219], v137 offset:51200
	ds_read_b128 v[220:223], v137 offset:52224
	ds_read_b128 v[228:231], v137 offset:53248
	ds_read_b128 v[232:235], v137 offset:54272
	ds_read_b128 v[236:239], v137 offset:55296
	ds_read_b128 v[240:243], v137 offset:56320
	buffer_load_dwordx4 v133, s[8:11], s3 offen lds
	s_mov_b32 m0, s40
	s_nop 0
	buffer_load_dwordx4 v135, s[8:11], s3 offen lds
	s_or_b32 s3, s51, 0x40180
	s_mov_b32 m0, s43
	s_nop 0
	buffer_load_dwordx4 v133, s[8:11], s3 offen lds
	s_mov_b32 m0, s42
	s_nop 0
	buffer_load_dwordx4 v135, s[8:11], s3 offen lds
	s_waitcnt vmcnt(6)
	s_waitcnt lgkmcnt(0)
	s_nop 0
	s_setprio 1
	s_barrier
	v_mfma_f32_16x16x32_bf16 v[20:23], v[10:13], v[32:35], v[142:145]
	v_mfma_f32_16x16x32_bf16 v[60:63], v[24:27], v[40:43], v[20:23]
	v_mfma_f32_16x16x32_bf16 v[20:23], v[194:197], v[32:35], v[146:149]
	v_mfma_f32_16x16x32_bf16 v[52:55], v[200:203], v[40:43], v[20:23]
	v_mfma_f32_16x16x32_bf16 v[20:23], v[10:13], v[216:219], v[150:153]
	v_mfma_f32_16x16x32_bf16 v[44:47], v[24:27], v[220:223], v[20:23]
	v_mfma_f32_16x16x32_bf16 v[20:23], v[194:197], v[216:219], v[154:157]
	v_mfma_f32_16x16x32_bf16 v[36:39], v[200:203], v[220:223], v[20:23]
	v_mfma_f32_16x16x32_bf16 v[20:23], v[10:13], v[228:231], v[158:161]
	v_mfma_f32_16x16x32_bf16 v[2:5], v[10:13], v[236:239], v[2:5]
	v_mfma_f32_16x16x32_bf16 v[28:31], v[24:27], v[232:235], v[20:23]
	v_mfma_f32_16x16x32_bf16 v[20:23], v[194:197], v[228:231], v[162:165]
	v_mfma_f32_16x16x32_bf16 v[12:15], v[24:27], v[240:243], v[2:5]
	v_mfma_f32_16x16x32_bf16 v[2:5], v[194:197], v[236:239], v[6:9]
	v_mfma_f32_16x16x32_bf16 v[20:23], v[200:203], v[232:235], v[20:23]
	v_mfma_f32_16x16x32_bf16 v[4:7], v[200:203], v[240:243], v[2:5]
	v_mfma_f32_16x16x32_bf16 v[8:11], v[204:207], v[32:35], v[166:169]
	v_mfma_f32_16x16x32_bf16 v[72:75], v[208:211], v[40:43], v[8:11]
	v_mfma_f32_16x16x32_bf16 v[8:11], v[212:215], v[32:35], v[170:173]
	v_mfma_f32_16x16x32_bf16 v[56:59], v[138:141], v[40:43], v[8:11]
	v_mfma_f32_16x16x32_bf16 v[8:11], v[204:207], v[216:219], v[174:177]
	v_mfma_f32_16x16x32_bf16 v[48:51], v[208:211], v[220:223], v[8:11]
	v_mfma_f32_16x16x32_bf16 v[8:11], v[212:215], v[216:219], v[178:181]
	v_mfma_f32_16x16x32_bf16 v[40:43], v[138:141], v[220:223], v[8:11]
	v_mfma_f32_16x16x32_bf16 v[8:11], v[204:207], v[228:231], v[182:185]
	v_mfma_f32_16x16x32_bf16 v[32:35], v[208:211], v[232:235], v[8:11]
	v_mfma_f32_16x16x32_bf16 v[8:11], v[212:215], v[228:231], v[186:189]
	v_mfma_f32_16x16x32_bf16 v[24:27], v[138:141], v[232:235], v[8:11]
	v_mfma_f32_16x16x32_bf16 v[8:11], v[204:207], v[236:239], v[16:19]
	v_mfma_f32_16x16x32_bf16 v[16:19], v[208:211], v[240:243], v[8:11]
	v_mfma_f32_16x16x32_bf16 v[8:11], v[212:215], v[236:239], v[190:193]
	v_mfma_f32_16x16x32_bf16 v[8:11], v[138:141], v[240:243], v[8:11]
	s_barrier
	s_setprio 0
	s_mov_b64 s[2:3], 0
	v_mov_b64_e32 v[234:235], v[226:227]
	v_mov_b32_e32 v226, v0
	v_mov_b64_e32 v[236:237], v[198:199]
	v_mov_b32_e32 v198, v225

; template <class Epi, bool ALIGN_EPI, bool SP2, class Hook>
; __device__ __forceinline__ void gemm_phase(LAS unsigned char* lds, const Gemm g, const StaticOrder& S, const Epi& E, Acc& acc, const bool fresh, const Hook& H, const int wave_id) {
;     ...
;             const Src a1 = cA + (size_t)(t + 1) * kstep;
;             const Src a2 = last ? nA : cA + (size_t)(t + 2) * kstep, b2 = last ? nB : cB + (size_t)(t + 2) * kstep;
;             const Src a3 = a2 + kstep, b3 = b2 + kstep;
.LBB0_1461:
	s_add_i32 s100, s55, 0xfffc0000
	v_add_u32_e32 v138, 0x10000, v136
	v_add_u32_e32 v139, 0x14000, v136
	ds_read_b128 v[140:143], v138
	ds_read_b128 v[144:147], v138 offset:1024
	ds_read_b128 v[148:151], v138 offset:2048
	ds_read_b128 v[152:155], v138 offset:3072
	ds_read_b128 v[156:159], v139
	ds_read_b128 v[160:163], v139 offset:1024
	ds_read_b128 v[164:167], v139 offset:2048
	ds_read_b128 v[168:171], v139 offset:3072
	s_mov_b32 m0, s41
	s_nop 0
	buffer_load_dwordx4 v132, s[12:15], s100 offen lds
	s_mov_b32 m0, s33
	s_nop 0
	buffer_load_dwordx4 v134, s[12:15], s100 offen lds
	s_mov_b32 m0, s45
	ds_read_b128 v[172:175], v137
	ds_read_b128 v[176:179], v137 offset:1024
	ds_read_b128 v[180:183], v137 offset:2048
	ds_read_b128 v[184:187], v137 offset:3072
	ds_read_b128 v[188:191], v137 offset:4096
	ds_read_b128 v[192:195], v137 offset:5120
	ds_read_b128 v[200:203], v137 offset:6144
	ds_read_b128 v[204:207], v137 offset:7168
	buffer_load_dwordx4 v132, s[12:15], s55 offen lds
	s_mov_b32 m0, s46
	s_nop 0
	buffer_load_dwordx4 v134, s[12:15], s55 offen lds
	s_waitcnt vmcnt(8)
	s_waitcnt lgkmcnt(0)
	s_setprio 1
	s_barrier
	v_mfma_f32_16x16x32_bf16 v[124:127], v[140:143], v[172:175], v[124:127]
	v_mfma_f32_16x16x32_bf16 v[116:119], v[148:151], v[172:175], v[116:119]
	v_mfma_f32_16x16x32_bf16 v[108:111], v[140:143], v[180:183], v[108:111]
	v_mfma_f32_16x16x32_bf16 v[100:103], v[148:151], v[180:183], v[100:103]
	v_mfma_f32_16x16x32_bf16 v[92:95], v[140:143], v[188:191], v[92:95]
	v_mfma_f32_16x16x32_bf16 v[84:87], v[148:151], v[188:191], v[84:87]
	v_mfma_f32_16x16x32_bf16 v[76:79], v[140:143], v[200:203], v[76:79]
	v_mfma_f32_16x16x32_bf16 v[64:67], v[148:151], v[200:203], v[64:67]
	v_mfma_f32_16x16x32_bf16 v[124:127], v[144:147], v[176:179], v[124:127]
	v_mfma_f32_16x16x32_bf16 v[116:119], v[152:155], v[176:179], v[116:119]
	v_mfma_f32_16x16x32_bf16 v[108:111], v[144:147], v[184:187], v[108:111]
	v_mfma_f32_16x16x32_bf16 v[100:103], v[152:155], v[184:187], v[100:103]
	v_mfma_f32_16x16x32_bf16 v[92:95], v[144:147], v[192:195], v[92:95]
	v_mfma_f32_16x16x32_bf16 v[84:87], v[152:155], v[192:195], v[84:87]
	v_mfma_f32_16x16x32_bf16 v[76:79], v[144:147], v[204:207], v[76:79]
	v_mfma_f32_16x16x32_bf16 v[64:67], v[152:155], v[204:207], v[64:67]
	v_mfma_f32_16x16x32_bf16 v[128:131], v[156:159], v[172:175], v[128:131]
	v_mfma_f32_16x16x32_bf16 v[120:123], v[164:167], v[172:175], v[120:123]
	v_mfma_f32_16x16x32_bf16 v[112:115], v[156:159], v[180:183], v[112:115]
	v_mfma_f32_16x16x32_bf16 v[104:107], v[164:167], v[180:183], v[104:107]
	v_mfma_f32_16x16x32_bf16 v[96:99], v[156:159], v[188:191], v[96:99]
	v_mfma_f32_16x16x32_bf16 v[88:91], v[164:167], v[188:191], v[88:91]
	v_mfma_f32_16x16x32_bf16 v[80:83], v[156:159], v[200:203], v[80:83]
	v_mfma_f32_16x16x32_bf16 v[68:71], v[164:167], v[200:203], v[68:71]
	v_mfma_f32_16x16x32_bf16 v[128:131], v[160:163], v[176:179], v[128:131]
	v_mfma_f32_16x16x32_bf16 v[120:123], v[168:171], v[176:179], v[120:123]
	v_mfma_f32_16x16x32_bf16 v[112:115], v[160:163], v[184:187], v[112:115]
	v_mfma_f32_16x16x32_bf16 v[104:107], v[168:171], v[184:187], v[104:107]
	v_mfma_f32_16x16x32_bf16 v[96:99], v[160:163], v[192:195], v[96:99]
	v_mfma_f32_16x16x32_bf16 v[88:91], v[168:171], v[192:195], v[88:91]
	v_mfma_f32_16x16x32_bf16 v[80:83], v[160:163], v[204:207], v[80:83]
	v_mfma_f32_16x16x32_bf16 v[68:71], v[168:171], v[204:207], v[68:71]
	s_barrier
	s_setprio 0
	s_add_i32 s16, s55, 0xfffc0080
	s_cmp_eq_u32 s54, 12
	s_cselect_b32 s59, s50, s16
	s_cselect_b32 s17, s9, s77
	s_cselect_b32 s16, s8, s76
	s_cselect_b32 s19, s11, s29
	s_cselect_b32 s18, s10, s28
	s_cselect_b32 s57, s51, s56
	s_cselect_b32 s20, s4, s12
	s_cselect_b32 s21, s5, s13
	s_cselect_b32 s22, s6, s14
	s_cselect_b32 s23, s7, s15
	s_or_b32 s58, s59, 0x80
	s_mov_b32 m0, s92
	ds_read_b128 v[172:175], v137 offset:16384
	ds_read_b128 v[176:179], v137 offset:17408
	ds_read_b128 v[180:183], v137 offset:18432
	ds_read_b128 v[184:187], v137 offset:19456
	ds_read_b128 v[188:191], v137 offset:20480
	ds_read_b128 v[192:195], v137 offset:21504
	ds_read_b128 v[200:203], v137 offset:22528
	ds_read_b128 v[204:207], v137 offset:23552
	buffer_load_dwordx4 v133, s[16:19], s57 offen lds
	s_mov_b32 m0, s93
	s_add_i32 s60, s57, 0x40000
	buffer_load_dwordx4 v135, s[16:19], s57 offen lds
	s_mov_b32 m0, s94
	s_nop 0
	buffer_load_dwordx4 v133, s[16:19], s60 offen lds
	s_mov_b32 m0, s95
	s_nop 0
	buffer_load_dwordx4 v135, s[16:19], s60 offen lds
	s_waitcnt vmcnt(6)
	s_waitcnt lgkmcnt(0)
	s_nop 0
	s_setprio 1
	s_barrier
	v_mfma_f32_16x16x32_bf16 v[60:63], v[140:143], v[172:175], v[60:63]
	v_mfma_f32_16x16x32_bf16 v[52:55], v[148:151], v[172:175], v[52:55]
	v_mfma_f32_16x16x32_bf16 v[44:47], v[140:143], v[180:183], v[44:47]
	v_mfma_f32_16x16x32_bf16 v[36:39], v[148:151], v[180:183], v[36:39]
	v_mfma_f32_16x16x32_bf16 v[28:31], v[140:143], v[188:191], v[28:31]
	v_mfma_f32_16x16x32_bf16 v[20:23], v[148:151], v[188:191], v[20:23]
	v_mfma_f32_16x16x32_bf16 v[12:15], v[140:143], v[200:203], v[12:15]
	v_mfma_f32_16x16x32_bf16 v[2:5], v[148:151], v[200:203], v[4:7]
	v_mfma_f32_16x16x32_bf16 v[60:63], v[144:147], v[176:179], v[60:63]
	v_mfma_f32_16x16x32_bf16 v[52:55], v[152:155], v[176:179], v[52:55]
	v_mfma_f32_16x16x32_bf16 v[44:47], v[144:147], v[184:187], v[44:47]
	v_mfma_f32_16x16x32_bf16 v[36:39], v[152:155], v[184:187], v[36:39]
	v_mfma_f32_16x16x32_bf16 v[28:31], v[144:147], v[192:195], v[28:31]
	v_mfma_f32_16x16x32_bf16 v[20:23], v[152:155], v[192:195], v[20:23]
	v_mfma_f32_16x16x32_bf16 v[12:15], v[144:147], v[204:207], v[12:15]
	v_mfma_f32_16x16x32_bf16 v[2:5], v[152:155], v[204:207], v[2:5]
	v_mfma_f32_16x16x32_bf16 v[72:75], v[156:159], v[172:175], v[72:75]
	v_mfma_f32_16x16x32_bf16 v[56:59], v[164:167], v[172:175], v[56:59]
	v_mfma_f32_16x16x32_bf16 v[48:51], v[156:159], v[180:183], v[48:51]
	v_mfma_f32_16x16x32_bf16 v[40:43], v[164:167], v[180:183], v[40:43]
	v_mfma_f32_16x16x32_bf16 v[32:35], v[156:159], v[188:191], v[32:35]
	v_mfma_f32_16x16x32_bf16 v[24:27], v[164:167], v[188:191], v[24:27]
	v_mfma_f32_16x16x32_bf16 v[16:19], v[156:159], v[200:203], v[16:19]
	v_mfma_f32_16x16x32_bf16 v[6:9], v[164:167], v[200:203], v[8:11]
	v_mfma_f32_16x16x32_bf16 v[72:75], v[160:163], v[176:179], v[72:75]
	v_mfma_f32_16x16x32_bf16 v[56:59], v[168:171], v[176:179], v[56:59]
	v_mfma_f32_16x16x32_bf16 v[48:51], v[160:163], v[184:187], v[48:51]
	v_mfma_f32_16x16x32_bf16 v[40:43], v[168:171], v[184:187], v[40:43]
	v_mfma_f32_16x16x32_bf16 v[32:35], v[160:163], v[192:195], v[32:35]
	v_mfma_f32_16x16x32_bf16 v[24:27], v[168:171], v[192:195], v[24:27]
	v_mfma_f32_16x16x32_bf16 v[16:19], v[160:163], v[204:207], v[16:19]
	v_mfma_f32_16x16x32_bf16 v[8:11], v[168:171], v[204:207], v[6:9]
	s_barrier
	s_setprio 0
	s_mov_b32 m0, s44
	s_nop 0
	buffer_load_dwordx4 v132, s[20:23], s59 offen lds
	s_mov_b32 m0, s36
	s_nop 0
	buffer_load_dwordx4 v134, s[20:23], s59 offen lds
	v_add_u32_e32 v140, 0x18000, v136
	v_add_u32_e32 v141, 0x1c000, v136
	ds_read_b128 v[142:145], v140
	ds_read_b128 v[146:149], v140 offset:1024
	ds_read_b128 v[150:153], v140 offset:2048
	ds_read_b128 v[154:157], v140 offset:3072
	ds_read_b128 v[158:161], v141
	ds_read_b128 v[162:165], v141 offset:1024
	ds_read_b128 v[166:169], v141 offset:2048
	ds_read_b128 v[170:173], v141 offset:3072
	s_add_i32 s59, s59, 0x40000
	s_mov_b32 m0, s37
	ds_read_b128 v[174:177], v137 offset:32768
	ds_read_b128 v[178:181], v137 offset:33792
	ds_read_b128 v[182:185], v137 offset:34816
	ds_read_b128 v[186:189], v137 offset:35840
	ds_read_b128 v[190:193], v137 offset:36864
	ds_read_b128 v[194:197], v137 offset:37888
	ds_read_b128 v[200:203], v137 offset:38912
	ds_read_b128 v[204:207], v137 offset:39936
	buffer_load_dwordx4 v132, s[20:23], s59 offen lds
	s_mov_b32 m0, s38
	s_nop 0
	buffer_load_dwordx4 v134, s[20:23], s59 offen lds
	s_waitcnt vmcnt(8)
	s_waitcnt lgkmcnt(0)
	s_nop 0
	s_setprio 1
	s_barrier
	v_mfma_f32_16x16x32_bf16 v[124:127], v[142:145], v[174:177], v[124:127]
	v_mfma_f32_16x16x32_bf16 v[116:119], v[150:153], v[174:177], v[116:119]
	v_mfma_f32_16x16x32_bf16 v[108:111], v[142:145], v[182:185], v[108:111]
	v_mfma_f32_16x16x32_bf16 v[100:103], v[150:153], v[182:185], v[100:103]
	v_mfma_f32_16x16x32_bf16 v[92:95], v[142:145], v[190:193], v[92:95]
	v_mfma_f32_16x16x32_bf16 v[84:87], v[150:153], v[190:193], v[84:87]
	v_mfma_f32_16x16x32_bf16 v[76:79], v[142:145], v[200:203], v[76:79]
	v_mfma_f32_16x16x32_bf16 v[64:67], v[150:153], v[200:203], v[64:67]
	v_mfma_f32_16x16x32_bf16 v[124:127], v[146:149], v[178:181], v[124:127]
	v_mfma_f32_16x16x32_bf16 v[116:119], v[154:157], v[178:181], v[116:119]
	v_mfma_f32_16x16x32_bf16 v[108:111], v[146:149], v[186:189], v[108:111]
	v_mfma_f32_16x16x32_bf16 v[100:103], v[154:157], v[186:189], v[100:103]
	v_mfma_f32_16x16x32_bf16 v[92:95], v[146:149], v[194:197], v[92:95]
	v_mfma_f32_16x16x32_bf16 v[84:87], v[154:157], v[194:197], v[84:87]
	v_mfma_f32_16x16x32_bf16 v[76:79], v[146:149], v[204:207], v[76:79]
	v_mfma_f32_16x16x32_bf16 v[64:67], v[154:157], v[204:207], v[64:67]
	v_mfma_f32_16x16x32_bf16 v[128:131], v[158:161], v[174:177], v[128:131]
	v_mfma_f32_16x16x32_bf16 v[120:123], v[166:169], v[174:177], v[120:123]
	v_mfma_f32_16x16x32_bf16 v[112:115], v[158:161], v[182:185], v[112:115]
	v_mfma_f32_16x16x32_bf16 v[104:107], v[166:169], v[182:185], v[104:107]
	v_mfma_f32_16x16x32_bf16 v[96:99], v[158:161], v[190:193], v[96:99]
	v_mfma_f32_16x16x32_bf16 v[88:91], v[166:169], v[190:193], v[88:91]
	v_mfma_f32_16x16x32_bf16 v[80:83], v[158:161], v[200:203], v[80:83]
	v_mfma_f32_16x16x32_bf16 v[68:71], v[166:169], v[200:203], v[68:71]
	v_mfma_f32_16x16x32_bf16 v[128:131], v[162:165], v[178:181], v[128:131]
	v_mfma_f32_16x16x32_bf16 v[120:123], v[170:173], v[178:181], v[120:123]
	v_mfma_f32_16x16x32_bf16 v[112:115], v[162:165], v[186:189], v[112:115]
	v_mfma_f32_16x16x32_bf16 v[104:107], v[170:173], v[186:189], v[104:107]
	v_mfma_f32_16x16x32_bf16 v[96:99], v[162:165], v[194:197], v[96:99]
	v_mfma_f32_16x16x32_bf16 v[88:91], v[170:173], v[194:197], v[88:91]
	v_mfma_f32_16x16x32_bf16 v[80:83], v[162:165], v[204:207], v[80:83]
	v_mfma_f32_16x16x32_bf16 v[68:71], v[170:173], v[204:207], v[68:71]
	s_barrier
	s_setprio 0
	s_mov_b32 m0, s39
	s_or_b32 s59, s57, 0x80
	ds_read_b128 v[174:177], v137 offset:49152
	ds_read_b128 v[178:181], v137 offset:50176
	ds_read_b128 v[182:185], v137 offset:51200
	ds_read_b128 v[186:189], v137 offset:52224
	ds_read_b128 v[190:193], v137 offset:53248
	ds_read_b128 v[194:197], v137 offset:54272
	ds_read_b128 v[200:203], v137 offset:55296
	ds_read_b128 v[204:207], v137 offset:56320
	buffer_load_dwordx4 v133, s[16:19], s59 offen lds
	s_mov_b32 m0, s40
	s_add_i32 s57, s57, 0x40080
	buffer_load_dwordx4 v135, s[16:19], s59 offen lds
	s_mov_b32 m0, s43
	s_nop 0
	buffer_load_dwordx4 v133, s[16:19], s57 offen lds
	s_mov_b32 m0, s42
	s_nop 0
	buffer_load_dwordx4 v135, s[16:19], s57 offen lds
	s_add_i32 s54, s54, 2
	s_addk_i32 s55, 0x100
	s_addk_i32 s56, 0x100
	s_cmp_gt_u32 s54, 13
	s_waitcnt vmcnt(6)
	s_waitcnt lgkmcnt(0)
	s_setprio 1
	s_barrier
	v_mfma_f32_16x16x32_bf16 v[60:63], v[142:145], v[174:177], v[60:63]
	v_mfma_f32_16x16x32_bf16 v[52:55], v[150:153], v[174:177], v[52:55]
	v_mfma_f32_16x16x32_bf16 v[44:47], v[142:145], v[182:185], v[44:47]
	v_mfma_f32_16x16x32_bf16 v[36:39], v[150:153], v[182:185], v[36:39]
	v_mfma_f32_16x16x32_bf16 v[28:31], v[142:145], v[190:193], v[28:31]
	v_mfma_f32_16x16x32_bf16 v[20:23], v[150:153], v[190:193], v[20:23]
	v_mfma_f32_16x16x32_bf16 v[12:15], v[142:145], v[200:203], v[12:15]
	v_mfma_f32_16x16x32_bf16 v[2:5], v[150:153], v[200:203], v[2:5]
	v_mfma_f32_16x16x32_bf16 v[60:63], v[146:149], v[178:181], v[60:63]
	v_mfma_f32_16x16x32_bf16 v[52:55], v[154:157], v[178:181], v[52:55]
	v_mfma_f32_16x16x32_bf16 v[44:47], v[146:149], v[186:189], v[44:47]
	v_mfma_f32_16x16x32_bf16 v[36:39], v[154:157], v[186:189], v[36:39]
	v_mfma_f32_16x16x32_bf16 v[28:31], v[146:149], v[194:197], v[28:31]
	v_mfma_f32_16x16x32_bf16 v[20:23], v[154:157], v[194:197], v[20:23]
	v_mfma_f32_16x16x32_bf16 v[12:15], v[146:149], v[204:207], v[12:15]
	v_mfma_f32_16x16x32_bf16 v[4:7], v[154:157], v[204:207], v[2:5]
	v_mfma_f32_16x16x32_bf16 v[72:75], v[158:161], v[174:177], v[72:75]
	v_mfma_f32_16x16x32_bf16 v[56:59], v[166:169], v[174:177], v[56:59]
	v_mfma_f32_16x16x32_bf16 v[48:51], v[158:161], v[182:185], v[48:51]
	v_mfma_f32_16x16x32_bf16 v[40:43], v[166:169], v[182:185], v[40:43]
	v_mfma_f32_16x16x32_bf16 v[32:35], v[158:161], v[190:193], v[32:35]
	v_mfma_f32_16x16x32_bf16 v[24:27], v[166:169], v[190:193], v[24:27]
	v_mfma_f32_16x16x32_bf16 v[16:19], v[158:161], v[200:203], v[16:19]
	v_mfma_f32_16x16x32_bf16 v[8:11], v[166:169], v[200:203], v[8:11]
	v_mfma_f32_16x16x32_bf16 v[72:75], v[162:165], v[178:181], v[72:75]
	v_mfma_f32_16x16x32_bf16 v[56:59], v[170:173], v[178:181], v[56:59]
	v_mfma_f32_16x16x32_bf16 v[48:51], v[162:165], v[186:189], v[48:51]
	v_mfma_f32_16x16x32_bf16 v[40:43], v[170:173], v[186:189], v[40:43]
	v_mfma_f32_16x16x32_bf16 v[32:35], v[162:165], v[194:197], v[32:35]
	v_mfma_f32_16x16x32_bf16 v[24:27], v[170:173], v[194:197], v[24:27]
	v_mfma_f32_16x16x32_bf16 v[16:19], v[162:165], v[204:207], v[16:19]
	v_mfma_f32_16x16x32_bf16 v[8:11], v[170:173], v[204:207], v[8:11]
	s_barrier
	s_setprio 0
	s_cbranch_scc0 .LBB0_1461
	s_mov_b32 m0, s41
	s_nop 0
	buffer_load_dwordx4 v132, s[20:23], s58 offen lds
	s_mov_b32 m0, s33
	s_nop 0
	buffer_load_dwordx4 v134, s[20:23], s58 offen lds
	v_readlane_b32 s12, v251, 45
	v_readlane_b32 s13, v251, 46
	s_and_b64 vcc, exec, s[12:13]
	s_cbranch_vccz .LBB0_1464
	s_barrier

; template <class Epi, bool ALIGN_EPI, bool SP2, class Hook>
; __device__ __forceinline__ void gemm_phase(LAS unsigned char* lds, const Gemm g, const StaticOrder& S, const Epi& E, Acc& acc, const bool fresh, const Hook& H, const int wave_id) {
;     ...
;             const Src a1 = cA + (size_t)(t + 1) * kstep;
;             const Src a2 = last ? nA : cA + (size_t)(t + 2) * kstep, b2 = last ? nB : cB + (size_t)(t + 2) * kstep;
;             const Src a3 = a2 + kstep, b3 = b2 + kstep;
.LBB0_1572:
	s_add_i32 s100, s2, 0xfff40000
	v_add_u32_e32 v142, 0x10000, v161
	v_add_u32_e32 v163, 0x14000, v161
	ds_read_b128 v[130:133], v142
	ds_read_b128 v[134:137], v142 offset:1024
	ds_read_b128 v[138:141], v142 offset:2048
	ds_read_b128 v[142:145], v142 offset:3072
	ds_read_b128 v[146:149], v163
	ds_read_b128 v[150:153], v163 offset:1024
	ds_read_b128 v[154:157], v163 offset:2048
	ds_read_b128 v[164:167], v163 offset:3072
	s_mov_b32 m0, s41
	s_nop 0
	buffer_load_dwordx4 v0, s[12:15], s100 offen lds
	s_mov_b32 m0, s33
	s_nop 0
	buffer_load_dwordx4 v159, s[12:15], s100 offen lds
	s_mov_b32 m0, s45
	ds_read_b128 v[168:171], v162
	ds_read_b128 v[172:175], v162 offset:1024
	ds_read_b128 v[176:179], v162 offset:2048
	ds_read_b128 v[180:183], v162 offset:3072
	ds_read_b128 v[184:187], v162 offset:4096
	ds_read_b128 v[188:191], v162 offset:5120
	ds_read_b128 v[192:195], v162 offset:6144
	ds_read_b128 v[200:203], v162 offset:7168
	buffer_load_dwordx4 v0, s[12:15], s2 offen lds
	s_mov_b32 m0, s46
	s_nop 0
	buffer_load_dwordx4 v159, s[12:15], s2 offen lds
	s_waitcnt vmcnt(8)
	s_waitcnt lgkmcnt(0)
	s_nop 0
	s_setprio 1
	s_barrier
	v_mfma_f32_16x16x32_bf16 v[126:129], v[130:133], v[168:171], v[126:129]
	v_mfma_f32_16x16x32_bf16 v[122:125], v[138:141], v[168:171], v[122:125]
	v_mfma_f32_16x16x32_bf16 v[110:113], v[130:133], v[176:179], v[110:113]
	v_mfma_f32_16x16x32_bf16 v[106:109], v[138:141], v[176:179], v[106:109]
	v_mfma_f32_16x16x32_bf16 v[94:97], v[130:133], v[184:187], v[94:97]
	v_mfma_f32_16x16x32_bf16 v[90:93], v[138:141], v[184:187], v[90:93]
	v_mfma_f32_16x16x32_bf16 v[78:81], v[130:133], v[192:195], v[78:81]
	v_mfma_f32_16x16x32_bf16 v[74:77], v[138:141], v[192:195], v[74:77]
	v_mfma_f32_16x16x32_bf16 v[126:129], v[134:137], v[172:175], v[126:129]
	v_mfma_f32_16x16x32_bf16 v[122:125], v[142:145], v[172:175], v[122:125]
	v_mfma_f32_16x16x32_bf16 v[110:113], v[134:137], v[180:183], v[110:113]
	v_mfma_f32_16x16x32_bf16 v[106:109], v[142:145], v[180:183], v[106:109]
	v_mfma_f32_16x16x32_bf16 v[94:97], v[134:137], v[188:191], v[94:97]
	v_mfma_f32_16x16x32_bf16 v[90:93], v[142:145], v[188:191], v[90:93]
	v_mfma_f32_16x16x32_bf16 v[78:81], v[134:137], v[200:203], v[78:81]
	v_mfma_f32_16x16x32_bf16 v[74:77], v[142:145], v[200:203], v[74:77]
	v_mfma_f32_16x16x32_bf16 v[118:121], v[146:149], v[168:171], v[118:121]
	v_mfma_f32_16x16x32_bf16 v[114:117], v[154:157], v[168:171], v[114:117]
	v_mfma_f32_16x16x32_bf16 v[102:105], v[146:149], v[176:179], v[102:105]
	v_mfma_f32_16x16x32_bf16 v[98:101], v[154:157], v[176:179], v[98:101]
	v_mfma_f32_16x16x32_bf16 v[86:89], v[146:149], v[184:187], v[86:89]
	v_mfma_f32_16x16x32_bf16 v[82:85], v[154:157], v[184:187], v[82:85]
	v_mfma_f32_16x16x32_bf16 v[70:73], v[146:149], v[192:195], v[70:73]
	v_mfma_f32_16x16x32_bf16 v[66:69], v[154:157], v[192:195], v[66:69]
	v_mfma_f32_16x16x32_bf16 v[118:121], v[150:153], v[172:175], v[118:121]
	v_mfma_f32_16x16x32_bf16 v[114:117], v[164:167], v[172:175], v[114:117]
	v_mfma_f32_16x16x32_bf16 v[102:105], v[150:153], v[180:183], v[102:105]
	v_mfma_f32_16x16x32_bf16 v[98:101], v[164:167], v[180:183], v[98:101]
	v_mfma_f32_16x16x32_bf16 v[86:89], v[150:153], v[188:191], v[86:89]
	v_mfma_f32_16x16x32_bf16 v[82:85], v[164:167], v[188:191], v[82:85]
	v_mfma_f32_16x16x32_bf16 v[70:73], v[150:153], v[200:203], v[70:73]
	v_mfma_f32_16x16x32_bf16 v[66:69], v[164:167], v[200:203], v[66:69]
	s_barrier
	s_setprio 0
	s_add_i32 s16, s2, 0xfff40080
	s_cmp_eq_u32 s61, 40
	s_cselect_b32 s64, s57, s16
	s_cselect_b32 s17, s35, s9
	s_cselect_b32 s16, s34, s8
	s_cselect_b32 s19, s51, s53
	s_cselect_b32 s18, s50, s52
	s_cselect_b32 s62, s58, s3
	s_cselect_b32 s20, s10, s12
	s_cselect_b32 s21, s11, s13
	s_cselect_b32 s22, s30, s14
	s_cselect_b32 s23, s31, s15
	s_or_b32 s63, s64, 0x80
	s_mov_b32 m0, s92
	ds_read_b128 v[168:171], v162 offset:16384
	ds_read_b128 v[172:175], v162 offset:17408
	ds_read_b128 v[176:179], v162 offset:18432
	ds_read_b128 v[180:183], v162 offset:19456
	ds_read_b128 v[184:187], v162 offset:20480
	ds_read_b128 v[188:191], v162 offset:21504
	ds_read_b128 v[192:195], v162 offset:22528
	ds_read_b128 v[200:203], v162 offset:23552
	buffer_load_dwordx4 v158, s[16:19], s62 offen lds
	s_mov_b32 m0, s93
	s_add_i32 s65, s62, 0xb0000
	buffer_load_dwordx4 v160, s[16:19], s62 offen lds
	s_mov_b32 m0, s94
	s_nop 0
	buffer_load_dwordx4 v158, s[16:19], s65 offen lds
	s_mov_b32 m0, s95
	s_nop 0
	buffer_load_dwordx4 v160, s[16:19], s65 offen lds
	s_waitcnt vmcnt(6)
	s_waitcnt lgkmcnt(0)
	s_nop 0
	s_setprio 1
	s_barrier
	v_mfma_f32_16x16x32_bf16 v[62:65], v[130:133], v[168:171], v[62:65]
	v_mfma_f32_16x16x32_bf16 v[58:61], v[138:141], v[168:171], v[58:61]
	v_mfma_f32_16x16x32_bf16 v[46:49], v[130:133], v[176:179], v[46:49]
	v_mfma_f32_16x16x32_bf16 v[42:45], v[138:141], v[176:179], v[42:45]
	v_mfma_f32_16x16x32_bf16 v[30:33], v[130:133], v[184:187], v[30:33]
	v_mfma_f32_16x16x32_bf16 v[26:29], v[138:141], v[184:187], v[26:29]
	v_mfma_f32_16x16x32_bf16 v[14:17], v[130:133], v[192:195], v[14:17]
	v_mfma_f32_16x16x32_bf16 v[10:13], v[138:141], v[192:195], v[10:13]
	v_mfma_f32_16x16x32_bf16 v[62:65], v[134:137], v[172:175], v[62:65]
	v_mfma_f32_16x16x32_bf16 v[58:61], v[142:145], v[172:175], v[58:61]
	v_mfma_f32_16x16x32_bf16 v[46:49], v[134:137], v[180:183], v[46:49]
	v_mfma_f32_16x16x32_bf16 v[42:45], v[142:145], v[180:183], v[42:45]
	v_mfma_f32_16x16x32_bf16 v[30:33], v[134:137], v[188:191], v[30:33]
	v_mfma_f32_16x16x32_bf16 v[26:29], v[142:145], v[188:191], v[26:29]
	v_mfma_f32_16x16x32_bf16 v[14:17], v[134:137], v[200:203], v[14:17]
	v_mfma_f32_16x16x32_bf16 v[10:13], v[142:145], v[200:203], v[10:13]
	v_mfma_f32_16x16x32_bf16 v[54:57], v[146:149], v[168:171], v[54:57]
	v_mfma_f32_16x16x32_bf16 v[50:53], v[154:157], v[168:171], v[50:53]
	v_mfma_f32_16x16x32_bf16 v[38:41], v[146:149], v[176:179], v[38:41]
	v_mfma_f32_16x16x32_bf16 v[34:37], v[154:157], v[176:179], v[34:37]
	v_mfma_f32_16x16x32_bf16 v[22:25], v[146:149], v[184:187], v[22:25]
	v_mfma_f32_16x16x32_bf16 v[18:21], v[154:157], v[184:187], v[18:21]
	v_mfma_f32_16x16x32_bf16 v[6:9], v[146:149], v[192:195], v[6:9]
	v_mfma_f32_16x16x32_bf16 v[2:5], v[154:157], v[192:195], v[2:5]
	v_mfma_f32_16x16x32_bf16 v[54:57], v[150:153], v[172:175], v[54:57]
	v_mfma_f32_16x16x32_bf16 v[50:53], v[164:167], v[172:175], v[50:53]
	v_mfma_f32_16x16x32_bf16 v[38:41], v[150:153], v[180:183], v[38:41]
	v_mfma_f32_16x16x32_bf16 v[34:37], v[164:167], v[180:183], v[34:37]
	v_mfma_f32_16x16x32_bf16 v[22:25], v[150:153], v[188:191], v[22:25]
	v_mfma_f32_16x16x32_bf16 v[18:21], v[164:167], v[188:191], v[18:21]
	v_mfma_f32_16x16x32_bf16 v[6:9], v[150:153], v[200:203], v[6:9]
	v_mfma_f32_16x16x32_bf16 v[2:5], v[164:167], v[200:203], v[2:5]
	s_barrier
	s_setprio 0
	s_mov_b32 m0, s44
	s_nop 0
	buffer_load_dwordx4 v0, s[20:23], s64 offen lds
	s_mov_b32 m0, s36
	s_nop 0
	buffer_load_dwordx4 v159, s[20:23], s64 offen lds
	v_add_u32_e32 v142, 0x18000, v161
	v_add_u32_e32 v163, 0x1c000, v161
	ds_read_b128 v[130:133], v142
	ds_read_b128 v[134:137], v142 offset:1024
	ds_read_b128 v[138:141], v142 offset:2048
	ds_read_b128 v[142:145], v142 offset:3072
	ds_read_b128 v[146:149], v163
	ds_read_b128 v[150:153], v163 offset:1024
	ds_read_b128 v[154:157], v163 offset:2048
	ds_read_b128 v[164:167], v163 offset:3072
	s_add_i32 s64, s64, 0xc0000
	s_mov_b32 m0, s37
	ds_read_b128 v[168:171], v162 offset:32768
	ds_read_b128 v[172:175], v162 offset:33792
	ds_read_b128 v[176:179], v162 offset:34816
	ds_read_b128 v[180:183], v162 offset:35840
	ds_read_b128 v[184:187], v162 offset:36864
	ds_read_b128 v[188:191], v162 offset:37888
	ds_read_b128 v[192:195], v162 offset:38912
	ds_read_b128 v[200:203], v162 offset:39936
	buffer_load_dwordx4 v0, s[20:23], s64 offen lds
	s_mov_b32 m0, s38
	s_nop 0
	buffer_load_dwordx4 v159, s[20:23], s64 offen lds
	s_waitcnt vmcnt(8)
	s_waitcnt lgkmcnt(0)
	s_nop 0
	s_setprio 1
	s_barrier
	v_mfma_f32_16x16x32_bf16 v[126:129], v[130:133], v[168:171], v[126:129]
	v_mfma_f32_16x16x32_bf16 v[122:125], v[138:141], v[168:171], v[122:125]
	v_mfma_f32_16x16x32_bf16 v[110:113], v[130:133], v[176:179], v[110:113]
	v_mfma_f32_16x16x32_bf16 v[106:109], v[138:141], v[176:179], v[106:109]
	v_mfma_f32_16x16x32_bf16 v[94:97], v[130:133], v[184:187], v[94:97]
	v_mfma_f32_16x16x32_bf16 v[90:93], v[138:141], v[184:187], v[90:93]
	v_mfma_f32_16x16x32_bf16 v[78:81], v[130:133], v[192:195], v[78:81]
	v_mfma_f32_16x16x32_bf16 v[74:77], v[138:141], v[192:195], v[74:77]
	v_mfma_f32_16x16x32_bf16 v[126:129], v[134:137], v[172:175], v[126:129]
	v_mfma_f32_16x16x32_bf16 v[122:125], v[142:145], v[172:175], v[122:125]
	v_mfma_f32_16x16x32_bf16 v[110:113], v[134:137], v[180:183], v[110:113]
	v_mfma_f32_16x16x32_bf16 v[106:109], v[142:145], v[180:183], v[106:109]
	v_mfma_f32_16x16x32_bf16 v[94:97], v[134:137], v[188:191], v[94:97]
	v_mfma_f32_16x16x32_bf16 v[90:93], v[142:145], v[188:191], v[90:93]
	v_mfma_f32_16x16x32_bf16 v[78:81], v[134:137], v[200:203], v[78:81]
	v_mfma_f32_16x16x32_bf16 v[74:77], v[142:145], v[200:203], v[74:77]
	v_mfma_f32_16x16x32_bf16 v[118:121], v[146:149], v[168:171], v[118:121]
	v_mfma_f32_16x16x32_bf16 v[114:117], v[154:157], v[168:171], v[114:117]
	v_mfma_f32_16x16x32_bf16 v[102:105], v[146:149], v[176:179], v[102:105]
	v_mfma_f32_16x16x32_bf16 v[98:101], v[154:157], v[176:179], v[98:101]
	v_mfma_f32_16x16x32_bf16 v[86:89], v[146:149], v[184:187], v[86:89]
	v_mfma_f32_16x16x32_bf16 v[82:85], v[154:157], v[184:187], v[82:85]
	v_mfma_f32_16x16x32_bf16 v[70:73], v[146:149], v[192:195], v[70:73]
	v_mfma_f32_16x16x32_bf16 v[66:69], v[154:157], v[192:195], v[66:69]
	v_mfma_f32_16x16x32_bf16 v[118:121], v[150:153], v[172:175], v[118:121]
	v_mfma_f32_16x16x32_bf16 v[114:117], v[164:167], v[172:175], v[114:117]
	v_mfma_f32_16x16x32_bf16 v[102:105], v[150:153], v[180:183], v[102:105]
	v_mfma_f32_16x16x32_bf16 v[98:101], v[164:167], v[180:183], v[98:101]
	v_mfma_f32_16x16x32_bf16 v[86:89], v[150:153], v[188:191], v[86:89]
	v_mfma_f32_16x16x32_bf16 v[82:85], v[164:167], v[188:191], v[82:85]
	v_mfma_f32_16x16x32_bf16 v[70:73], v[150:153], v[200:203], v[70:73]
	v_mfma_f32_16x16x32_bf16 v[66:69], v[164:167], v[200:203], v[66:69]
	s_barrier
	s_setprio 0
	s_mov_b32 m0, s39
	s_or_b32 s64, s62, 0x80
	ds_read_b128 v[168:171], v162 offset:49152
	ds_read_b128 v[172:175], v162 offset:50176
	ds_read_b128 v[176:179], v162 offset:51200
	ds_read_b128 v[180:183], v162 offset:52224
	ds_read_b128 v[184:187], v162 offset:53248
	ds_read_b128 v[188:191], v162 offset:54272
	ds_read_b128 v[192:195], v162 offset:55296
	ds_read_b128 v[200:203], v162 offset:56320
	buffer_load_dwordx4 v158, s[16:19], s64 offen lds
	s_mov_b32 m0, s40
	s_add_i32 s62, s62, 0xb0080
	buffer_load_dwordx4 v160, s[16:19], s64 offen lds
	s_mov_b32 m0, s43
	s_nop 0
	buffer_load_dwordx4 v158, s[16:19], s62 offen lds
	s_mov_b32 m0, s42
	s_nop 0
	buffer_load_dwordx4 v160, s[16:19], s62 offen lds
	s_add_i32 s61, s61, 2
	s_addk_i32 s2, 0x100
	s_addk_i32 s3, 0x100
	s_cmp_gt_u32 s61, 41
	s_waitcnt vmcnt(6)
	s_waitcnt lgkmcnt(0)
	s_setprio 1
	s_barrier
	v_mfma_f32_16x16x32_bf16 v[62:65], v[130:133], v[168:171], v[62:65]
	v_mfma_f32_16x16x32_bf16 v[58:61], v[138:141], v[168:171], v[58:61]
	v_mfma_f32_16x16x32_bf16 v[46:49], v[130:133], v[176:179], v[46:49]
	v_mfma_f32_16x16x32_bf16 v[42:45], v[138:141], v[176:179], v[42:45]
	v_mfma_f32_16x16x32_bf16 v[30:33], v[130:133], v[184:187], v[30:33]
	v_mfma_f32_16x16x32_bf16 v[26:29], v[138:141], v[184:187], v[26:29]
	v_mfma_f32_16x16x32_bf16 v[14:17], v[130:133], v[192:195], v[14:17]
	v_mfma_f32_16x16x32_bf16 v[10:13], v[138:141], v[192:195], v[10:13]
	v_mfma_f32_16x16x32_bf16 v[62:65], v[134:137], v[172:175], v[62:65]
	v_mfma_f32_16x16x32_bf16 v[58:61], v[142:145], v[172:175], v[58:61]
	v_mfma_f32_16x16x32_bf16 v[46:49], v[134:137], v[180:183], v[46:49]
	v_mfma_f32_16x16x32_bf16 v[42:45], v[142:145], v[180:183], v[42:45]
	v_mfma_f32_16x16x32_bf16 v[30:33], v[134:137], v[188:191], v[30:33]
	v_mfma_f32_16x16x32_bf16 v[26:29], v[142:145], v[188:191], v[26:29]
	v_mfma_f32_16x16x32_bf16 v[14:17], v[134:137], v[200:203], v[14:17]
	v_mfma_f32_16x16x32_bf16 v[10:13], v[142:145], v[200:203], v[10:13]
	v_mfma_f32_16x16x32_bf16 v[54:57], v[146:149], v[168:171], v[54:57]
	v_mfma_f32_16x16x32_bf16 v[50:53], v[154:157], v[168:171], v[50:53]
	v_mfma_f32_16x16x32_bf16 v[38:41], v[146:149], v[176:179], v[38:41]
	v_mfma_f32_16x16x32_bf16 v[34:37], v[154:157], v[176:179], v[34:37]
	v_mfma_f32_16x16x32_bf16 v[22:25], v[146:149], v[184:187], v[22:25]
	v_mfma_f32_16x16x32_bf16 v[18:21], v[154:157], v[184:187], v[18:21]
	v_mfma_f32_16x16x32_bf16 v[6:9], v[146:149], v[192:195], v[6:9]
	v_mfma_f32_16x16x32_bf16 v[2:5], v[154:157], v[192:195], v[2:5]
	v_mfma_f32_16x16x32_bf16 v[54:57], v[150:153], v[172:175], v[54:57]
	v_mfma_f32_16x16x32_bf16 v[50:53], v[164:167], v[172:175], v[50:53]
	v_mfma_f32_16x16x32_bf16 v[38:41], v[150:153], v[180:183], v[38:41]
	v_mfma_f32_16x16x32_bf16 v[34:37], v[164:167], v[180:183], v[34:37]
	v_mfma_f32_16x16x32_bf16 v[22:25], v[150:153], v[188:191], v[22:25]
	v_mfma_f32_16x16x32_bf16 v[18:21], v[164:167], v[188:191], v[18:21]
	v_mfma_f32_16x16x32_bf16 v[6:9], v[150:153], v[200:203], v[6:9]
	v_mfma_f32_16x16x32_bf16 v[2:5], v[164:167], v[200:203], v[2:5]
	s_barrier
	s_setprio 0
	s_cbranch_scc0 .LBB0_1572
	s_mov_b32 m0, s41
	s_nop 0
	buffer_load_dwordx4 v0, s[20:23], s63 offen lds
	s_mov_b32 m0, s33
	s_nop 0
	buffer_load_dwordx4 v159, s[20:23], s63 offen lds
	v_readlane_b32 s2, v251, 45
	v_readlane_b32 s3, v251, 46
	s_and_b64 vcc, exec, s[2:3]
	s_cbranch_vccz .LBB0_1575
	s_barrier

; template <class Epi, bool ALIGN_EPI, bool SP2, class Hook>
; __device__ __forceinline__ void gemm_phase(LAS unsigned char* lds, const Gemm g, const StaticOrder& S, const Epi& E, Acc& acc, const bool fresh, const Hook& H, const int wave_id) {
;     ...
;             const Src a1 = cA + (size_t)(t + 1) * kstep;
;             const Src a2 = last ? nA : cA + (size_t)(t + 2) * kstep, b2 = last ? nB : cB + (size_t)(t + 2) * kstep;
;             const Src a3 = a2 + kstep, b3 = b2 + kstep;
.LBB0_1614:
	s_add_i32 s100, s2, 0xfff40000
	v_add_u32_e32 v0, 0x10000, v172
	ds_read_b128 v[130:133], v0
	ds_read_b128 v[134:137], v0 offset:1024
	ds_read_b128 v[138:141], v0 offset:2048
	ds_read_b128 v[142:145], v0 offset:3072
	v_add_u32_e32 v0, 0x14000, v172
	ds_read_b128 v[146:149], v0
	ds_read_b128 v[150:153], v0 offset:1024
	ds_read_b128 v[154:157], v0 offset:2048
	ds_read_b128 v[158:161], v0 offset:3072
	s_mov_b32 m0, s41
	s_nop 0
	buffer_load_dwordx4 v168, s[8:11], s100 offen lds
	s_mov_b32 m0, s33
	s_nop 0
	buffer_load_dwordx4 v170, s[8:11], s100 offen lds
	s_mov_b32 m0, s45
	ds_read_b128 v[162:165], v173
	ds_read_b128 v[174:177], v173 offset:1024
	ds_read_b128 v[178:181], v173 offset:2048
	ds_read_b128 v[182:185], v173 offset:3072
	ds_read_b128 v[186:189], v173 offset:4096
	ds_read_b128 v[190:193], v173 offset:5120
	ds_read_b128 v[194:197], v173 offset:6144
	ds_read_b128 v[200:203], v173 offset:7168
	buffer_load_dwordx4 v168, s[8:11], s2 offen lds
	s_mov_b32 m0, s46
	s_nop 0
	buffer_load_dwordx4 v170, s[8:11], s2 offen lds
	s_waitcnt vmcnt(8)
	s_waitcnt lgkmcnt(0)
	s_nop 0
	s_setprio 1
	s_barrier
	v_mfma_f32_16x16x32_bf16 v[126:129], v[130:133], v[162:165], v[126:129]
	v_mfma_f32_16x16x32_bf16 v[122:125], v[138:141], v[162:165], v[122:125]
	v_mfma_f32_16x16x32_bf16 v[110:113], v[130:133], v[178:181], v[110:113]
	v_mfma_f32_16x16x32_bf16 v[106:109], v[138:141], v[178:181], v[106:109]
	v_mfma_f32_16x16x32_bf16 v[94:97], v[130:133], v[186:189], v[94:97]
	v_mfma_f32_16x16x32_bf16 v[90:93], v[138:141], v[186:189], v[90:93]
	v_mfma_f32_16x16x32_bf16 v[78:81], v[130:133], v[194:197], v[78:81]
	v_mfma_f32_16x16x32_bf16 v[74:77], v[138:141], v[194:197], v[74:77]
	v_mfma_f32_16x16x32_bf16 v[126:129], v[134:137], v[174:177], v[126:129]
	v_mfma_f32_16x16x32_bf16 v[122:125], v[142:145], v[174:177], v[122:125]
	v_mfma_f32_16x16x32_bf16 v[110:113], v[134:137], v[182:185], v[110:113]
	v_mfma_f32_16x16x32_bf16 v[106:109], v[142:145], v[182:185], v[106:109]
	v_mfma_f32_16x16x32_bf16 v[94:97], v[134:137], v[190:193], v[94:97]
	v_mfma_f32_16x16x32_bf16 v[90:93], v[142:145], v[190:193], v[90:93]
	v_mfma_f32_16x16x32_bf16 v[78:81], v[134:137], v[200:203], v[78:81]
	v_mfma_f32_16x16x32_bf16 v[74:77], v[142:145], v[200:203], v[74:77]
	v_mfma_f32_16x16x32_bf16 v[118:121], v[146:149], v[162:165], v[118:121]
	v_mfma_f32_16x16x32_bf16 v[114:117], v[154:157], v[162:165], v[114:117]
	v_mfma_f32_16x16x32_bf16 v[102:105], v[146:149], v[178:181], v[102:105]
	v_mfma_f32_16x16x32_bf16 v[98:101], v[154:157], v[178:181], v[98:101]
	v_mfma_f32_16x16x32_bf16 v[86:89], v[146:149], v[186:189], v[86:89]
	v_mfma_f32_16x16x32_bf16 v[82:85], v[154:157], v[186:189], v[82:85]
	v_mfma_f32_16x16x32_bf16 v[70:73], v[146:149], v[194:197], v[70:73]
	v_mfma_f32_16x16x32_bf16 v[66:69], v[154:157], v[194:197], v[66:69]
	v_mfma_f32_16x16x32_bf16 v[118:121], v[150:153], v[174:177], v[118:121]
	v_mfma_f32_16x16x32_bf16 v[114:117], v[158:161], v[174:177], v[114:117]
	v_mfma_f32_16x16x32_bf16 v[102:105], v[150:153], v[182:185], v[102:105]
	v_mfma_f32_16x16x32_bf16 v[98:101], v[158:161], v[182:185], v[98:101]
	v_mfma_f32_16x16x32_bf16 v[86:89], v[150:153], v[190:193], v[86:89]
	v_mfma_f32_16x16x32_bf16 v[82:85], v[158:161], v[190:193], v[82:85]
	v_mfma_f32_16x16x32_bf16 v[70:73], v[150:153], v[200:203], v[70:73]
	v_mfma_f32_16x16x32_bf16 v[66:69], v[158:161], v[200:203], v[66:69]
	s_barrier
	s_setprio 0
	s_add_i32 s12, s2, 0xfff40080
	s_cmp_eq_u32 s59, 40
	s_cselect_b32 s62, s55, s12
	s_cselect_b32 s13, s31, s77
	s_cselect_b32 s12, s30, s76
	s_cselect_b32 s15, s35, s51
	s_cselect_b32 s14, s34, s50
	s_cselect_b32 s60, s56, s3
	s_cselect_b32 s16, s20, s8
	s_cselect_b32 s17, s21, s9
	s_cselect_b32 s18, s22, s10
	s_cselect_b32 s19, s23, s11
	s_or_b32 s61, s62, 0x80
	s_mov_b32 m0, s92
	ds_read_b128 v[162:165], v173 offset:16384
	ds_read_b128 v[174:177], v173 offset:17408
	ds_read_b128 v[178:181], v173 offset:18432
	ds_read_b128 v[182:185], v173 offset:19456
	ds_read_b128 v[186:189], v173 offset:20480
	ds_read_b128 v[190:193], v173 offset:21504
	ds_read_b128 v[194:197], v173 offset:22528
	ds_read_b128 v[200:203], v173 offset:23552
	buffer_load_dwordx4 v169, s[12:15], s60 offen lds
	s_mov_b32 m0, s93
	s_add_i32 s63, s60, 0xb0000
	buffer_load_dwordx4 v171, s[12:15], s60 offen lds
	s_mov_b32 m0, s94
	s_nop 0
	buffer_load_dwordx4 v169, s[12:15], s63 offen lds
	s_mov_b32 m0, s95
	s_nop 0
	buffer_load_dwordx4 v171, s[12:15], s63 offen lds
	s_waitcnt vmcnt(6)
	s_waitcnt lgkmcnt(0)
	s_nop 0
	s_setprio 1
	s_barrier
	v_mfma_f32_16x16x32_bf16 v[62:65], v[130:133], v[162:165], v[62:65]
	v_mfma_f32_16x16x32_bf16 v[58:61], v[138:141], v[162:165], v[58:61]
	v_mfma_f32_16x16x32_bf16 v[46:49], v[130:133], v[178:181], v[46:49]
	v_mfma_f32_16x16x32_bf16 v[42:45], v[138:141], v[178:181], v[42:45]
	v_mfma_f32_16x16x32_bf16 v[30:33], v[130:133], v[186:189], v[30:33]
	v_mfma_f32_16x16x32_bf16 v[26:29], v[138:141], v[186:189], v[26:29]
	v_mfma_f32_16x16x32_bf16 v[14:17], v[130:133], v[194:197], v[14:17]
	v_mfma_f32_16x16x32_bf16 v[10:13], v[138:141], v[194:197], v[10:13]
	v_mfma_f32_16x16x32_bf16 v[62:65], v[134:137], v[174:177], v[62:65]
	v_mfma_f32_16x16x32_bf16 v[58:61], v[142:145], v[174:177], v[58:61]
	v_mfma_f32_16x16x32_bf16 v[46:49], v[134:137], v[182:185], v[46:49]
	v_mfma_f32_16x16x32_bf16 v[42:45], v[142:145], v[182:185], v[42:45]
	v_mfma_f32_16x16x32_bf16 v[30:33], v[134:137], v[190:193], v[30:33]
	v_mfma_f32_16x16x32_bf16 v[26:29], v[142:145], v[190:193], v[26:29]
	v_mfma_f32_16x16x32_bf16 v[14:17], v[134:137], v[200:203], v[14:17]
	v_mfma_f32_16x16x32_bf16 v[10:13], v[142:145], v[200:203], v[10:13]
	v_mfma_f32_16x16x32_bf16 v[54:57], v[146:149], v[162:165], v[54:57]
	v_mfma_f32_16x16x32_bf16 v[50:53], v[154:157], v[162:165], v[50:53]
	v_mfma_f32_16x16x32_bf16 v[38:41], v[146:149], v[178:181], v[38:41]
	v_mfma_f32_16x16x32_bf16 v[34:37], v[154:157], v[178:181], v[34:37]
	v_mfma_f32_16x16x32_bf16 v[22:25], v[146:149], v[186:189], v[22:25]
	v_mfma_f32_16x16x32_bf16 v[18:21], v[154:157], v[186:189], v[18:21]
	v_mfma_f32_16x16x32_bf16 v[6:9], v[146:149], v[194:197], v[6:9]
	v_mfma_f32_16x16x32_bf16 v[2:5], v[154:157], v[194:197], v[2:5]
	v_mfma_f32_16x16x32_bf16 v[54:57], v[150:153], v[174:177], v[54:57]
	v_mfma_f32_16x16x32_bf16 v[50:53], v[158:161], v[174:177], v[50:53]
	v_mfma_f32_16x16x32_bf16 v[38:41], v[150:153], v[182:185], v[38:41]
	v_mfma_f32_16x16x32_bf16 v[34:37], v[158:161], v[182:185], v[34:37]
	v_mfma_f32_16x16x32_bf16 v[22:25], v[150:153], v[190:193], v[22:25]
	v_mfma_f32_16x16x32_bf16 v[18:21], v[158:161], v[190:193], v[18:21]
	v_mfma_f32_16x16x32_bf16 v[6:9], v[150:153], v[200:203], v[6:9]
	v_mfma_f32_16x16x32_bf16 v[2:5], v[158:161], v[200:203], v[2:5]
	s_barrier
	s_setprio 0
	s_mov_b32 m0, s44
	s_nop 0
	buffer_load_dwordx4 v168, s[16:19], s62 offen lds
	s_mov_b32 m0, s36
	s_nop 0
	buffer_load_dwordx4 v170, s[16:19], s62 offen lds
	v_add_u32_e32 v0, 0x18000, v172
	ds_read_b128 v[130:133], v0
	ds_read_b128 v[134:137], v0 offset:1024
	ds_read_b128 v[138:141], v0 offset:2048
	ds_read_b128 v[142:145], v0 offset:3072
	v_add_u32_e32 v0, 0x1c000, v172
	ds_read_b128 v[146:149], v0
	ds_read_b128 v[150:153], v0 offset:1024
	ds_read_b128 v[154:157], v0 offset:2048
	ds_read_b128 v[158:161], v0 offset:3072
	s_add_i32 s62, s62, 0xc0000
	s_mov_b32 m0, s37
	ds_read_b128 v[162:165], v173 offset:32768
	ds_read_b128 v[174:177], v173 offset:33792
	ds_read_b128 v[178:181], v173 offset:34816
	ds_read_b128 v[182:185], v173 offset:35840
	ds_read_b128 v[186:189], v173 offset:36864
	ds_read_b128 v[190:193], v173 offset:37888
	ds_read_b128 v[194:197], v173 offset:38912
	ds_read_b128 v[200:203], v173 offset:39936
	buffer_load_dwordx4 v168, s[16:19], s62 offen lds
	s_mov_b32 m0, s38
	s_nop 0
	buffer_load_dwordx4 v170, s[16:19], s62 offen lds
	s_waitcnt vmcnt(8)
	s_waitcnt lgkmcnt(0)
	s_nop 0
	s_setprio 1
	s_barrier
	v_mfma_f32_16x16x32_bf16 v[126:129], v[130:133], v[162:165], v[126:129]
	v_mfma_f32_16x16x32_bf16 v[122:125], v[138:141], v[162:165], v[122:125]
	v_mfma_f32_16x16x32_bf16 v[110:113], v[130:133], v[178:181], v[110:113]
	v_mfma_f32_16x16x32_bf16 v[106:109], v[138:141], v[178:181], v[106:109]
	v_mfma_f32_16x16x32_bf16 v[94:97], v[130:133], v[186:189], v[94:97]
	v_mfma_f32_16x16x32_bf16 v[90:93], v[138:141], v[186:189], v[90:93]
	v_mfma_f32_16x16x32_bf16 v[78:81], v[130:133], v[194:197], v[78:81]
	v_mfma_f32_16x16x32_bf16 v[74:77], v[138:141], v[194:197], v[74:77]
	v_mfma_f32_16x16x32_bf16 v[126:129], v[134:137], v[174:177], v[126:129]
	v_mfma_f32_16x16x32_bf16 v[122:125], v[142:145], v[174:177], v[122:125]
	v_mfma_f32_16x16x32_bf16 v[110:113], v[134:137], v[182:185], v[110:113]
	v_mfma_f32_16x16x32_bf16 v[106:109], v[142:145], v[182:185], v[106:109]
	v_mfma_f32_16x16x32_bf16 v[94:97], v[134:137], v[190:193], v[94:97]
	v_mfma_f32_16x16x32_bf16 v[90:93], v[142:145], v[190:193], v[90:93]
	v_mfma_f32_16x16x32_bf16 v[78:81], v[134:137], v[200:203], v[78:81]
	v_mfma_f32_16x16x32_bf16 v[74:77], v[142:145], v[200:203], v[74:77]
	v_mfma_f32_16x16x32_bf16 v[118:121], v[146:149], v[162:165], v[118:121]
	v_mfma_f32_16x16x32_bf16 v[114:117], v[154:157], v[162:165], v[114:117]
	v_mfma_f32_16x16x32_bf16 v[102:105], v[146:149], v[178:181], v[102:105]
	v_mfma_f32_16x16x32_bf16 v[98:101], v[154:157], v[178:181], v[98:101]
	v_mfma_f32_16x16x32_bf16 v[86:89], v[146:149], v[186:189], v[86:89]
	v_mfma_f32_16x16x32_bf16 v[82:85], v[154:157], v[186:189], v[82:85]
	v_mfma_f32_16x16x32_bf16 v[70:73], v[146:149], v[194:197], v[70:73]
	v_mfma_f32_16x16x32_bf16 v[66:69], v[154:157], v[194:197], v[66:69]
	v_mfma_f32_16x16x32_bf16 v[118:121], v[150:153], v[174:177], v[118:121]
	v_mfma_f32_16x16x32_bf16 v[114:117], v[158:161], v[174:177], v[114:117]
	v_mfma_f32_16x16x32_bf16 v[102:105], v[150:153], v[182:185], v[102:105]
	v_mfma_f32_16x16x32_bf16 v[98:101], v[158:161], v[182:185], v[98:101]
	v_mfma_f32_16x16x32_bf16 v[86:89], v[150:153], v[190:193], v[86:89]
	v_mfma_f32_16x16x32_bf16 v[82:85], v[158:161], v[190:193], v[82:85]
	v_mfma_f32_16x16x32_bf16 v[70:73], v[150:153], v[200:203], v[70:73]
	v_mfma_f32_16x16x32_bf16 v[66:69], v[158:161], v[200:203], v[66:69]
	s_barrier
	s_setprio 0
	s_mov_b32 m0, s39
	s_or_b32 s62, s60, 0x80
	ds_read_b128 v[162:165], v173 offset:49152
	ds_read_b128 v[174:177], v173 offset:50176
	ds_read_b128 v[178:181], v173 offset:51200
	ds_read_b128 v[182:185], v173 offset:52224
	ds_read_b128 v[186:189], v173 offset:53248
	ds_read_b128 v[190:193], v173 offset:54272
	ds_read_b128 v[194:197], v173 offset:55296
	ds_read_b128 v[200:203], v173 offset:56320
	buffer_load_dwordx4 v169, s[12:15], s62 offen lds
	s_mov_b32 m0, s40
	s_add_i32 s60, s60, 0xb0080
	buffer_load_dwordx4 v171, s[12:15], s62 offen lds
	s_mov_b32 m0, s43
	s_nop 0
	buffer_load_dwordx4 v169, s[12:15], s60 offen lds
	s_mov_b32 m0, s42
	s_nop 0
	buffer_load_dwordx4 v171, s[12:15], s60 offen lds
	s_add_i32 s59, s59, 2
	s_addk_i32 s2, 0x100
	s_addk_i32 s3, 0x100
	s_cmp_gt_u32 s59, 41
	s_waitcnt vmcnt(6)
	s_waitcnt lgkmcnt(0)
	s_setprio 1
	s_barrier
	v_mfma_f32_16x16x32_bf16 v[62:65], v[130:133], v[162:165], v[62:65]
	v_mfma_f32_16x16x32_bf16 v[58:61], v[138:141], v[162:165], v[58:61]
	v_mfma_f32_16x16x32_bf16 v[46:49], v[130:133], v[178:181], v[46:49]
	v_mfma_f32_16x16x32_bf16 v[42:45], v[138:141], v[178:181], v[42:45]
	v_mfma_f32_16x16x32_bf16 v[30:33], v[130:133], v[186:189], v[30:33]
	v_mfma_f32_16x16x32_bf16 v[26:29], v[138:141], v[186:189], v[26:29]
	v_mfma_f32_16x16x32_bf16 v[14:17], v[130:133], v[194:197], v[14:17]
	v_mfma_f32_16x16x32_bf16 v[10:13], v[138:141], v[194:197], v[10:13]
	v_mfma_f32_16x16x32_bf16 v[62:65], v[134:137], v[174:177], v[62:65]
	v_mfma_f32_16x16x32_bf16 v[58:61], v[142:145], v[174:177], v[58:61]
	v_mfma_f32_16x16x32_bf16 v[46:49], v[134:137], v[182:185], v[46:49]
	v_mfma_f32_16x16x32_bf16 v[42:45], v[142:145], v[182:185], v[42:45]
	v_mfma_f32_16x16x32_bf16 v[30:33], v[134:137], v[190:193], v[30:33]
	v_mfma_f32_16x16x32_bf16 v[26:29], v[142:145], v[190:193], v[26:29]
	v_mfma_f32_16x16x32_bf16 v[14:17], v[134:137], v[200:203], v[14:17]
	v_mfma_f32_16x16x32_bf16 v[10:13], v[142:145], v[200:203], v[10:13]
	v_mfma_f32_16x16x32_bf16 v[54:57], v[146:149], v[162:165], v[54:57]
	v_mfma_f32_16x16x32_bf16 v[50:53], v[154:157], v[162:165], v[50:53]
	v_mfma_f32_16x16x32_bf16 v[38:41], v[146:149], v[178:181], v[38:41]
	v_mfma_f32_16x16x32_bf16 v[34:37], v[154:157], v[178:181], v[34:37]
	v_mfma_f32_16x16x32_bf16 v[22:25], v[146:149], v[186:189], v[22:25]
	v_mfma_f32_16x16x32_bf16 v[18:21], v[154:157], v[186:189], v[18:21]
	v_mfma_f32_16x16x32_bf16 v[6:9], v[146:149], v[194:197], v[6:9]
	v_mfma_f32_16x16x32_bf16 v[2:5], v[154:157], v[194:197], v[2:5]
	v_mfma_f32_16x16x32_bf16 v[54:57], v[150:153], v[174:177], v[54:57]
	v_mfma_f32_16x16x32_bf16 v[50:53], v[158:161], v[174:177], v[50:53]
	v_mfma_f32_16x16x32_bf16 v[38:41], v[150:153], v[182:185], v[38:41]
	v_mfma_f32_16x16x32_bf16 v[34:37], v[158:161], v[182:185], v[34:37]
	v_mfma_f32_16x16x32_bf16 v[22:25], v[150:153], v[190:193], v[22:25]
	v_mfma_f32_16x16x32_bf16 v[18:21], v[158:161], v[190:193], v[18:21]
	v_mfma_f32_16x16x32_bf16 v[6:9], v[150:153], v[200:203], v[6:9]
	v_mfma_f32_16x16x32_bf16 v[2:5], v[158:161], v[200:203], v[2:5]
	s_barrier
	s_setprio 0
	s_cbranch_scc0 .LBB0_1614
	s_mov_b32 m0, s41
	s_nop 0
	buffer_load_dwordx4 v168, s[16:19], s61 offen lds
	s_mov_b32 m0, s33
	s_nop 0
	buffer_load_dwordx4 v170, s[16:19], s61 offen lds
	v_readlane_b32 s2, v251, 45
	v_readlane_b32 s3, v251, 46
	s_and_b64 vcc, exec, s[2:3]
	s_cbranch_vccz .LBB0_1617
	s_barrier
